# phase D out-projection GEMM rewritten by hand: LDS-DMA staging into a 3-stage ring of XOR-swizzled rows (static LDS +16 KiB), DMA issue interleaved with MFMAs; B0 per-channel params staged once in LDS
# speedup vs baseline: 1.1310x; 1.0262x over previous
.LBB0_472:
	v_mov_b32_e32 v8, v0
	ds_read2_b64 v[2:5], v131 offset0:17 offset1:18
	ds_read_b64 v[6:7], v131 offset:152
	s_mov_b32 s81, s97
	s_lshl_b64 s[0:1], s[80:81], 17
	v_readlane_b32 s4, v253, 34
	s_add_u32 s6, s4, s0
	v_readlane_b32 s0, v253, 35
	s_addc_u32 s7, s0, s1
	s_lshl_b32 s96, s80, 8
	s_waitcnt lgkmcnt(1)
	v_readfirstlane_b32 s1, v2
	s_lshl_b64 s[94:95], s[96:97], 2
	v_readfirstlane_b32 s0, v3
	s_add_u32 s24, s1, s94
	s_addc_u32 s25, s0, s95
	v_readfirstlane_b32 s0, v5
	v_readfirstlane_b32 s1, v4
	ds_read2_b64 v[2:5], v131 offset0:13 offset1:15
	v_and_b32_e32 v9, 15, v8
	v_lshrrev_b32_e32 v1, 2, v8
	v_and_or_b32 v1, v1, 16, v9
	v_bfe_u32 v10, v8, 4, 2
	v_ashrrev_i32_e32 v98, 7, v8
	s_add_u32 s10, s1, s94
	s_waitcnt lgkmcnt(0)
	v_readfirstlane_b32 s5, v2
	v_mul_u32_u24_e32 v2, 0x48, v1
	s_addc_u32 s11, s0, s95
	v_readfirstlane_b32 s1, v6
	v_readfirstlane_b32 s4, v3
	v_lshlrev_b32_e32 v2, 1, v2
	v_lshlrev_b32_e32 v130, 4, v10
	s_movk_i32 s73, 0xf0
	v_lshlrev_b32_e32 v3, 6, v98
	v_readfirstlane_b32 s0, v7
	s_add_u32 s14, s1, s94
	v_add3_u32 v101, s73, v2, v130
	v_or_b32_e32 v2, v3, v9
	v_lshl_or_b32 v6, v10, 2, v3
	v_add_u32_e32 v3, 0x200, v8
	s_addc_u32 s15, s0, s95
	s_lshl_b32 s0, s80, 9
	s_mov_b32 s1, s97
	v_ashrrev_i32_e32 v227, 7, v3
	v_add_u32_e32 v3, 0x400, v8
	s_mov_b32 s8, s0
	s_lshl_b64 s[0:1], s[0:1], 2
	v_ashrrev_i32_e32 v228, 7, v3
	v_add_u32_e32 v3, 0x600, v8
	s_add_u32 s20, s5, s0
	v_ashrrev_i32_e32 v229, 7, v3
	v_add_u32_e32 v3, 0x800, v8
	s_addc_u32 s21, s4, s1
	v_readfirstlane_b32 s5, v4
	v_ashrrev_i32_e32 v230, 7, v3
	v_add_u32_e32 v3, 0xa00, v8
	v_readfirstlane_b32 s4, v5
	s_add_u32 s22, s5, s0
	v_ashrrev_i32_e32 v231, 7, v3
	v_add_u32_e32 v3, 0xc00, v8
	v_writelane_b32 v254, s8, 59
	s_addc_u32 s23, s4, s1
	s_lshl_b64 s[12:13], s[80:81], 2
	v_readlane_b32 s0, v253, 36
	v_ashrrev_i32_e32 v232, 7, v3
	v_add_u32_e32 v3, 0xe00, v8
	v_writelane_b32 v254, s9, 60
	s_add_u32 s8, s0, s12
	v_readlane_b32 s0, v253, 37
	v_ashrrev_i32_e32 v233, 7, v3
	v_ashrrev_i32_e32 v3, 31, v2
	s_addc_u32 s9, s0, s13
	v_cmp_eq_u32_e64 s[0:1], 0, v8
	v_and_b32_e32 v100, 0x7f, v8
	v_lshl_add_u64 v[4:5], s[6:7], 0, v[130:131]
	v_lshlrev_b64 v[8:9], 7, v[2:3]
	v_lshl_add_u64 v[102:103], v[4:5], 0, v[8:9]
	v_or_b32_e32 v8, 16, v2
	v_ashrrev_i32_e32 v9, 31, v8
	v_lshlrev_b64 v[8:9], 7, v[8:9]
	v_lshl_add_u64 v[110:111], v[4:5], 0, v[8:9]
	v_or_b32_e32 v8, 32, v2
	v_or_b32_e32 v2, 48, v2
	v_ashrrev_i32_e32 v7, 31, v6
	v_ashrrev_i32_e32 v9, 31, v8
	v_ashrrev_i32_e32 v3, 31, v2
	v_lshlrev_b64 v[164:165], 2, v[6:7]
	v_lshlrev_b64 v[8:9], 7, v[8:9]
	v_lshlrev_b64 v[2:3], 7, v[2:3]
	v_lshl_add_u64 v[174:175], s[10:11], 0, v[164:165]
	v_readlane_b32 s10, v253, 28
	s_mov_b64 s[52:53], 0x10000
	v_lshl_add_u64 v[118:119], v[4:5], 0, v[8:9]
	v_lshl_add_u64 v[126:127], v[4:5], 0, v[2:3]
	v_readlane_b32 s11, v253, 29
	s_movk_i32 s62, 0x90
	s_mov_b64 s[50:51], 0x8000
	v_lshl_add_u64 v[106:107], v[102:103], 0, s[52:53]
	s_mov_b64 s[70:71], 0x18000
	v_lshl_add_u64 v[114:115], v[110:111], 0, s[52:53]
	v_lshl_add_u64 v[122:123], v[118:119], 0, s[52:53]
	v_lshl_add_u64 v[136:137], v[126:127], 0, s[52:53]
	s_mov_b64 s[52:53], 0x10040
	v_lshl_add_u64 v[182:183], s[10:11], 0, v[130:131]
	v_readlane_b32 s10, v253, 30
	v_lshl_add_u32 v11, v100, 1, v212
	v_cmp_eq_u32_e64 s[6:7], 0, v10
	v_mul_lo_u32 v10, v98, s62
	v_mul_lo_u32 v12, v227, s62
	v_mul_lo_u32 v13, v228, s62
	v_mul_lo_u32 v14, v229, s62
	v_mul_lo_u32 v15, v230, s62
	v_mul_lo_u32 v16, v231, s62
	v_mul_lo_u32 v17, v232, s62
	v_mul_lo_u32 v18, v233, s62
	v_lshl_add_u64 v[104:105], v[102:103], 0, s[50:51]
	v_lshl_add_u64 v[108:109], v[102:103], 0, s[70:71]
	v_lshl_add_u64 v[112:113], v[110:111], 0, s[50:51]
	v_lshl_add_u64 v[116:117], v[110:111], 0, s[70:71]
	v_lshl_add_u64 v[120:121], v[118:119], 0, s[50:51]
	v_lshl_add_u64 v[124:125], v[118:119], 0, s[70:71]
	v_lshl_add_u64 v[128:129], v[126:127], 0, s[50:51]
	v_lshl_add_u64 v[138:139], v[126:127], 0, s[70:71]
	s_mov_b64 s[50:51], 0x8040
	v_lshl_add_u64 v[142:143], v[102:103], 0, s[52:53]
	s_mov_b64 s[70:71], 0x18040
	v_lshl_add_u64 v[148:149], v[110:111], 0, s[52:53]
	v_lshl_add_u64 v[154:155], v[118:119], 0, s[52:53]
	v_lshl_add_u64 v[160:161], v[126:127], 0, s[52:53]
	v_lshl_add_u64 v[166:167], s[24:25], 0, v[164:165]
	v_or_b32_e32 v168, 16, v6
	v_or_b32_e32 v170, 32, v6
	v_or_b32_e32 v172, 48, v6
	v_readlane_b32 s11, v253, 31
	v_readlane_b32 s52, v253, 32
	v_readlane_b32 s24, v253, 39
	v_mov_b32_e32 v134, 0xbdc00
	v_mov_b32_e32 v133, 0xffc00
	v_mov_b32_e32 v132, 0x900
	v_mov_b32_e32 v222, 0x1800
	v_mov_b32_e32 v252, 0xc00
	v_mov_b32_e32 v223, 0xbe800
	v_cmp_lt_u32_e64 s[4:5], 63, v100
	v_ashrrev_i32_e32 v99, 31, v98
	v_lshl_add_u64 v[140:141], v[102:103], 0, s[50:51]
	v_lshl_add_u64 v[144:145], v[102:103], 0, s[70:71]
	v_lshl_add_u64 v[146:147], v[110:111], 0, s[50:51]
	v_lshl_add_u64 v[150:151], v[110:111], 0, s[70:71]
	v_lshl_add_u64 v[152:153], v[118:119], 0, s[50:51]
	v_lshl_add_u64 v[156:157], v[118:119], 0, s[70:71]
	v_lshl_add_u64 v[158:159], v[126:127], 0, s[50:51]
	v_lshl_add_u64 v[162:163], v[126:127], 0, s[70:71]
	v_ashrrev_i32_e32 v169, 31, v168
	v_ashrrev_i32_e32 v171, 31, v170
	v_ashrrev_i32_e32 v173, 31, v172
	v_add_u32_e32 v234, v11, v10
	v_add_u32_e32 v235, v11, v12
	v_add_u32_e32 v236, v11, v13
	v_add_u32_e32 v237, v11, v14
	v_add_u32_e32 v238, v11, v15
	v_add_u32_e32 v239, v11, v16
	v_add_u32_e32 v240, v11, v17
	v_add_u32_e32 v241, v11, v18
	v_mov_b32_e32 v242, 0
	v_lshl_add_u64 v[176:177], s[14:15], 0, v[164:165]
	v_lshl_add_u64 v[178:179], s[20:21], 0, v[164:165]
	v_lshl_add_u64 v[180:181], s[22:23], 0, v[164:165]
	v_lshl_add_u64 v[184:185], s[10:11], 0, v[130:131]
	v_readlane_b32 s53, v253, 33
	v_readlane_b32 s25, v253, 40
	v_readlane_b32 s50, v253, 42
	v_lshrrev_b32_e32 v255, 6, v0
	v_bfe_u32 v34, v0, 4, 2
	v_lshlrev_b32_e32 v255, 10, v255
	v_lshl_add_u32 v255, v34, 8, v255
	v_add_u32_e32 v255, 0x40f0, v255
	global_load_dwordx4 v[34:37], v[178:179], off
	global_load_dwordx4 v[38:41], v[178:179], off offset:64
	global_load_dwordx4 v[42:45], v[178:179], off offset:128
	global_load_dwordx4 v[46:49], v[178:179], off offset:192
	global_load_dwordx4 v[50:53], v[178:179], off offset:1024
	global_load_dwordx4 v[54:57], v[178:179], off offset:1088
	global_load_dwordx4 v[58:61], v[178:179], off offset:1152
	global_load_dwordx4 v[62:65], v[178:179], off offset:1216
	s_waitcnt vmcnt(0)
	ds_write_b128 v255, v[34:37]
	ds_write_b128 v255, v[38:41] offset:16
	ds_write_b128 v255, v[42:45] offset:32
	ds_write_b128 v255, v[46:49] offset:48
	ds_write_b128 v255, v[50:53] offset:64
	ds_write_b128 v255, v[54:57] offset:80
	ds_write_b128 v255, v[58:61] offset:96
	ds_write_b128 v255, v[62:65] offset:112
	global_load_dwordx4 v[34:37], v[180:181], off
	global_load_dwordx4 v[38:41], v[180:181], off offset:64
	global_load_dwordx4 v[42:45], v[180:181], off offset:128
	global_load_dwordx4 v[46:49], v[180:181], off offset:192
	global_load_dwordx4 v[50:53], v[180:181], off offset:1024
	global_load_dwordx4 v[54:57], v[180:181], off offset:1088
	global_load_dwordx4 v[58:61], v[180:181], off offset:1152
	global_load_dwordx4 v[62:65], v[180:181], off offset:1216
	s_waitcnt vmcnt(0)
	ds_write_b128 v255, v[34:37] offset:128
	ds_write_b128 v255, v[38:41] offset:144
	ds_write_b128 v255, v[42:45] offset:160
	ds_write_b128 v255, v[46:49] offset:176
	ds_write_b128 v255, v[50:53] offset:192
	ds_write_b128 v255, v[54:57] offset:208
	ds_write_b128 v255, v[58:61] offset:224
	ds_write_b128 v255, v[62:65] offset:240
	s_waitcnt lgkmcnt(0)
	s_branch .LBB0_474

.LBB0_513:
	s_or_b64 exec, exec, s[10:11]
	s_waitcnt lgkmcnt(0)
	s_barrier
	global_load_dwordx4 v[2:5], v[102:103], off
	global_load_dwordx4 v[6:9], v[104:105], off
	ds_read_b128 v[12:15], v101
	ds_read_b128 v[22:25], v101 offset:64
	global_load_dwordx4 v[16:19], v[102:103], off offset:64
	global_load_dwordx4 v[26:29], v[106:107], off
	v_or_b32_e32 v243, v10, v1
	v_cmp_gt_i32_e32 vcc, s37, v243
	s_waitcnt vmcnt(3) lgkmcnt(1)
	v_mfma_f32_16x16x32_bf16 v[2:5], v[2:5], v[12:15], 0
	v_cndmask_b32_e32 v11, v213, v214, vcc
	s_waitcnt vmcnt(2)
	v_mfma_f32_16x16x32_bf16 v[30:33], v[6:9], v[12:15], 0
	ds_read_b128 v[38:41], v101 offset:4608
	ds_read_b128 v[6:9], v101 offset:4672
	global_load_dwordx4 v[34:37], v[110:111], off
	global_load_dwordx4 v[42:45], v[112:113], off
	global_load_dwordx4 v[46:49], v[110:111], off offset:64
	global_load_dwordx4 v[50:53], v[118:119], off
	global_load_dwordx4 v[54:57], v[118:119], off offset:64
	global_load_dwordx4 v[58:61], v[120:121], off
	global_load_dwordx4 v[66:69], v[122:123], off
	global_load_dwordx4 v[62:65], v[126:127], off
	s_waitcnt vmcnt(9) lgkmcnt(2)
	v_mfma_f32_16x16x32_bf16 v[94:97], v[16:19], v[22:25], v[2:5]
	s_waitcnt vmcnt(8) lgkmcnt(1)
	v_mfma_f32_16x16x32_bf16 v[26:29], v[26:29], v[38:41], 0
	s_waitcnt vmcnt(6)
	v_mfma_f32_16x16x32_bf16 v[42:45], v[42:45], v[12:15], 0
	s_waitcnt vmcnt(0)
	v_mfma_f32_16x16x32_bf16 v[74:77], v[62:65], v[12:15], 0
	global_load_dwordx4 v[62:65], v[128:129], off
	global_load_dwordx4 v[78:81], v[126:127], off offset:64
	global_load_dwordx4 v[2:5], v[140:141], off
	global_load_dwordx4 v[86:89], v[142:143], off
	v_mfma_f32_16x16x32_bf16 v[34:37], v[34:37], v[12:15], 0
	v_mfma_f32_16x16x32_bf16 v[50:53], v[50:53], v[12:15], 0
	v_mfma_f32_16x16x32_bf16 v[58:61], v[58:61], v[12:15], 0
	v_mfma_f32_16x16x32_bf16 v[70:73], v[46:49], v[22:25], v[34:37]
	s_waitcnt vmcnt(1)
	v_mfma_f32_16x16x32_bf16 v[82:85], v[2:5], v[22:25], v[30:33]
	global_load_dwordx4 v[2:5], v[108:109], off
	v_mfma_f32_16x16x32_bf16 v[12:15], v[62:65], v[12:15], 0
	v_mfma_f32_16x16x32_bf16 v[18:21], v[78:81], v[22:25], v[74:77]
	s_waitcnt vmcnt(1) lgkmcnt(0)
	v_mfma_f32_16x16x32_bf16 v[90:93], v[86:89], v[6:9], v[26:29]
	s_waitcnt vmcnt(0)
	v_mfma_f32_16x16x32_bf16 v[30:33], v[2:5], v[38:41], 0
	global_load_dwordx4 v[2:5], v[146:147], off
	s_waitcnt vmcnt(0)
	v_mfma_f32_16x16x32_bf16 v[62:65], v[2:5], v[22:25], v[42:45]
	global_load_dwordx4 v[2:5], v[152:153], off
	global_load_dwordx4 v[46:49], v[154:155], off
	v_mfma_f32_16x16x32_bf16 v[42:45], v[54:57], v[22:25], v[50:53]
	s_nop 2
	global_load_dwordx4 v[50:53], v[114:115], off
	v_mfma_f32_16x16x32_bf16 v[54:57], v[66:69], v[38:41], 0
	s_waitcnt vmcnt(2)
	v_mfma_f32_16x16x32_bf16 v[34:37], v[2:5], v[22:25], v[58:61]
	global_load_dwordx4 v[2:5], v[158:159], off
	s_waitcnt vmcnt(0)
	v_mfma_f32_16x16x32_bf16 v[2:5], v[2:5], v[22:25], v[12:15]
	s_nop 2
	global_load_dwordx4 v[12:15], v[116:117], off
	v_mfma_f32_16x16x32_bf16 v[22:25], v[50:53], v[38:41], 0
	global_load_dwordx4 v[50:53], v[124:125], off
	s_waitcnt vmcnt(0)
	v_mfma_f32_16x16x32_bf16 v[74:77], v[50:53], v[38:41], 0
	global_load_dwordx4 v[50:53], v[136:137], off
	global_load_dwordx4 v[58:61], v[138:139], off
	global_load_dwordx4 v[26:29], v[144:145], off
	v_mfma_f32_16x16x32_bf16 v[12:15], v[12:15], v[38:41], 0
	s_waitcnt vmcnt(2)
	v_mfma_f32_16x16x32_bf16 v[78:81], v[50:53], v[38:41], 0
	s_waitcnt vmcnt(0)
	v_mfma_f32_16x16x32_bf16 v[50:53], v[26:29], v[6:9], v[30:33]
	global_load_dwordx4 v[26:29], v[148:149], off
	s_nop 1
	global_load_dwordx4 v[30:33], v[150:151], off
	v_mfma_f32_16x16x32_bf16 v[186:189], v[58:61], v[38:41], 0
	v_mfma_f32_16x16x32_bf16 v[38:41], v[46:49], v[6:9], v[54:57]
	s_waitcnt vmcnt(1)
	v_mfma_f32_16x16x32_bf16 v[66:69], v[26:29], v[6:9], v[22:25]
	s_waitcnt vmcnt(0)
	v_mfma_f32_16x16x32_bf16 v[58:61], v[30:33], v[6:9], v[12:15]
	s_nop 2
	global_load_dwordx4 v[12:15], v[156:157], off
	s_waitcnt vmcnt(0)
	v_mfma_f32_16x16x32_bf16 v[30:33], v[12:15], v[6:9], v[74:77]
	global_load_dwordx4 v[12:15], v[160:161], off
	global_load_dwordx4 v[22:25], v[162:163], off
	s_waitcnt vmcnt(1)
	v_mfma_f32_16x16x32_bf16 v[14:17], v[12:15], v[6:9], v[78:81]
	v_cndmask_b32_e32 v12, v215, v216, vcc
	v_bitop3_b32 v130, v12, v10, v1 bitop3:0xe0
	v_mov_b64_e32 v[12:13], s[28:29]
	s_waitcnt vmcnt(0)
	v_mfma_f32_16x16x32_bf16 v[6:9], v[22:25], v[6:9], v[186:189]
	v_cndmask_b32_e64 v22, 10, 8, vcc
	v_and_b32_e32 v10, v11, v10
	v_mad_i64_i32 v[12:13], s[10:11], v243, s36, v[12:13]
	v_lshlrev_b64 v[22:23], v22, v[98:99]
	v_ashrrev_i32_e32 v11, 31, v10
	v_lshl_add_u64 v[22:23], v[22:23], 0, v[130:131]
	v_lshl_add_u64 v[190:191], v[12:13], 0, s[92:93]
	v_lshl_add_u64 v[204:205], v[10:11], 2, v[22:23]
	v_lshl_add_u64 v[10:11], v[190:191], 0, v[164:165]
	v_lshl_add_u64 v[188:189], v[12:13], 0, v[164:165]
	global_load_dwordx4 v[86:89], v[10:11], off
	global_load_dwordx4 v[46:49], v[188:189], off offset:3072
	flat_load_dwordx4 v[192:195], v[166:167]
	flat_load_dwordx4 v[196:199], v[166:167] offset:64
	global_load_dwordx4 v[54:57], v[188:189], off offset:3136
	global_load_dwordx4 v[26:29], v[188:189], off offset:3200
	flat_load_dwordx4 v[244:247], v[166:167] offset:128
	global_load_dwordx4 v[10:13], v[188:189], off offset:3264
	flat_load_dwordx4 v[248:251], v[166:167] offset:192
	global_load_dwordx4 v[74:77], v[188:189], off offset:2048
	flat_load_dwordx4 v[78:81], v[174:175]
	flat_load_dwordx4 v[22:25], v[176:177]
	v_mad_u64_u32 v[186:187], s[10:11], v204, s66, v[182:183]
	v_mad_i32_i24 v187, v205, s66, v187
	s_mov_b32 s10, 0x800000
	s_waitcnt vmcnt(0)
	global_store_dwordx4 v[186:187], v[86:89], off offset:512
	s_waitcnt lgkmcnt(0)
	s_nop 0
	v_pk_mul_f32 v[86:87], v[48:49], v[194:195]
	v_pk_mul_f32 v[224:225], v[46:47], v[192:193]
	v_pk_mul_f32 v[88:89], v[86:87], v[86:87]
	v_pk_mul_f32 v[192:193], v[224:225], v[224:225]
	v_pk_mul_f32 v[200:201], v[56:57], v[198:199]
	v_pk_mov_b32 v[194:195], v[192:193], v[88:89] op_sel:[1,0]
	v_mov_b32_e32 v193, v89
	v_pk_mul_f32 v[202:203], v[54:55], v[196:197]
	v_pk_add_f32 v[88:89], v[194:195], v[192:193]
	v_pk_mul_f32 v[192:193], v[200:201], v[200:201]
	v_pk_mul_f32 v[194:195], v[202:203], v[202:203]
	v_pk_mul_f32 v[198:199], v[26:27], v[244:245]
	v_pk_mov_b32 v[196:197], v[194:195], v[192:193] op_sel:[1,0]
	v_mov_b32_e32 v195, v193
	v_pk_add_f32 v[218:219], v[196:197], v[194:195]
	v_pk_mul_f32 v[194:195], v[10:11], v[248:249]
	v_pk_add_f32 v[88:89], v[88:89], v[88:89] op_sel:[0,1] op_sel_hi:[1,0]
	v_pk_add_f32 v[218:219], v[218:219], v[218:219] op_sel:[0,1] op_sel_hi:[1,0]
	v_pk_mul_f32 v[196:197], v[28:29], v[246:247]
	v_mul_f32_e32 v89, v194, v194
	v_mul_f32_e32 v219, v195, v195
	v_mul_f32_e32 v130, v199, v199
	v_pk_add_f32 v[88:89], v[88:89], v[218:219]
	v_pk_fma_f32 v[218:219], v[198:199], v[198:199], v[130:131] op_sel_hi:[1,1,0]
	v_mul_f32_e32 v130, v197, v197
	v_pk_mul_f32 v[192:193], v[12:13], v[250:251]
	v_pk_fma_f32 v[244:245], v[196:197], v[196:197], v[130:131] op_sel_hi:[1,1,0]
	v_mul_f32_e32 v219, v192, v192
	v_mul_f32_e32 v245, v193, v193
	v_pk_add_f32 v[218:219], v[218:219], v[244:245]
	v_xor_b32_e32 v130, 16, v217
	v_pk_add_f32 v[88:89], v[88:89], v[218:219]
	s_nop 0
	v_add_f32_e32 v88, v88, v89
	v_and_b32_e32 v89, 64, v217
	v_add_u32_e32 v89, 64, v89
	v_cmp_lt_i32_e32 vcc, v130, v89
	s_nop 1
	v_cndmask_b32_e32 v130, v217, v130, vcc
	v_lshlrev_b32_e32 v244, 2, v130
	ds_bpermute_b32 v130, v244, v88
	s_waitcnt lgkmcnt(0)
	v_add_f32_e32 v88, v88, v130
	v_xor_b32_e32 v130, 32, v217
	v_cmp_lt_i32_e32 vcc, v130, v89
	s_nop 1
	v_cndmask_b32_e32 v89, v217, v130, vcc
	v_lshlrev_b32_e32 v245, 2, v89
	ds_bpermute_b32 v89, v245, v88
	s_waitcnt lgkmcnt(0)
	v_add_f32_e32 v88, v88, v89
	v_add_f32_e32 v88, 0x2b8cbccc, v88
	v_mul_f32_e32 v89, 0x4b800000, v88
	v_cmp_gt_f32_e32 vcc, s10, v88
	s_nop 1
	v_cndmask_b32_e32 v88, v88, v89, vcc
	v_rsq_f32_e32 v88, v88
	s_nop 0
	v_mul_f32_e32 v89, 0x45800000, v88
	v_cndmask_b32_e32 v130, v88, v89, vcc
	v_pk_mul_f32 v[88:89], v[86:87], v[130:131] op_sel_hi:[1,0]
	v_pk_mul_f32 v[86:87], v[224:225], v[130:131] op_sel_hi:[1,0]
	global_store_dwordx4 v[186:187], v[74:77], off
	global_store_dwordx4 v[186:187], v[86:89], off offset:256
	ds_read_b128 v[246:249], v255
	s_waitcnt lgkmcnt(0)
	v_add_f32_e32 v218, v94, v246
	v_add_f32_e32 v219, v95, v247
	v_add_f32_e32 v224, v96, v248
	v_add_f32_e32 v96, v97, v249
	ds_read_b128 v[246:249], v255 offset:128
	v_mul_f32_e32 v97, 0xbfb8aa3b, v218
	v_exp_f32_e32 v97, v97
	v_mad_u64_u32 v[94:95], s[10:11], v204, s66, v[184:185]
	v_mad_i32_i24 v95, v205, s66, v95
	v_add_f32_e32 v97, 1.0, v97
	v_div_scale_f32 v204, s[10:11], v97, v97, s45
	v_rcp_f32_e32 v205, v204
	v_mul_f32_e32 v224, 0xbfb8aa3b, v224
	v_exp_f32_e32 v224, v224
	v_mul_f32_e32 v96, 0xbfb8aa3b, v96
	v_fma_f32 v218, -v204, v205, 1.0
	v_fmac_f32_e32 v205, v218, v205
	v_div_scale_f32 v218, vcc, s45, v97, s45
	v_mul_f32_e32 v225, v218, v205
	v_add_f32_e32 v224, 1.0, v224
	v_exp_f32_e32 v96, v96
	s_waitcnt lgkmcnt(0)
	v_add_f32_e32 v90, v90, v246
	v_fma_f32 v246, -v204, v225, v218
	v_fmac_f32_e32 v225, v246, v205
	v_fma_f32 v204, -v204, v225, v218
	v_div_fmas_f32 v204, v204, v205, v225
	v_mul_f32_e32 v205, 0xbfb8aa3b, v219
	v_exp_f32_e32 v205, v205
	v_add_f32_e32 v91, v91, v247
	v_mul_f32_e32 v90, 0xbfb8aa3b, v90
	v_mul_f32_e32 v91, 0xbfb8aa3b, v91
	v_add_f32_e32 v205, 1.0, v205
	v_div_scale_f32 v218, s[10:11], v205, v205, s45
	v_rcp_f32_e32 v219, v218
	v_exp_f32_e32 v90, v90
	v_exp_f32_e32 v91, v91
	v_add_f32_e32 v92, v92, v248
	v_fma_f32 v225, -v218, v219, 1.0
	v_fmac_f32_e32 v219, v225, v219
	v_div_scale_f32 v225, vcc, s45, v205, s45
	v_mul_f32_e32 v246, v225, v219
	v_fma_f32 v247, -v218, v246, v225
	v_fmac_f32_e32 v246, v247, v219
	v_fma_f32 v218, -v218, v246, v225
	v_pk_add_f32 v[90:91], v[90:91], 1.0 op_sel_hi:[1,0]
	v_div_fmas_f32 v218, v218, v219, v246
	v_div_scale_f32 v219, s[10:11], v91, v91, 1.0
	v_rcp_f32_e32 v225, v219
	v_add_f32_e32 v93, v93, v249
	v_add_f32_e32 v96, 1.0, v96
	v_div_fixup_f32 v97, v204, v97, s45
	v_fma_f32 v246, -v219, v225, 1.0
	v_fmac_f32_e32 v225, v246, v225
	v_div_scale_f32 v246, vcc, 1.0, v91, 1.0
	v_mul_f32_e32 v247, v246, v225
	v_fma_f32 v248, -v219, v247, v246
	v_fmac_f32_e32 v247, v248, v225
	v_fma_f32 v219, -v219, v247, v246
	v_div_fmas_f32 v219, v219, v225, v247
	v_div_scale_f32 v225, s[10:11], v90, v90, 1.0
	v_rcp_f32_e32 v246, v225
	v_mul_f32_e32 v97, 0x3fb8aa3b, v97
	v_div_fixup_f32 v204, v218, v205, s45
	v_mul_f32_e32 v204, 0x3fb8aa3b, v204
	v_fma_f32 v247, -v225, v246, 1.0
	v_fmac_f32_e32 v246, v247, v246
	v_div_scale_f32 v247, vcc, 1.0, v90, 1.0
	v_mul_f32_e32 v248, v247, v246
	v_fma_f32 v249, -v225, v248, v247
	v_fmac_f32_e32 v248, v249, v246
	v_fma_f32 v225, -v225, v248, v247
	v_div_fmas_f32 v225, v225, v246, v248
	v_div_scale_f32 v246, s[10:11], v224, v224, s45
	v_rcp_f32_e32 v247, v246
	s_nop 0
	v_fma_f32 v248, -v246, v247, 1.0
	v_fmac_f32_e32 v247, v248, v247
	v_div_scale_f32 v248, vcc, s45, v224, s45
	v_mul_f32_e32 v249, v248, v247
	v_fma_f32 v250, -v246, v249, v248
	v_fmac_f32_e32 v249, v250, v247
	v_fma_f32 v246, -v246, v249, v248
	v_div_fmas_f32 v248, v246, v247, v249
	v_div_scale_f32 v246, s[10:11], v96, v96, s45
	v_rcp_f32_e32 v247, v246
	s_nop 0
	v_fma_f32 v249, -v246, v247, 1.0
	v_fmac_f32_e32 v247, v249, v247
	v_div_scale_f32 v249, vcc, s45, v96, s45
	v_mul_f32_e32 v250, v249, v247
	v_fma_f32 v251, -v246, v250, v249
	v_fmac_f32_e32 v250, v251, v247
	v_fma_f32 v246, -v246, v250, v249
	v_div_fmas_f32 v249, v246, v247, v250
	v_exp_f32_e32 v246, v97
	v_div_fixup_f32 v97, v248, v224, s45
	v_div_fixup_f32 v96, v249, v96, s45
	v_mul_f32_e32 v97, 0x3fb8aa3b, v97
	v_mul_f32_e32 v96, 0x3fb8aa3b, v96
	v_exp_f32_e32 v248, v97
	v_exp_f32_e32 v249, v96
	v_div_fixup_f32 v97, v219, v91, 1.0
	v_div_fixup_f32 v96, v225, v90, 1.0
	v_mul_f32_e32 v90, 0xbfb8aa3b, v92
	v_mul_f32_e32 v91, 0xbfb8aa3b, v93
	v_exp_f32_e32 v90, v90
	v_exp_f32_e32 v91, v91
	v_exp_f32_e32 v247, v204
	v_pk_add_f32 v[90:91], v[90:91], 1.0 op_sel_hi:[1,0]
	s_nop 0
	v_div_scale_f32 v92, s[10:11], v91, v91, 1.0
	v_rcp_f32_e32 v93, v92
	global_store_dwordx4 v[94:95], v[246:249], off
	v_fma_f32 v204, -v92, v93, 1.0
	v_fmac_f32_e32 v93, v204, v93
	v_div_scale_f32 v204, vcc, 1.0, v91, 1.0
	v_mul_f32_e32 v205, v204, v93
	v_fma_f32 v218, -v92, v205, v204
	v_fmac_f32_e32 v205, v218, v93
	v_fma_f32 v92, -v92, v205, v204
	v_div_fmas_f32 v92, v92, v93, v205
	v_div_scale_f32 v93, s[10:11], v90, v90, 1.0
	v_rcp_f32_e32 v204, v93
	s_nop 0
	v_fma_f32 v205, -v93, v204, 1.0
	v_fmac_f32_e32 v204, v205, v204
	v_div_scale_f32 v205, vcc, 1.0, v90, 1.0
	v_mul_f32_e32 v218, v205, v204
	v_fma_f32 v219, -v93, v218, v205
	v_fmac_f32_e32 v218, v219, v204
	v_fma_f32 v93, -v93, v218, v205
	v_div_fmas_f32 v93, v93, v204, v218
	v_div_fixup_f32 v205, v92, v91, 1.0
	v_div_fixup_f32 v204, v93, v90, 1.0
	v_xor_b32_e32 v91, 0x80000000, v97
	v_xor_b32_e32 v90, 0x80000000, v96
	v_xor_b32_e32 v93, 0x80000000, v205
	v_xor_b32_e32 v92, 0x80000000, v204
	v_pk_mul_f32 v[92:93], v[88:89], v[92:93]
	v_pk_mul_f32 v[90:91], v[86:87], v[90:91]
	global_store_dwordx4 v[94:95], v[90:93], off offset:256
	s_nop 1
	v_pk_add_f32 v[90:91], v[96:97], -1.0 op_sel_hi:[1,0]
	v_pk_add_f32 v[92:93], v[204:205], -1.0 op_sel_hi:[1,0]
	v_pk_fma_f32 v[90:91], v[78:79], v[90:91], 1.0 op_sel_hi:[1,1,0]
	v_pk_fma_f32 v[92:93], v[80:81], v[92:93], 1.0 op_sel_hi:[1,1,0]
	v_pk_mul_f32 v[90:91], v[46:47], v[90:91]
	v_pk_mul_f32 v[92:93], v[48:49], v[92:93]
	global_store_dwordx4 v[94:95], v[90:93], off offset:512
	ds_read_b128 v[246:249], v255 offset:64
	s_waitcnt lgkmcnt(0)
	v_add_f32_e32 v96, v82, v246
	v_add_f32_e32 v97, v83, v247
	v_add_f32_e32 v204, v84, v248
	v_add_f32_e32 v205, v85, v249
	ds_read_b128 v[82:85], v255 offset:192
	s_waitcnt lgkmcnt(0)
	v_add_f32_e32 v50, v50, v82
	v_mul_f32_e32 v82, 0xbfb8aa3b, v96
	v_exp_f32_e32 v82, v82
	v_add_f32_e32 v52, v52, v84
	v_add_f32_e32 v51, v51, v83
	v_add_f32_e32 v53, v53, v85
	v_add_f32_e32 v84, 1.0, v82
	v_div_scale_f32 v82, s[10:11], v84, v84, s45
	v_rcp_f32_e32 v83, v82
	v_mul_f32_e32 v50, 0xbfb8aa3b, v50
	v_mul_f32_e32 v51, 0xbfb8aa3b, v51
	v_exp_f32_e32 v50, v50
	v_fma_f32 v85, -v82, v83, 1.0
	v_fmac_f32_e32 v83, v85, v83
	v_div_scale_f32 v85, vcc, s45, v84, s45
	v_mul_f32_e32 v96, v85, v83
	v_fma_f32 v218, -v82, v96, v85
	v_fmac_f32_e32 v96, v218, v83
	v_fma_f32 v82, -v82, v96, v85
	v_div_fmas_f32 v85, v82, v83, v96
	v_mul_f32_e32 v82, 0xbfb8aa3b, v97
	v_exp_f32_e32 v82, v82
	v_exp_f32_e32 v51, v51
	v_mul_f32_e32 v52, 0xbfb8aa3b, v52
	v_mul_f32_e32 v53, 0xbfb8aa3b, v53
	v_add_f32_e32 v96, 1.0, v82
	v_div_scale_f32 v82, s[10:11], v96, v96, s45
	v_rcp_f32_e32 v83, v82
	v_pk_add_f32 v[50:51], v[50:51], 1.0 op_sel_hi:[1,0]
	v_exp_f32_e32 v52, v52
	v_exp_f32_e32 v53, v53
	v_fma_f32 v97, -v82, v83, 1.0
	v_fmac_f32_e32 v83, v97, v83
	v_div_scale_f32 v97, vcc, s45, v96, s45
	v_mul_f32_e32 v218, v97, v83
	v_fma_f32 v219, -v82, v218, v97
	v_fmac_f32_e32 v218, v219, v83
	v_fma_f32 v82, -v82, v218, v97
	v_div_fmas_f32 v97, v82, v83, v218
	v_div_scale_f32 v82, s[10:11], v51, v51, 1.0
	v_rcp_f32_e32 v83, v82
	v_pk_add_f32 v[52:53], v[52:53], 1.0 op_sel_hi:[1,0]
	v_fma_f32 v218, -v82, v83, 1.0
	v_fmac_f32_e32 v83, v218, v83
	v_div_scale_f32 v218, vcc, 1.0, v51, 1.0
	v_mul_f32_e32 v219, v218, v83
	v_fma_f32 v224, -v82, v219, v218
	v_fmac_f32_e32 v219, v224, v83
	v_fma_f32 v82, -v82, v219, v218
	v_div_fmas_f32 v82, v82, v83, v219
	v_div_scale_f32 v83, s[10:11], v50, v50, 1.0
	v_rcp_f32_e32 v218, v83
	v_div_fixup_f32 v51, v82, v51, 1.0
	v_mul_f32_e32 v82, 0xbfb8aa3b, v204
	v_exp_f32_e32 v82, v82
	v_fma_f32 v219, -v83, v218, 1.0
	v_fmac_f32_e32 v218, v219, v218
	v_div_scale_f32 v219, vcc, 1.0, v50, 1.0
	v_mul_f32_e32 v224, v219, v218
	v_fma_f32 v225, -v83, v224, v219
	v_fmac_f32_e32 v224, v225, v218
	v_fma_f32 v83, -v83, v224, v219
	v_add_f32_e32 v204, 1.0, v82
	v_div_fmas_f32 v83, v83, v218, v224
	v_div_scale_f32 v82, s[10:11], v204, v204, s45
	v_div_fixup_f32 v50, v83, v50, 1.0
	v_rcp_f32_e32 v83, v82
	s_nop 0
	v_fma_f32 v218, -v82, v83, 1.0
	v_fmac_f32_e32 v83, v218, v83
	v_div_scale_f32 v218, vcc, s45, v204, s45
	v_mul_f32_e32 v219, v218, v83
	v_fma_f32 v224, -v82, v219, v218
	v_fmac_f32_e32 v219, v224, v83
	v_fma_f32 v82, -v82, v219, v218
	v_div_fmas_f32 v218, v82, v83, v219
	v_mul_f32_e32 v82, 0xbfb8aa3b, v205
	v_exp_f32_e32 v82, v82
	s_nop 0
	v_add_f32_e32 v205, 1.0, v82
	v_div_scale_f32 v82, s[10:11], v205, v205, s45
	v_rcp_f32_e32 v83, v82
	s_nop 0
	v_fma_f32 v219, -v82, v83, 1.0
	v_fmac_f32_e32 v83, v219, v83
	v_div_scale_f32 v219, vcc, s45, v205, s45
	v_mul_f32_e32 v224, v219, v83
	v_fma_f32 v225, -v82, v224, v219
	v_fmac_f32_e32 v224, v225, v83
	v_fma_f32 v82, -v82, v224, v219
	v_div_fmas_f32 v219, v82, v83, v224
	v_div_scale_f32 v82, s[10:11], v53, v53, 1.0
	v_rcp_f32_e32 v83, v82
	s_nop 0
	v_fma_f32 v224, -v82, v83, 1.0
	v_fmac_f32_e32 v83, v224, v83
	v_div_scale_f32 v224, vcc, 1.0, v53, 1.0
	v_mul_f32_e32 v225, v224, v83
	v_fma_f32 v246, -v82, v225, v224
	v_fmac_f32_e32 v225, v246, v83
	v_fma_f32 v82, -v82, v225, v224
	v_div_fmas_f32 v82, v82, v83, v225
	v_div_scale_f32 v83, s[10:11], v52, v52, 1.0
	v_rcp_f32_e32 v224, v83
	v_div_fixup_f32 v53, v82, v53, 1.0
	s_mov_b32 s10, 0x1800000
	v_fma_f32 v225, -v83, v224, 1.0
	v_fmac_f32_e32 v224, v225, v224
	v_div_scale_f32 v225, vcc, 1.0, v52, 1.0
	v_mul_f32_e32 v246, v225, v224
	v_fma_f32 v247, -v83, v246, v225
	v_fmac_f32_e32 v246, v247, v224
	v_fma_f32 v83, -v83, v246, v225
	v_div_fmas_f32 v83, v83, v224, v246
	v_div_fixup_f32 v52, v83, v52, 1.0
	v_pk_add_f32 v[82:83], v[50:51], -1.0 op_sel_hi:[1,0]
	v_xor_b32_e32 v51, 0x80000000, v51
	v_pk_fma_f32 v[78:79], v[78:79], v[82:83], 1.0 op_sel_hi:[1,1,0]
	v_pk_add_f32 v[82:83], v[52:53], -1.0 op_sel_hi:[1,0]
	v_pk_mul_f32 v[46:47], v[46:47], v[78:79]
	v_pk_fma_f32 v[80:81], v[80:81], v[82:83], 1.0 op_sel_hi:[1,1,0]
	v_div_fixup_f32 v78, v85, v84, s45
	v_pk_mul_f32 v[48:49], v[48:49], v[80:81]
	v_div_fixup_f32 v79, v97, v96, s45
	v_div_fixup_f32 v80, v218, v204, s45
	v_div_fixup_f32 v81, v219, v205, s45
	v_mul_f32_e32 v78, 0x3fb8aa3b, v78
	v_mul_f32_e32 v79, 0x3fb8aa3b, v79
	v_mul_f32_e32 v80, 0x3fb8aa3b, v80
	v_mul_f32_e32 v81, 0x3fb8aa3b, v81
	v_exp_f32_e32 v78, v78
	v_exp_f32_e32 v79, v79
	v_exp_f32_e32 v80, v80
	v_exp_f32_e32 v81, v81
	v_add_co_u32_e32 v82, vcc, s10, v94
	v_xor_b32_e32 v50, 0x80000000, v50
	v_xor_b32_e32 v53, 0x80000000, v53
	v_xor_b32_e32 v52, 0x80000000, v52
	v_addc_co_u32_e32 v83, vcc, 0, v95, vcc
	v_pk_mul_f32 v[52:53], v[88:89], v[52:53]
	v_pk_mul_f32 v[50:51], v[86:87], v[50:51]
	global_store_dwordx4 v[82:83], v[78:81], off
	global_store_dwordx4 v[82:83], v[50:53], off offset:256
	v_mul_f32_e32 v88, v74, v46
	v_mul_f32_e32 v89, v75, v47
	global_store_dwordx4 v[82:83], v[46:49], off offset:512
	v_mul_f32_e32 v84, v74, v90
	v_mul_f32_e32 v85, v75, v91
	v_lshl_add_u64 v[46:47], v[168:169], 2, v[190:191]
	v_mul_f32_e32 v86, v76, v92
	v_mul_f32_e32 v87, v77, v93
	v_mul_f32_e32 v90, v76, v48
	v_mul_f32_e32 v91, v77, v49
	global_load_dwordx4 v[74:77], v[46:47], off
	s_nop 0
	global_load_dwordx4 v[46:49], v[188:189], off offset:2112
	flat_load_dwordx4 v[78:81], v[174:175] offset:64
	flat_load_dwordx4 v[50:53], v[176:177] offset:64
	s_waitcnt vmcnt(0)
	global_store_dwordx4 v[186:187], v[74:77], off offset:576
	s_nop 1
	v_pk_mul_f32 v[76:77], v[200:201], v[130:131] op_sel_hi:[1,0]
	v_pk_mul_f32 v[74:75], v[202:203], v[130:131] op_sel_hi:[1,0]
	global_store_dwordx4 v[186:187], v[46:49], off offset:64
	global_store_dwordx4 v[186:187], v[74:77], off offset:320
	ds_read_b128 v[200:203], v255 offset:16
	s_waitcnt lgkmcnt(0)
	v_add_f32_e32 v92, v70, v200
	v_add_f32_e32 v93, v71, v201
	v_add_f32_e32 v96, v72, v202
	v_add_f32_e32 v97, v73, v203
	ds_read_b128 v[70:73], v255 offset:144
	s_waitcnt lgkmcnt(0)
	v_add_f32_e32 v72, v68, v72
	v_mul_f32_e32 v68, 0xbfb8aa3b, v92
	v_exp_f32_e32 v68, v68
	v_add_f32_e32 v73, v69, v73
	v_add_f32_e32 v66, v66, v70
	v_add_f32_e32 v67, v67, v71
	v_add_f32_e32 v68, 1.0, v68
	v_div_scale_f32 v69, s[10:11], v68, v68, s45
	v_rcp_f32_e32 v70, v69
	v_mul_f32_e32 v66, 0xbfb8aa3b, v66
	v_mul_f32_e32 v67, 0xbfb8aa3b, v67
	v_exp_f32_e32 v66, v66
	v_fma_f32 v71, -v69, v70, 1.0
	v_fmac_f32_e32 v70, v71, v70
	v_div_scale_f32 v71, vcc, s45, v68, s45
	v_mul_f32_e32 v92, v71, v70
	v_fma_f32 v200, -v69, v92, v71
	v_fmac_f32_e32 v92, v200, v70
	v_fma_f32 v69, -v69, v92, v71
	v_div_fmas_f32 v69, v69, v70, v92
	v_mul_f32_e32 v70, 0xbfb8aa3b, v93
	v_exp_f32_e32 v70, v70
	v_exp_f32_e32 v67, v67
	v_add_f32_e32 v92, 1.0, v70
	v_div_scale_f32 v70, s[10:11], v92, v92, s45
	v_rcp_f32_e32 v71, v70
	s_nop 0
	v_fma_f32 v93, -v70, v71, 1.0
	v_fmac_f32_e32 v71, v93, v71
	v_div_scale_f32 v93, vcc, s45, v92, s45
	v_mul_f32_e32 v200, v93, v71
	v_fma_f32 v201, -v70, v200, v93
	v_fmac_f32_e32 v200, v201, v71
	v_fma_f32 v70, -v70, v200, v93
	v_div_fmas_f32 v93, v70, v71, v200
	v_pk_add_f32 v[70:71], v[66:67], 1.0 op_sel_hi:[1,0]
	s_nop 0
	v_div_scale_f32 v66, s[10:11], v71, v71, 1.0
	v_rcp_f32_e32 v67, v66
	s_nop 0
	v_fma_f32 v200, -v66, v67, 1.0
	v_fmac_f32_e32 v67, v200, v67
	v_div_scale_f32 v200, vcc, 1.0, v71, 1.0
	v_mul_f32_e32 v201, v200, v67
	v_fma_f32 v202, -v66, v201, v200
	v_fmac_f32_e32 v201, v202, v67
	v_fma_f32 v66, -v66, v201, v200
	v_div_fmas_f32 v200, v66, v67, v201
	v_div_scale_f32 v66, s[10:11], v70, v70, 1.0
	v_rcp_f32_e32 v67, v66
	v_div_fixup_f32 v71, v200, v71, 1.0
	v_fma_f32 v201, -v66, v67, 1.0
	v_fmac_f32_e32 v67, v201, v67
	v_div_scale_f32 v201, vcc, 1.0, v70, 1.0
	v_mul_f32_e32 v202, v201, v67
	v_fma_f32 v203, -v66, v202, v201
	v_fmac_f32_e32 v202, v203, v67
	v_fma_f32 v66, -v66, v202, v201
	v_div_fmas_f32 v201, v66, v67, v202
	v_mul_f32_e32 v66, 0xbfb8aa3b, v96
	v_exp_f32_e32 v66, v66
	v_div_fixup_f32 v70, v201, v70, 1.0
	v_add_f32_e32 v96, 1.0, v66
	v_div_scale_f32 v66, s[10:11], v96, v96, s45
	v_rcp_f32_e32 v67, v66
	s_nop 0
	v_fma_f32 v202, -v66, v67, 1.0
	v_fmac_f32_e32 v67, v202, v67
	v_div_scale_f32 v202, vcc, s45, v96, s45
	v_mul_f32_e32 v203, v202, v67
	v_fma_f32 v204, -v66, v203, v202
	v_fmac_f32_e32 v203, v204, v67
	v_fma_f32 v66, -v66, v203, v202
	v_div_fmas_f32 v202, v66, v67, v203
	v_mul_f32_e32 v66, 0xbfb8aa3b, v97
	v_exp_f32_e32 v66, v66
	s_nop 0
	v_add_f32_e32 v97, 1.0, v66
	v_div_scale_f32 v66, s[10:11], v97, v97, s45
	v_rcp_f32_e32 v67, v66
	s_nop 0
	v_fma_f32 v203, -v66, v67, 1.0
	v_fmac_f32_e32 v67, v203, v67
	v_div_scale_f32 v203, vcc, s45, v97, s45
	v_mul_f32_e32 v204, v203, v67
	v_fma_f32 v205, -v66, v204, v203
	v_fmac_f32_e32 v204, v205, v67
	v_fma_f32 v66, -v66, v204, v203
	v_div_fmas_f32 v203, v66, v67, v204
	v_div_fixup_f32 v66, v69, v68, s45
	v_div_fixup_f32 v67, v93, v92, s45
	v_div_fixup_f32 v68, v202, v96, s45
	v_div_fixup_f32 v69, v203, v97, s45
	v_mul_f32_e32 v66, 0x3fb8aa3b, v66
	v_mul_f32_e32 v67, 0x3fb8aa3b, v67
	v_mul_f32_e32 v68, 0x3fb8aa3b, v68
	v_mul_f32_e32 v69, 0x3fb8aa3b, v69
	v_exp_f32_e32 v66, v66
	v_exp_f32_e32 v67, v67
	v_exp_f32_e32 v68, v68
	v_exp_f32_e32 v69, v69
	global_store_dwordx4 v[94:95], v[66:69], off offset:64
	s_nop 1
	v_mul_f32_e32 v66, 0xbfb8aa3b, v72
	v_mul_f32_e32 v67, 0xbfb8aa3b, v73
	v_exp_f32_e32 v66, v66
	v_exp_f32_e32 v67, v67
	s_nop 0
	v_pk_add_f32 v[66:67], v[66:67], 1.0 op_sel_hi:[1,0]
	s_nop 0
	v_div_scale_f32 v68, s[10:11], v67, v67, 1.0
	v_rcp_f32_e32 v69, v68
	s_nop 0
	v_fma_f32 v72, -v68, v69, 1.0
	v_fmac_f32_e32 v69, v72, v69
	v_div_scale_f32 v72, vcc, 1.0, v67, 1.0
	v_mul_f32_e32 v73, v72, v69
	v_fma_f32 v92, -v68, v73, v72
	v_fmac_f32_e32 v73, v92, v69
	v_fma_f32 v68, -v68, v73, v72
	v_div_fmas_f32 v68, v68, v69, v73
	v_div_scale_f32 v69, s[10:11], v66, v66, 1.0
	v_rcp_f32_e32 v72, v69
	s_nop 0
	v_fma_f32 v73, -v69, v72, 1.0
	v_fmac_f32_e32 v72, v73, v72
	v_div_scale_f32 v73, vcc, 1.0, v66, 1.0
	v_mul_f32_e32 v92, v73, v72
	v_fma_f32 v93, -v69, v92, v73
	v_fmac_f32_e32 v92, v93, v72
	v_fma_f32 v69, -v69, v92, v73
	v_div_fmas_f32 v69, v69, v72, v92
	v_div_fixup_f32 v73, v68, v67, 1.0
	v_div_fixup_f32 v72, v69, v66, 1.0
	v_xor_b32_e32 v67, 0x80000000, v71
	v_xor_b32_e32 v66, 0x80000000, v70
	v_xor_b32_e32 v69, 0x80000000, v73
	v_xor_b32_e32 v68, 0x80000000, v72
	v_pk_mul_f32 v[68:69], v[76:77], v[68:69]
	v_pk_mul_f32 v[66:67], v[74:75], v[66:67]
	global_store_dwordx4 v[94:95], v[66:69], off offset:320
	s_nop 1
	v_pk_add_f32 v[66:67], v[70:71], -1.0 op_sel_hi:[1,0]
	v_pk_add_f32 v[68:69], v[72:73], -1.0 op_sel_hi:[1,0]
	v_pk_fma_f32 v[66:67], v[78:79], v[66:67], 1.0 op_sel_hi:[1,1,0]
	v_pk_fma_f32 v[68:69], v[80:81], v[68:69], 1.0 op_sel_hi:[1,1,0]
	v_pk_mul_f32 v[66:67], v[54:55], v[66:67]
	v_pk_mul_f32 v[68:69], v[56:57], v[68:69]
	global_store_dwordx4 v[94:95], v[66:69], off offset:576
	ds_read_b128 v[70:73], v255 offset:80
	s_waitcnt lgkmcnt(0)
	v_add_f32_e32 v70, v62, v70
	v_add_f32_e32 v71, v63, v71
	v_add_f32_e32 v72, v64, v72
	v_add_f32_e32 v73, v65, v73
	ds_read_b128 v[62:65], v255 offset:208
	s_waitcnt lgkmcnt(0)
	v_add_f32_e32 v58, v58, v62
	v_mul_f32_e32 v62, 0xbfb8aa3b, v70
	v_exp_f32_e32 v62, v62
	v_add_f32_e32 v59, v59, v63
	v_add_f32_e32 v60, v60, v64
	v_add_f32_e32 v61, v61, v65
	v_add_f32_e32 v70, 1.0, v62
	v_div_scale_f32 v62, s[10:11], v70, v70, s45
	v_rcp_f32_e32 v63, v62
	v_mul_f32_e32 v58, 0xbfb8aa3b, v58
	v_mul_f32_e32 v59, 0xbfb8aa3b, v59
	v_exp_f32_e32 v58, v58
	v_fma_f32 v64, -v62, v63, 1.0
	v_fmac_f32_e32 v63, v64, v63
	v_div_scale_f32 v64, vcc, s45, v70, s45
	v_mul_f32_e32 v65, v64, v63
	v_fma_f32 v92, -v62, v65, v64
	v_fmac_f32_e32 v65, v92, v63
	v_fma_f32 v62, -v62, v65, v64
	v_div_fmas_f32 v92, v62, v63, v65
	v_mul_f32_e32 v62, 0xbfb8aa3b, v71
	v_exp_f32_e32 v62, v62
	v_exp_f32_e32 v59, v59
	v_mul_f32_e32 v60, 0xbfb8aa3b, v60
	v_mul_f32_e32 v61, 0xbfb8aa3b, v61
	v_add_f32_e32 v71, 1.0, v62
	v_div_scale_f32 v62, s[10:11], v71, v71, s45
	v_rcp_f32_e32 v63, v62
	v_pk_add_f32 v[58:59], v[58:59], 1.0 op_sel_hi:[1,0]
	v_exp_f32_e32 v60, v60
	v_exp_f32_e32 v61, v61
	v_fma_f32 v64, -v62, v63, 1.0
	v_fmac_f32_e32 v63, v64, v63
	v_div_scale_f32 v64, vcc, s45, v71, s45
	v_mul_f32_e32 v65, v64, v63
	v_fma_f32 v93, -v62, v65, v64
	v_fmac_f32_e32 v65, v93, v63
	v_fma_f32 v62, -v62, v65, v64
	v_div_fmas_f32 v93, v62, v63, v65
	v_div_scale_f32 v62, s[10:11], v59, v59, 1.0
	v_rcp_f32_e32 v63, v62
	v_pk_add_f32 v[60:61], v[60:61], 1.0 op_sel_hi:[1,0]
	v_fma_f32 v64, -v62, v63, 1.0
	v_fmac_f32_e32 v63, v64, v63
	v_div_scale_f32 v64, vcc, 1.0, v59, 1.0
	v_mul_f32_e32 v65, v64, v63
	v_fma_f32 v96, -v62, v65, v64
	v_fmac_f32_e32 v65, v96, v63
	v_fma_f32 v62, -v62, v65, v64
	v_div_fmas_f32 v62, v62, v63, v65
	v_div_scale_f32 v63, s[10:11], v58, v58, 1.0
	v_rcp_f32_e32 v64, v63
	v_div_fixup_f32 v59, v62, v59, 1.0
	v_mul_f32_e32 v62, 0xbfb8aa3b, v72
	v_exp_f32_e32 v62, v62
	v_fma_f32 v65, -v63, v64, 1.0
	v_fmac_f32_e32 v64, v65, v64
	v_div_scale_f32 v65, vcc, 1.0, v58, 1.0
	v_mul_f32_e32 v96, v65, v64
	v_fma_f32 v97, -v63, v96, v65
	v_fmac_f32_e32 v96, v97, v64
	v_fma_f32 v63, -v63, v96, v65
	v_add_f32_e32 v72, 1.0, v62
	v_div_fmas_f32 v63, v63, v64, v96
	v_div_scale_f32 v62, s[10:11], v72, v72, s45
	v_div_fixup_f32 v58, v63, v58, 1.0
	v_rcp_f32_e32 v63, v62
	s_nop 0
	v_fma_f32 v64, -v62, v63, 1.0
	v_fmac_f32_e32 v63, v64, v63
	v_div_scale_f32 v64, vcc, s45, v72, s45
	v_mul_f32_e32 v65, v64, v63
	v_fma_f32 v96, -v62, v65, v64
	v_fmac_f32_e32 v65, v96, v63
	v_fma_f32 v62, -v62, v65, v64
	v_div_fmas_f32 v96, v62, v63, v65
	v_mul_f32_e32 v62, 0xbfb8aa3b, v73
	v_exp_f32_e32 v62, v62
	s_nop 0
	v_add_f32_e32 v73, 1.0, v62
	v_div_scale_f32 v62, s[10:11], v73, v73, s45
	v_rcp_f32_e32 v63, v62
	s_nop 0
	v_fma_f32 v64, -v62, v63, 1.0
	v_fmac_f32_e32 v63, v64, v63
	v_div_scale_f32 v64, vcc, s45, v73, s45
	v_mul_f32_e32 v65, v64, v63
	v_fma_f32 v97, -v62, v65, v64
	v_fmac_f32_e32 v65, v97, v63
	v_fma_f32 v62, -v62, v65, v64
	v_div_fmas_f32 v97, v62, v63, v65
	v_div_scale_f32 v62, s[10:11], v61, v61, 1.0
	v_rcp_f32_e32 v63, v62
	s_nop 0
	v_fma_f32 v64, -v62, v63, 1.0
	v_fmac_f32_e32 v63, v64, v63
	v_div_scale_f32 v64, vcc, 1.0, v61, 1.0
	v_mul_f32_e32 v65, v64, v63
	v_fma_f32 v200, -v62, v65, v64
	v_fmac_f32_e32 v65, v200, v63
	v_fma_f32 v62, -v62, v65, v64
	v_div_fmas_f32 v62, v62, v63, v65
	v_div_scale_f32 v63, s[10:11], v60, v60, 1.0
	v_rcp_f32_e32 v64, v63
	v_div_fixup_f32 v61, v62, v61, 1.0
	v_fma_f32 v65, -v63, v64, 1.0
	v_fmac_f32_e32 v64, v65, v64
	v_div_scale_f32 v65, vcc, 1.0, v60, 1.0
	v_mul_f32_e32 v200, v65, v64
	v_fma_f32 v201, -v63, v200, v65
	v_fmac_f32_e32 v200, v201, v64
	v_fma_f32 v63, -v63, v200, v65
	v_div_fmas_f32 v63, v63, v64, v200
	v_div_fixup_f32 v60, v63, v60, 1.0
	v_pk_add_f32 v[62:63], v[58:59], -1.0 op_sel_hi:[1,0]
	v_pk_add_f32 v[64:65], v[60:61], -1.0 op_sel_hi:[1,0]
	v_pk_fma_f32 v[62:63], v[78:79], v[62:63], 1.0 op_sel_hi:[1,1,0]
	v_pk_fma_f32 v[64:65], v[80:81], v[64:65], 1.0 op_sel_hi:[1,1,0]
	v_pk_mul_f32 v[54:55], v[54:55], v[62:63]
	v_pk_mul_f32 v[56:57], v[56:57], v[64:65]
	v_div_fixup_f32 v62, v92, v70, s45
	v_div_fixup_f32 v63, v93, v71, s45
	v_div_fixup_f32 v64, v96, v72, s45
	v_div_fixup_f32 v65, v97, v73, s45
	v_mul_f32_e32 v62, 0x3fb8aa3b, v62
	v_mul_f32_e32 v63, 0x3fb8aa3b, v63
	v_mul_f32_e32 v64, 0x3fb8aa3b, v64
	v_mul_f32_e32 v65, 0x3fb8aa3b, v65
	v_exp_f32_e32 v62, v62
	v_exp_f32_e32 v63, v63
	v_exp_f32_e32 v64, v64
	v_exp_f32_e32 v65, v65
	v_xor_b32_e32 v59, 0x80000000, v59
	v_xor_b32_e32 v58, 0x80000000, v58
	v_xor_b32_e32 v61, 0x80000000, v61
	v_xor_b32_e32 v60, 0x80000000, v60
	v_pk_mul_f32 v[58:59], v[74:75], v[58:59]
	v_pk_mul_f32 v[60:61], v[76:77], v[60:61]
	global_store_dwordx4 v[82:83], v[62:65], off offset:64
	global_store_dwordx4 v[82:83], v[58:61], off offset:320
	global_store_dwordx4 v[82:83], v[54:57], off offset:576
	s_nop 0
	v_lshl_add_u64 v[58:59], v[170:171], 2, v[190:191]
	global_load_dwordx4 v[70:73], v[58:59], off
	s_nop 0
	global_load_dwordx4 v[58:61], v[188:189], off offset:2176
	flat_load_dwordx4 v[74:77], v[174:175] offset:128
	flat_load_dwordx4 v[62:65], v[176:177] offset:128
	s_waitcnt vmcnt(0)
	global_store_dwordx4 v[186:187], v[70:73], off offset:640
	s_nop 1
	v_pk_mul_f32 v[72:73], v[196:197], v[130:131] op_sel_hi:[1,0]
	v_pk_mul_f32 v[70:71], v[198:199], v[130:131] op_sel_hi:[1,0]
	global_store_dwordx4 v[186:187], v[58:61], off offset:128
	global_store_dwordx4 v[186:187], v[70:73], off offset:384
	ds_read_b128 v[78:81], v255 offset:32
	s_waitcnt lgkmcnt(0)
	v_add_f32_e32 v78, v42, v78
	v_add_f32_e32 v79, v43, v79
	v_add_f32_e32 v80, v44, v80
	v_add_f32_e32 v81, v45, v81
	ds_read_b128 v[42:45], v255 offset:160
	s_waitcnt lgkmcnt(0)
	v_add_f32_e32 v44, v40, v44
	v_mul_f32_e32 v40, 0xbfb8aa3b, v78
	v_exp_f32_e32 v40, v40
	v_add_f32_e32 v45, v41, v45
	v_add_f32_e32 v38, v38, v42
	v_add_f32_e32 v39, v39, v43
	v_add_f32_e32 v40, 1.0, v40
	v_div_scale_f32 v41, s[10:11], v40, v40, s45
	v_rcp_f32_e32 v42, v41
	v_mul_f32_e32 v38, 0xbfb8aa3b, v38
	v_mul_f32_e32 v39, 0xbfb8aa3b, v39
	v_exp_f32_e32 v38, v38
	v_fma_f32 v43, -v41, v42, 1.0
	v_fmac_f32_e32 v42, v43, v42
	v_div_scale_f32 v43, vcc, s45, v40, s45
	v_mul_f32_e32 v78, v43, v42
	v_fma_f32 v92, -v41, v78, v43
	v_fmac_f32_e32 v78, v92, v42
	v_fma_f32 v41, -v41, v78, v43
	v_div_fmas_f32 v41, v41, v42, v78
	v_mul_f32_e32 v42, 0xbfb8aa3b, v79
	v_exp_f32_e32 v42, v42
	v_exp_f32_e32 v39, v39
	v_add_f32_e32 v78, 1.0, v42
	v_div_scale_f32 v42, s[10:11], v78, v78, s45
	v_rcp_f32_e32 v43, v42
	s_nop 0
	v_fma_f32 v79, -v42, v43, 1.0
	v_fmac_f32_e32 v43, v79, v43
	v_div_scale_f32 v79, vcc, s45, v78, s45
	v_mul_f32_e32 v92, v79, v43
	v_fma_f32 v93, -v42, v92, v79
	v_fmac_f32_e32 v92, v93, v43
	v_fma_f32 v42, -v42, v92, v79
	v_div_fmas_f32 v79, v42, v43, v92
	v_pk_add_f32 v[42:43], v[38:39], 1.0 op_sel_hi:[1,0]
	s_nop 0
	v_div_scale_f32 v38, s[10:11], v43, v43, 1.0
	v_rcp_f32_e32 v39, v38
	s_nop 0
	v_fma_f32 v92, -v38, v39, 1.0
	v_fmac_f32_e32 v39, v92, v39
	v_div_scale_f32 v92, vcc, 1.0, v43, 1.0
	v_mul_f32_e32 v93, v92, v39
	v_fma_f32 v96, -v38, v93, v92
	v_fmac_f32_e32 v93, v96, v39
	v_fma_f32 v38, -v38, v93, v92
	v_div_fmas_f32 v92, v38, v39, v93
	v_div_scale_f32 v38, s[10:11], v42, v42, 1.0
	v_rcp_f32_e32 v39, v38
	v_div_fixup_f32 v43, v92, v43, 1.0
	v_fma_f32 v93, -v38, v39, 1.0
	v_fmac_f32_e32 v39, v93, v39
	v_div_scale_f32 v93, vcc, 1.0, v42, 1.0
	v_mul_f32_e32 v96, v93, v39
	v_fma_f32 v97, -v38, v96, v93
	v_fmac_f32_e32 v96, v97, v39
	v_fma_f32 v38, -v38, v96, v93
	v_div_fmas_f32 v93, v38, v39, v96
	v_mul_f32_e32 v38, 0xbfb8aa3b, v80
	v_exp_f32_e32 v38, v38
	v_div_fixup_f32 v42, v93, v42, 1.0
	v_add_f32_e32 v80, 1.0, v38
	v_div_scale_f32 v38, s[10:11], v80, v80, s45
	v_rcp_f32_e32 v39, v38
	s_nop 0
	v_fma_f32 v96, -v38, v39, 1.0
	v_fmac_f32_e32 v39, v96, v39
	v_div_scale_f32 v96, vcc, s45, v80, s45
	v_mul_f32_e32 v97, v96, v39
	v_fma_f32 v196, -v38, v97, v96
	v_fmac_f32_e32 v97, v196, v39
	v_fma_f32 v38, -v38, v97, v96
	v_div_fmas_f32 v96, v38, v39, v97
	v_mul_f32_e32 v38, 0xbfb8aa3b, v81
	v_exp_f32_e32 v38, v38
	s_nop 0
	v_add_f32_e32 v81, 1.0, v38
	v_div_scale_f32 v38, s[10:11], v81, v81, s45
	v_rcp_f32_e32 v39, v38
	s_nop 0
	v_fma_f32 v97, -v38, v39, 1.0
	v_fmac_f32_e32 v39, v97, v39
	v_div_scale_f32 v97, vcc, s45, v81, s45
	v_mul_f32_e32 v196, v97, v39
	v_fma_f32 v197, -v38, v196, v97
	v_fmac_f32_e32 v196, v197, v39
	v_fma_f32 v38, -v38, v196, v97
	v_div_fmas_f32 v97, v38, v39, v196
	v_div_fixup_f32 v38, v41, v40, s45
	v_div_fixup_f32 v39, v79, v78, s45
	v_div_fixup_f32 v40, v96, v80, s45
	v_div_fixup_f32 v41, v97, v81, s45
	v_mul_f32_e32 v38, 0x3fb8aa3b, v38
	v_mul_f32_e32 v39, 0x3fb8aa3b, v39
	v_mul_f32_e32 v40, 0x3fb8aa3b, v40
	v_mul_f32_e32 v41, 0x3fb8aa3b, v41
	v_exp_f32_e32 v38, v38
	v_exp_f32_e32 v39, v39
	v_exp_f32_e32 v40, v40
	v_exp_f32_e32 v41, v41
	global_store_dwordx4 v[94:95], v[38:41], off offset:128
	s_nop 1
	v_mul_f32_e32 v38, 0xbfb8aa3b, v44
	v_mul_f32_e32 v39, 0xbfb8aa3b, v45
	v_exp_f32_e32 v38, v38
	v_exp_f32_e32 v39, v39
	s_nop 0
	v_pk_add_f32 v[38:39], v[38:39], 1.0 op_sel_hi:[1,0]
	s_nop 0
	v_div_scale_f32 v40, s[10:11], v39, v39, 1.0
	v_rcp_f32_e32 v41, v40
	s_nop 0
	v_fma_f32 v44, -v40, v41, 1.0
	v_fmac_f32_e32 v41, v44, v41
	v_div_scale_f32 v44, vcc, 1.0, v39, 1.0
	v_mul_f32_e32 v45, v44, v41
	v_fma_f32 v78, -v40, v45, v44
	v_fmac_f32_e32 v45, v78, v41
	v_fma_f32 v40, -v40, v45, v44
	v_div_fmas_f32 v40, v40, v41, v45
	v_div_scale_f32 v41, s[10:11], v38, v38, 1.0
	v_rcp_f32_e32 v44, v41
	s_nop 0
	v_fma_f32 v45, -v41, v44, 1.0
	v_fmac_f32_e32 v44, v45, v44
	v_div_scale_f32 v45, vcc, 1.0, v38, 1.0
	v_mul_f32_e32 v78, v45, v44
	v_fma_f32 v79, -v41, v78, v45
	v_fmac_f32_e32 v78, v79, v44
	v_fma_f32 v41, -v41, v78, v45
	v_div_fmas_f32 v41, v41, v44, v78
	v_div_fixup_f32 v45, v40, v39, 1.0
	v_div_fixup_f32 v44, v41, v38, 1.0
	v_xor_b32_e32 v39, 0x80000000, v43
	v_xor_b32_e32 v38, 0x80000000, v42
	v_xor_b32_e32 v41, 0x80000000, v45
	v_xor_b32_e32 v40, 0x80000000, v44
	v_pk_mul_f32 v[40:41], v[72:73], v[40:41]
	v_pk_mul_f32 v[38:39], v[70:71], v[38:39]
	global_store_dwordx4 v[94:95], v[38:41], off offset:384
	s_nop 1
	v_pk_add_f32 v[38:39], v[42:43], -1.0 op_sel_hi:[1,0]
	v_pk_add_f32 v[40:41], v[44:45], -1.0 op_sel_hi:[1,0]
	v_pk_fma_f32 v[38:39], v[74:75], v[38:39], 1.0 op_sel_hi:[1,1,0]
	v_pk_fma_f32 v[40:41], v[76:77], v[40:41], 1.0 op_sel_hi:[1,1,0]
	v_pk_mul_f32 v[38:39], v[26:27], v[38:39]
	v_pk_mul_f32 v[40:41], v[28:29], v[40:41]
	global_store_dwordx4 v[94:95], v[38:41], off offset:640
	ds_read_b128 v[42:45], v255 offset:96
	s_waitcnt lgkmcnt(0)
	v_add_f32_e32 v42, v34, v42
	v_add_f32_e32 v43, v35, v43
	v_add_f32_e32 v44, v36, v44
	v_add_f32_e32 v45, v37, v45
	ds_read_b128 v[34:37], v255 offset:224
	s_waitcnt lgkmcnt(0)
	v_add_f32_e32 v30, v30, v34
	v_mul_f32_e32 v34, 0xbfb8aa3b, v42
	v_exp_f32_e32 v34, v34
	v_add_f32_e32 v31, v31, v35
	v_add_f32_e32 v32, v32, v36
	v_add_f32_e32 v33, v33, v37
	v_add_f32_e32 v42, 1.0, v34
	v_div_scale_f32 v34, s[10:11], v42, v42, s45
	v_rcp_f32_e32 v35, v34
	v_mul_f32_e32 v30, 0xbfb8aa3b, v30
	v_mul_f32_e32 v31, 0xbfb8aa3b, v31
	v_exp_f32_e32 v30, v30
	v_fma_f32 v36, -v34, v35, 1.0
	v_fmac_f32_e32 v35, v36, v35
	v_div_scale_f32 v36, vcc, s45, v42, s45
	v_mul_f32_e32 v37, v36, v35
	v_fma_f32 v78, -v34, v37, v36
	v_fmac_f32_e32 v37, v78, v35
	v_fma_f32 v34, -v34, v37, v36
	v_div_fmas_f32 v78, v34, v35, v37
	v_mul_f32_e32 v34, 0xbfb8aa3b, v43
	v_exp_f32_e32 v34, v34
	v_exp_f32_e32 v31, v31
	v_mul_f32_e32 v32, 0xbfb8aa3b, v32
	v_mul_f32_e32 v33, 0xbfb8aa3b, v33
	v_add_f32_e32 v43, 1.0, v34
	v_div_scale_f32 v34, s[10:11], v43, v43, s45
	v_rcp_f32_e32 v35, v34
	v_pk_add_f32 v[30:31], v[30:31], 1.0 op_sel_hi:[1,0]
	v_exp_f32_e32 v32, v32
	v_exp_f32_e32 v33, v33
	v_fma_f32 v36, -v34, v35, 1.0
	v_fmac_f32_e32 v35, v36, v35
	v_div_scale_f32 v36, vcc, s45, v43, s45
	v_mul_f32_e32 v37, v36, v35
	v_fma_f32 v79, -v34, v37, v36
	v_fmac_f32_e32 v37, v79, v35
	v_fma_f32 v34, -v34, v37, v36
	v_div_fmas_f32 v79, v34, v35, v37
	v_div_scale_f32 v34, s[10:11], v31, v31, 1.0
	v_rcp_f32_e32 v35, v34
	v_pk_add_f32 v[32:33], v[32:33], 1.0 op_sel_hi:[1,0]
	v_fma_f32 v36, -v34, v35, 1.0
	v_fmac_f32_e32 v35, v36, v35
	v_div_scale_f32 v36, vcc, 1.0, v31, 1.0
	v_mul_f32_e32 v37, v36, v35
	v_fma_f32 v80, -v34, v37, v36
	v_fmac_f32_e32 v37, v80, v35
	v_fma_f32 v34, -v34, v37, v36
	v_div_fmas_f32 v34, v34, v35, v37
	v_div_scale_f32 v35, s[10:11], v30, v30, 1.0
	v_rcp_f32_e32 v36, v35
	v_div_fixup_f32 v31, v34, v31, 1.0
	v_mul_f32_e32 v34, 0xbfb8aa3b, v44
	v_exp_f32_e32 v34, v34
	v_fma_f32 v37, -v35, v36, 1.0
	v_fmac_f32_e32 v36, v37, v36
	v_div_scale_f32 v37, vcc, 1.0, v30, 1.0
	v_mul_f32_e32 v80, v37, v36
	v_fma_f32 v81, -v35, v80, v37
	v_fmac_f32_e32 v80, v81, v36
	v_fma_f32 v35, -v35, v80, v37
	v_add_f32_e32 v44, 1.0, v34
	v_div_fmas_f32 v35, v35, v36, v80
	v_div_scale_f32 v34, s[10:11], v44, v44, s45
	v_div_fixup_f32 v30, v35, v30, 1.0
	v_rcp_f32_e32 v35, v34
	s_nop 0
	v_fma_f32 v36, -v34, v35, 1.0
	v_fmac_f32_e32 v35, v36, v35
	v_div_scale_f32 v36, vcc, s45, v44, s45
	v_mul_f32_e32 v37, v36, v35
	v_fma_f32 v80, -v34, v37, v36
	v_fmac_f32_e32 v37, v80, v35
	v_fma_f32 v34, -v34, v37, v36
	v_div_fmas_f32 v80, v34, v35, v37
	v_mul_f32_e32 v34, 0xbfb8aa3b, v45
	v_exp_f32_e32 v34, v34
	s_nop 0
	v_add_f32_e32 v45, 1.0, v34
	v_div_scale_f32 v34, s[10:11], v45, v45, s45
	v_rcp_f32_e32 v35, v34
	s_nop 0
	v_fma_f32 v36, -v34, v35, 1.0
	v_fmac_f32_e32 v35, v36, v35
	v_div_scale_f32 v36, vcc, s45, v45, s45
	v_mul_f32_e32 v37, v36, v35
	v_fma_f32 v81, -v34, v37, v36
	v_fmac_f32_e32 v37, v81, v35
	v_fma_f32 v34, -v34, v37, v36
	v_div_fmas_f32 v81, v34, v35, v37
	v_div_scale_f32 v34, s[10:11], v33, v33, 1.0
	v_rcp_f32_e32 v35, v34
	s_nop 0
	v_fma_f32 v36, -v34, v35, 1.0
	v_fmac_f32_e32 v35, v36, v35
	v_div_scale_f32 v36, vcc, 1.0, v33, 1.0
	v_mul_f32_e32 v37, v36, v35
	v_fma_f32 v92, -v34, v37, v36
	v_fmac_f32_e32 v37, v92, v35
	v_fma_f32 v34, -v34, v37, v36
	v_div_fmas_f32 v34, v34, v35, v37
	v_div_scale_f32 v35, s[10:11], v32, v32, 1.0
	v_rcp_f32_e32 v36, v35
	v_div_fixup_f32 v33, v34, v33, 1.0
	v_fma_f32 v37, -v35, v36, 1.0
	v_fmac_f32_e32 v36, v37, v36
	v_div_scale_f32 v37, vcc, 1.0, v32, 1.0
	v_mul_f32_e32 v92, v37, v36
	v_fma_f32 v93, -v35, v92, v37
	v_fmac_f32_e32 v92, v93, v36
	v_fma_f32 v35, -v35, v92, v37
	v_div_fmas_f32 v35, v35, v36, v92
	v_div_fixup_f32 v32, v35, v32, 1.0
	v_pk_add_f32 v[34:35], v[30:31], -1.0 op_sel_hi:[1,0]
	v_pk_add_f32 v[36:37], v[32:33], -1.0 op_sel_hi:[1,0]
	v_pk_fma_f32 v[34:35], v[74:75], v[34:35], 1.0 op_sel_hi:[1,1,0]
	v_pk_fma_f32 v[36:37], v[76:77], v[36:37], 1.0 op_sel_hi:[1,1,0]
	v_pk_mul_f32 v[74:75], v[26:27], v[34:35]
	v_pk_mul_f32 v[76:77], v[28:29], v[36:37]
	v_xor_b32_e32 v27, 0x80000000, v31
	v_xor_b32_e32 v26, 0x80000000, v30
	v_xor_b32_e32 v29, 0x80000000, v33
	v_xor_b32_e32 v28, 0x80000000, v32
	v_div_fixup_f32 v30, v78, v42, s45
	v_div_fixup_f32 v31, v79, v43, s45
	v_div_fixup_f32 v32, v80, v44, s45
	v_div_fixup_f32 v33, v81, v45, s45
	v_mul_f32_e32 v30, 0x3fb8aa3b, v30
	v_mul_f32_e32 v31, 0x3fb8aa3b, v31
	v_mul_f32_e32 v32, 0x3fb8aa3b, v32
	v_mul_f32_e32 v33, 0x3fb8aa3b, v33
	v_exp_f32_e32 v30, v30
	v_exp_f32_e32 v31, v31
	v_exp_f32_e32 v32, v32
	v_exp_f32_e32 v33, v33
	v_pk_mul_f32 v[28:29], v[72:73], v[28:29]
	v_pk_mul_f32 v[26:27], v[70:71], v[26:27]
	global_store_dwordx4 v[82:83], v[30:33], off offset:128
	global_store_dwordx4 v[82:83], v[26:29], off offset:384
	global_store_dwordx4 v[82:83], v[74:77], off offset:640
	v_lshl_add_u64 v[30:31], v[172:173], 2, v[190:191]
	global_load_dwordx4 v[70:73], v[30:31], off
	s_nop 0
	global_load_dwordx4 v[30:33], v[188:189], off offset:2240
	flat_load_dwordx4 v[42:45], v[174:175] offset:192
	flat_load_dwordx4 v[34:37], v[176:177] offset:192
	v_pk_mul_f32 v[28:29], v[192:193], v[130:131] op_sel_hi:[1,0]
	v_pk_mul_f32 v[26:27], v[194:195], v[130:131] op_sel_hi:[1,0]
	s_waitcnt vmcnt(0)
	global_store_dwordx4 v[186:187], v[70:73], off offset:704
	global_store_dwordx4 v[186:187], v[30:33], off offset:192
	global_store_dwordx4 v[186:187], v[26:29], off offset:448
	ds_read_b128 v[70:73], v255 offset:48
	s_waitcnt lgkmcnt(0)
	v_add_f32_e32 v70, v18, v70
	v_add_f32_e32 v71, v19, v71
	v_add_f32_e32 v72, v20, v72
	v_add_f32_e32 v73, v21, v73
	ds_read_b128 v[18:21], v255 offset:176
	s_waitcnt lgkmcnt(0)
	v_add_f32_e32 v15, v15, v19
	v_add_f32_e32 v19, v16, v20
	v_mul_f32_e32 v16, 0xbfb8aa3b, v70
	v_exp_f32_e32 v16, v16
	v_add_f32_e32 v78, v17, v21
	v_add_f32_e32 v14, v14, v18
	v_fma_f32 v18, v22, v84, 0
	v_add_f32_e32 v16, 1.0, v16
	v_div_scale_f32 v17, s[10:11], v16, v16, s45
	v_rcp_f32_e32 v20, v17
	v_fmac_f32_e32 v18, v23, v85
	v_fmac_f32_e32 v18, v24, v86
	v_fmac_f32_e32 v18, v25, v87
	v_fma_f32 v21, -v17, v20, 1.0
	v_fmac_f32_e32 v20, v21, v20
	v_div_scale_f32 v21, vcc, s45, v16, s45
	v_fmac_f32_e32 v18, v22, v88
	v_mul_f32_e32 v22, v21, v20
	v_fmac_f32_e32 v18, v23, v89
	v_fma_f32 v23, -v17, v22, v21
	v_fmac_f32_e32 v22, v23, v20
	v_fma_f32 v17, -v17, v22, v21
	v_div_fmas_f32 v17, v17, v20, v22
	v_mul_f32_e32 v20, 0xbfb8aa3b, v71
	v_exp_f32_e32 v20, v20
	v_mul_f32_e32 v14, 0xbfb8aa3b, v14
	v_mul_f32_e32 v15, 0xbfb8aa3b, v15
	v_fmac_f32_e32 v18, v24, v90
	v_add_f32_e32 v22, 1.0, v20
	v_div_scale_f32 v20, s[10:11], v22, v22, s45
	v_rcp_f32_e32 v21, v20
	v_exp_f32_e32 v14, v14
	v_exp_f32_e32 v15, v15
	v_fmac_f32_e32 v18, v25, v91
	v_fma_f32 v23, -v20, v21, 1.0
	v_fmac_f32_e32 v21, v23, v21
	v_div_scale_f32 v23, vcc, s45, v22, s45
	v_mul_f32_e32 v24, v23, v21
	v_fma_f32 v25, -v20, v24, v23
	v_fmac_f32_e32 v24, v25, v21
	v_fma_f32 v20, -v20, v24, v23
	v_div_fmas_f32 v23, v20, v21, v24
	v_pk_add_f32 v[20:21], v[14:15], 1.0 op_sel_hi:[1,0]
	s_nop 0
	v_div_scale_f32 v14, s[10:11], v21, v21, 1.0
	v_rcp_f32_e32 v15, v14
	s_nop 0
	v_fma_f32 v24, -v14, v15, 1.0
	v_fmac_f32_e32 v15, v24, v15
	v_div_scale_f32 v24, vcc, 1.0, v21, 1.0
	v_mul_f32_e32 v25, v24, v15
	v_fma_f32 v70, -v14, v25, v24
	v_fmac_f32_e32 v25, v70, v15
	v_fma_f32 v14, -v14, v25, v24
	v_div_fmas_f32 v24, v14, v15, v25
	v_div_scale_f32 v14, s[10:11], v20, v20, 1.0
	v_rcp_f32_e32 v15, v14
	v_div_fixup_f32 v21, v24, v21, 1.0
	v_fma_f32 v25, -v14, v15, 1.0
	v_fmac_f32_e32 v15, v25, v15
	v_div_scale_f32 v25, vcc, 1.0, v20, 1.0
	v_mul_f32_e32 v70, v25, v15
	v_fma_f32 v71, -v14, v70, v25
	v_fmac_f32_e32 v70, v71, v15
	v_fma_f32 v14, -v14, v70, v25
	v_div_fmas_f32 v25, v14, v15, v70
	v_mul_f32_e32 v14, 0xbfb8aa3b, v72
	v_exp_f32_e32 v14, v14
	v_div_fixup_f32 v20, v25, v20, 1.0
	v_add_f32_e32 v70, 1.0, v14
	v_div_scale_f32 v14, s[10:11], v70, v70, s45
	v_rcp_f32_e32 v15, v14
	s_nop 0
	v_fma_f32 v71, -v14, v15, 1.0
	v_fmac_f32_e32 v15, v71, v15
	v_div_scale_f32 v71, vcc, s45, v70, s45
	v_mul_f32_e32 v72, v71, v15
	v_fma_f32 v79, -v14, v72, v71
	v_fmac_f32_e32 v72, v79, v15
	v_fma_f32 v14, -v14, v72, v71
	v_div_fmas_f32 v71, v14, v15, v72
	v_mul_f32_e32 v14, 0xbfb8aa3b, v73
	v_exp_f32_e32 v14, v14
	s_nop 0
	v_add_f32_e32 v72, 1.0, v14
	v_div_scale_f32 v14, s[10:11], v72, v72, s45
	v_rcp_f32_e32 v15, v14
	s_nop 0
	v_fma_f32 v73, -v14, v15, 1.0
	v_fmac_f32_e32 v15, v73, v15
	v_div_scale_f32 v73, vcc, s45, v72, s45
	v_mul_f32_e32 v79, v73, v15
	v_fma_f32 v80, -v14, v79, v73
	v_fmac_f32_e32 v79, v80, v15
	v_fma_f32 v14, -v14, v79, v73
	v_div_fmas_f32 v73, v14, v15, v79
	v_div_fixup_f32 v14, v17, v16, s45
	v_div_fixup_f32 v15, v23, v22, s45
	v_div_fixup_f32 v16, v71, v70, s45
	v_div_fixup_f32 v17, v73, v72, s45
	v_mul_f32_e32 v14, 0x3fb8aa3b, v14
	v_mul_f32_e32 v15, 0x3fb8aa3b, v15
	v_mul_f32_e32 v16, 0x3fb8aa3b, v16
	v_mul_f32_e32 v17, 0x3fb8aa3b, v17
	v_exp_f32_e32 v14, v14
	v_exp_f32_e32 v15, v15
	v_exp_f32_e32 v16, v16
	v_exp_f32_e32 v17, v17
	global_store_dwordx4 v[94:95], v[14:17], off offset:192
	s_nop 1
	v_mul_f32_e32 v14, 0xbfb8aa3b, v19
	v_mul_f32_e32 v15, 0xbfb8aa3b, v78
	v_exp_f32_e32 v14, v14
	v_exp_f32_e32 v15, v15
	s_nop 0
	v_pk_add_f32 v[14:15], v[14:15], 1.0 op_sel_hi:[1,0]
	s_nop 0
	v_div_scale_f32 v16, s[10:11], v15, v15, 1.0
	v_rcp_f32_e32 v17, v16
	s_nop 0
	v_fma_f32 v19, -v16, v17, 1.0
	v_fmac_f32_e32 v17, v19, v17
	v_div_scale_f32 v19, vcc, 1.0, v15, 1.0
	v_mul_f32_e32 v22, v19, v17
	v_fma_f32 v23, -v16, v22, v19
	v_fmac_f32_e32 v22, v23, v17
	v_fma_f32 v16, -v16, v22, v19
	v_div_fmas_f32 v16, v16, v17, v22
	v_div_scale_f32 v17, s[10:11], v14, v14, 1.0
	v_rcp_f32_e32 v19, v17
	s_nop 0
	v_fma_f32 v22, -v17, v19, 1.0
	v_fmac_f32_e32 v19, v22, v19
	v_div_scale_f32 v22, vcc, 1.0, v14, 1.0
	v_mul_f32_e32 v23, v22, v19
	v_fma_f32 v24, -v17, v23, v22
	v_fmac_f32_e32 v23, v24, v19
	v_fma_f32 v17, -v17, v23, v22
	v_div_fmas_f32 v17, v17, v19, v23
	v_div_fixup_f32 v23, v16, v15, 1.0
	v_div_fixup_f32 v22, v17, v14, 1.0
	v_xor_b32_e32 v15, 0x80000000, v21
	v_xor_b32_e32 v14, 0x80000000, v20
	v_xor_b32_e32 v17, 0x80000000, v23
	v_xor_b32_e32 v16, 0x80000000, v22
	v_pk_mul_f32 v[16:17], v[28:29], v[16:17]
	v_pk_mul_f32 v[14:15], v[26:27], v[14:15]
	global_store_dwordx4 v[94:95], v[14:17], off offset:448
	v_mul_f32_e32 v19, v46, v66
	v_fmac_f32_e32 v18, v50, v19
	v_pk_add_f32 v[14:15], v[20:21], -1.0 op_sel_hi:[1,0]
	v_mul_f32_e32 v19, v47, v67
	v_pk_fma_f32 v[14:15], v[42:43], v[14:15], 1.0 op_sel_hi:[1,1,0]
	v_fmac_f32_e32 v18, v51, v19
	v_pk_mul_f32 v[20:21], v[10:11], v[14:15]
	v_pk_add_f32 v[14:15], v[22:23], -1.0 op_sel_hi:[1,0]
	v_mul_f32_e32 v19, v48, v68
	v_pk_fma_f32 v[14:15], v[44:45], v[14:15], 1.0 op_sel_hi:[1,1,0]
	v_fmac_f32_e32 v18, v52, v19
	v_pk_mul_f32 v[22:23], v[12:13], v[14:15]
	global_store_dwordx4 v[94:95], v[20:23], off offset:704
	ds_read_b128 v[14:17], v255 offset:112
	v_mul_f32_e32 v19, v49, v69
	ds_read_b128 v[66:69], v255 offset:240
	v_fmac_f32_e32 v18, v53, v19
	v_mul_f32_e32 v19, v46, v54
	v_fmac_f32_e32 v18, v50, v19
	v_mul_f32_e32 v19, v47, v55
	v_fmac_f32_e32 v18, v51, v19
	v_mul_f32_e32 v19, v48, v56
	v_fmac_f32_e32 v18, v52, v19
	v_mul_f32_e32 v19, v49, v57
	v_fmac_f32_e32 v18, v53, v19
	v_mul_f32_e32 v19, v58, v38
	v_fmac_f32_e32 v18, v62, v19
	v_mul_f32_e32 v19, v59, v39
	v_fmac_f32_e32 v18, v63, v19
	v_mul_f32_e32 v19, v60, v40
	v_fmac_f32_e32 v18, v64, v19
	v_mul_f32_e32 v19, v61, v41
	v_fmac_f32_e32 v18, v65, v19
	v_mul_f32_e32 v19, v58, v74
	v_fmac_f32_e32 v18, v62, v19
	v_mul_f32_e32 v19, v59, v75
	v_fmac_f32_e32 v18, v63, v19
	v_mul_f32_e32 v19, v60, v76
	v_fmac_f32_e32 v18, v64, v19
	v_mul_f32_e32 v19, v61, v77
	v_fmac_f32_e32 v18, v65, v19
	v_mul_f32_e32 v19, v30, v20
	v_fmac_f32_e32 v18, v34, v19
	s_waitcnt lgkmcnt(0)
	v_add_f32_e32 v2, v2, v14
	v_mul_f32_e32 v2, 0xbfb8aa3b, v2
	v_exp_f32_e32 v2, v2
	v_mul_f32_e32 v14, v31, v21
	v_fmac_f32_e32 v18, v35, v14
	v_mul_f32_e32 v14, v32, v22
	v_add_f32_e32 v2, 1.0, v2
	v_div_scale_f32 v19, s[10:11], v2, v2, s45
	v_rcp_f32_e32 v20, v19
	v_add_f32_e32 v3, v3, v15
	v_fmac_f32_e32 v18, v36, v14
	v_mul_f32_e32 v14, v33, v23
	v_mul_f32_e32 v3, 0xbfb8aa3b, v3
	v_fmac_f32_e32 v18, v37, v14
	v_fma_f32 v14, -v19, v20, 1.0
	v_exp_f32_e32 v3, v3
	v_fmac_f32_e32 v20, v14, v20
	v_div_scale_f32 v14, vcc, s45, v2, s45
	v_mul_f32_e32 v21, v14, v20
	v_fma_f32 v22, -v19, v21, v14
	v_fmac_f32_e32 v21, v22, v20
	v_add_f32_e32 v15, 1.0, v3
	v_fma_f32 v14, -v19, v21, v14
	v_div_scale_f32 v19, s[10:11], v15, v15, s45
	v_div_fmas_f32 v14, v14, v20, v21
	v_rcp_f32_e32 v20, v19
	v_div_fixup_f32 v2, v14, v2, s45
	v_mul_f32_e32 v2, 0x3fb8aa3b, v2
	v_exp_f32_e32 v14, v2
	v_fma_f32 v3, -v19, v20, 1.0
	v_add_f32_e32 v2, v6, v66
	v_fmac_f32_e32 v20, v3, v20
	v_div_scale_f32 v6, vcc, s45, v15, s45
	v_mul_f32_e32 v21, v6, v20
	v_fma_f32 v3, -v19, v21, v6
	v_fmac_f32_e32 v21, v3, v20
	v_add_f32_e32 v3, v7, v67
	v_mul_f32_e32 v2, 0xbfb8aa3b, v2
	v_mul_f32_e32 v3, 0xbfb8aa3b, v3
	v_exp_f32_e32 v2, v2
	v_exp_f32_e32 v3, v3
	v_fma_f32 v6, -v19, v21, v6
	v_div_fmas_f32 v6, v6, v20, v21
	v_div_fixup_f32 v6, v6, v15, s45
	v_pk_add_f32 v[2:3], v[2:3], 1.0 op_sel_hi:[1,0]
	v_mul_f32_e32 v6, 0x3fb8aa3b, v6
	v_div_scale_f32 v7, s[10:11], v3, v3, 1.0
	v_rcp_f32_e32 v19, v7
	v_exp_f32_e32 v15, v6
	v_add_f32_e32 v4, v4, v16
	v_mul_f32_e32 v4, 0xbfb8aa3b, v4
	v_fma_f32 v6, -v7, v19, 1.0
	v_fmac_f32_e32 v19, v6, v19
	v_div_scale_f32 v6, vcc, 1.0, v3, 1.0
	v_mul_f32_e32 v20, v6, v19
	v_fma_f32 v21, -v7, v20, v6
	v_fmac_f32_e32 v20, v21, v19
	v_fma_f32 v6, -v7, v20, v6
	v_div_scale_f32 v7, s[10:11], v2, v2, 1.0
	v_rcp_f32_e32 v21, v7
	v_div_fmas_f32 v6, v6, v19, v20
	v_div_fixup_f32 v3, v6, v3, 1.0
	v_exp_f32_e32 v4, v4
	v_fma_f32 v6, -v7, v21, 1.0
	v_fmac_f32_e32 v21, v6, v21
	v_div_scale_f32 v6, vcc, 1.0, v2, 1.0
	v_mul_f32_e32 v19, v6, v21
	v_fma_f32 v20, -v7, v19, v6
	v_fmac_f32_e32 v19, v20, v21
	v_fma_f32 v6, -v7, v19, v6
	v_div_fmas_f32 v6, v6, v21, v19
	v_div_fixup_f32 v2, v6, v2, 1.0
	v_pk_add_f32 v[6:7], v[2:3], -1.0 op_sel_hi:[1,0]
	v_add_f32_e32 v4, 1.0, v4
	v_pk_fma_f32 v[6:7], v[42:43], v[6:7], 1.0 op_sel_hi:[1,1,0]
	v_add_f32_e32 v5, v5, v17
	v_pk_mul_f32 v[6:7], v[10:11], v[6:7]
	v_div_scale_f32 v11, s[10:11], v4, v4, s45
	v_rcp_f32_e32 v16, v11
	v_mul_f32_e32 v10, v30, v6
	v_fmac_f32_e32 v18, v34, v10
	v_mul_f32_e32 v10, v31, v7
	v_fmac_f32_e32 v18, v35, v10
	v_fma_f32 v10, -v11, v16, 1.0
	v_fmac_f32_e32 v16, v10, v16
	v_div_scale_f32 v10, vcc, s45, v4, s45
	v_mul_f32_e32 v19, v10, v16
	v_mul_f32_e32 v5, 0xbfb8aa3b, v5
	v_fma_f32 v20, -v11, v19, v10
	v_exp_f32_e32 v5, v5
	v_fmac_f32_e32 v19, v20, v16
	v_fma_f32 v10, -v11, v19, v10
	v_div_fmas_f32 v10, v10, v16, v19
	v_div_fixup_f32 v4, v10, v4, s45
	v_add_f32_e32 v10, 1.0, v5
	v_div_scale_f32 v11, s[10:11], v10, v10, s45
	v_rcp_f32_e32 v17, v11
	v_mul_f32_e32 v4, 0x3fb8aa3b, v4
	v_exp_f32_e32 v16, v4
	v_add_f32_e32 v4, v8, v68
	v_fma_f32 v5, -v11, v17, 1.0
	v_fmac_f32_e32 v17, v5, v17
	v_div_scale_f32 v8, vcc, s45, v10, s45
	v_mul_f32_e32 v19, v8, v17
	v_fma_f32 v5, -v11, v19, v8
	v_fmac_f32_e32 v19, v5, v17
	v_add_f32_e32 v5, v9, v69
	v_mul_f32_e32 v4, 0xbfb8aa3b, v4
	v_mul_f32_e32 v5, 0xbfb8aa3b, v5
	v_exp_f32_e32 v4, v4
	v_exp_f32_e32 v5, v5
	v_fma_f32 v8, -v11, v19, v8
	v_div_fmas_f32 v8, v8, v17, v19
	v_div_fixup_f32 v8, v8, v10, s45
	v_pk_add_f32 v[4:5], v[4:5], 1.0 op_sel_hi:[1,0]
	v_mul_f32_e32 v8, 0x3fb8aa3b, v8
	v_div_scale_f32 v9, s[10:11], v5, v5, 1.0
	v_rcp_f32_e32 v11, v9
	v_exp_f32_e32 v17, v8
	v_fma_f32 v8, -v9, v11, 1.0
	v_fmac_f32_e32 v11, v8, v11
	v_div_scale_f32 v8, vcc, 1.0, v5, 1.0
	v_mul_f32_e32 v10, v8, v11
	v_fma_f32 v19, -v9, v10, v8
	v_fmac_f32_e32 v10, v19, v11
	v_fma_f32 v8, -v9, v10, v8
	v_div_scale_f32 v9, s[10:11], v4, v4, 1.0
	v_rcp_f32_e32 v19, v9
	v_div_fmas_f32 v8, v8, v11, v10
	v_div_fixup_f32 v5, v8, v5, 1.0
	v_fma_f32 v8, -v9, v19, 1.0
	v_fmac_f32_e32 v19, v8, v19
	v_div_scale_f32 v8, vcc, 1.0, v4, 1.0
	v_mul_f32_e32 v10, v8, v19
	v_fma_f32 v11, -v9, v10, v8
	v_fmac_f32_e32 v10, v11, v19
	v_fma_f32 v8, -v9, v10, v8
	v_div_fmas_f32 v8, v8, v19, v10
	v_div_fixup_f32 v4, v8, v4, 1.0
	v_pk_add_f32 v[8:9], v[4:5], -1.0 op_sel_hi:[1,0]
	v_xor_b32_e32 v11, 0x80000000, v3
	v_pk_fma_f32 v[8:9], v[44:45], v[8:9], 1.0 op_sel_hi:[1,1,0]
	s_nop 0
	v_pk_mul_f32 v[8:9], v[12:13], v[8:9]
	s_nop 0
	v_mul_f32_e32 v10, v32, v8
	v_fmac_f32_e32 v18, v36, v10
	v_mul_f32_e32 v3, v33, v9
	v_fmac_f32_e32 v18, v37, v3
	ds_bpermute_b32 v19, v244, v18
	v_xor_b32_e32 v10, 0x80000000, v2
	v_xor_b32_e32 v3, 0x80000000, v5
	v_xor_b32_e32 v2, 0x80000000, v4
	v_pk_mul_f32 v[12:13], v[28:29], v[2:3]
	s_waitcnt lgkmcnt(0)
	v_add_f32_e32 v2, v18, v19
	ds_bpermute_b32 v3, v245, v2
	v_pk_mul_f32 v[10:11], v[26:27], v[10:11]
	global_store_dwordx4 v[82:83], v[14:17], off offset:192
	global_store_dwordx4 v[82:83], v[10:13], off offset:448
	global_store_dwordx4 v[82:83], v[6:9], off offset:704
	s_and_saveexec_b64 s[10:11], s[6:7]
	s_cbranch_execz .LBB0_473
	s_waitcnt lgkmcnt(0)
	v_add_f32_e32 v4, v2, v3
	v_lshl_add_u32 v2, v243, 2, v98
	v_ashrrev_i32_e32 v3, 31, v2
	v_lshl_add_u64 v[2:3], v[2:3], 2, s[52:53]
	global_store_dword v[2:3], v4, off
	s_branch .LBB0_473

.LBB0_904:
	s_or_b64 exec, exec, s[0:1]
	s_ashr_i32 s20, s15, 5
	s_ashr_i32 s15, s14, 31
	v_mov_b32_e32 v43, v0
	s_barrier
	v_mov_b32_e32 v86, 0x200f0
	ds_read_b64 v[250:251], v86
	v_and_b32_e32 v86, 63, v0
	v_lshrrev_b32_e32 v87, 6, v0
	v_lshrrev_b32_e32 v88, 3, v86
	v_lshrrev_b32_e32 v89, 4, v86
	s_nop 0
	v_readfirstlane_b32 s0, v87
	v_add_u32_e32 v66, 0, v89
	v_xor_b32_e32 v66, v66, v86
	v_and_b32_e32 v66, 7, v66
	v_lshlrev_b32_e32 v66, 4, v66
	v_lshl_add_u32 v130, v87, 5, v88
	v_add_u32_e32 v130, 0, v130
	v_mul_u32_u24_e32 v130, 0x800, v130
	v_add_u32_e32 v66, v66, v130
	v_add_u32_e32 v67, 4, v89
	v_xor_b32_e32 v67, v67, v86
	v_and_b32_e32 v67, 7, v67
	v_lshlrev_b32_e32 v67, 4, v67
	v_lshl_add_u32 v130, v87, 5, v88
	v_add_u32_e32 v130, 8, v130
	v_mul_u32_u24_e32 v130, 0x800, v130
	v_add_u32_e32 v67, v67, v130
	v_add_u32_e32 v68, 8, v89
	v_xor_b32_e32 v68, v68, v86
	v_and_b32_e32 v68, 7, v68
	v_lshlrev_b32_e32 v68, 4, v68
	v_lshl_add_u32 v130, v87, 5, v88
	v_add_u32_e32 v130, 16, v130
	v_mul_u32_u24_e32 v130, 0x800, v130
	v_add_u32_e32 v68, v68, v130
	v_add_u32_e32 v69, 12, v89
	v_xor_b32_e32 v69, v69, v86
	v_and_b32_e32 v69, 7, v69
	v_lshlrev_b32_e32 v69, 4, v69
	v_lshl_add_u32 v130, v87, 5, v88
	v_add_u32_e32 v130, 24, v130
	v_mul_u32_u24_e32 v130, 0x800, v130
	v_add_u32_e32 v69, v69, v130
	v_add_u32_e32 v70, 0, v89
	v_xor_b32_e32 v70, v70, v86
	v_and_b32_e32 v70, 7, v70
	v_lshlrev_b32_e32 v70, 4, v70
	v_lshl_add_u32 v130, v87, 4, v88
	v_add_u32_e32 v130, 0, v130
	v_mul_u32_u24_e32 v130, 0x800, v130
	v_add_u32_e32 v70, v70, v130
	v_add_u32_e32 v71, 4, v89
	v_xor_b32_e32 v71, v71, v86
	v_and_b32_e32 v71, 7, v71
	v_lshlrev_b32_e32 v71, 4, v71
	v_lshl_add_u32 v130, v87, 4, v88
	v_add_u32_e32 v130, 8, v130
	v_mul_u32_u24_e32 v130, 0x800, v130
	v_add_u32_e32 v71, v71, v130
	v_and_b32_e32 v88, 15, v86
	v_lshrrev_b32_e32 v130, 1, v88
	v_xor_b32_e32 v130, v130, v89
	v_lshlrev_b32_e32 v130, 4, v130
	v_lshrrev_b32_e32 v86, 1, v87
	v_lshl_add_u32 v86, v86, 6, v88
	v_lshl_add_u32 v86, v86, 7, v130
	v_and_b32_e32 v87, 1, v87
	v_lshl_add_u32 v87, v87, 6, v88
	v_lshl_add_u32 v87, v87, 7, v130
	v_add_u32_e32 v72, 0x100, v86
	v_xor_b32_e32 v75, 64, v72
	v_add_u32_e32 v80, 0x8100, v87
	v_xor_b32_e32 v83, 64, v80
	v_add_u32_e32 v73, 0xc100, v86
	v_xor_b32_e32 v76, 64, v73
	v_add_u32_e32 v81, 0x14100, v87
	v_xor_b32_e32 v84, 64, v81
	v_add_u32_e32 v74, 0x18100, v86
	v_xor_b32_e32 v77, 64, v74
	v_add_u32_e32 v82, 0x20100, v87
	v_xor_b32_e32 v85, 64, v82
	s_lshl_b32 s1, s0, 12
	s_add_u32 s20, s1, 0x100
	s_add_u32 s21, s1, 0xc100
	s_add_u32 s22, s1, 0x18100
	s_lshl_b32 s1, s0, 11
	s_add_u32 s54, s1, 0x8100
	s_add_u32 s55, s1, 0x14100
	s_add_u32 s56, s1, 0x20100
	v_mov_b32_e32 v2, 0
	v_mov_b32_e32 v3, 0
	v_mov_b32_e32 v4, 0
	v_mov_b32_e32 v5, 0
	v_mov_b32_e32 v6, 0
	v_mov_b32_e32 v7, 0
	v_mov_b32_e32 v8, 0
	v_mov_b32_e32 v9, 0
	v_mov_b32_e32 v10, 0
	v_mov_b32_e32 v11, 0
	v_mov_b32_e32 v12, 0
	v_mov_b32_e32 v13, 0
	v_mov_b32_e32 v14, 0
	v_mov_b32_e32 v15, 0
	v_mov_b32_e32 v16, 0
	v_mov_b32_e32 v17, 0
	v_mov_b32_e32 v18, 0
	v_mov_b32_e32 v19, 0
	v_mov_b32_e32 v20, 0
	v_mov_b32_e32 v21, 0
	v_mov_b32_e32 v22, 0
	v_mov_b32_e32 v23, 0
	v_mov_b32_e32 v24, 0
	v_mov_b32_e32 v25, 0
	v_mov_b32_e32 v26, 0
	v_mov_b32_e32 v27, 0
	v_mov_b32_e32 v28, 0
	v_mov_b32_e32 v29, 0
	v_mov_b32_e32 v30, 0
	v_mov_b32_e32 v31, 0
	v_mov_b32_e32 v32, 0
	v_mov_b32_e32 v33, 0
	v_mov_b32_e32 v34, 0
	v_mov_b32_e32 v35, 0
	v_mov_b32_e32 v36, 0
	v_mov_b32_e32 v37, 0
	v_mov_b32_e32 v38, 0
	v_mov_b32_e32 v39, 0
	v_mov_b32_e32 v40, 0
	v_mov_b32_e32 v41, 0
	v_mov_b32_e32 v42, 0
	v_mov_b32_e32 v43, 0
	v_mov_b32_e32 v44, 0
	v_mov_b32_e32 v45, 0
	v_mov_b32_e32 v46, 0
	v_mov_b32_e32 v47, 0
	v_mov_b32_e32 v48, 0
	v_mov_b32_e32 v49, 0
	v_mov_b32_e32 v50, 0
	v_mov_b32_e32 v51, 0
	v_mov_b32_e32 v52, 0
	v_mov_b32_e32 v53, 0
	v_mov_b32_e32 v54, 0
	v_mov_b32_e32 v55, 0
	v_mov_b32_e32 v56, 0
	v_mov_b32_e32 v57, 0
	v_mov_b32_e32 v58, 0
	v_mov_b32_e32 v59, 0
	v_mov_b32_e32 v60, 0
	v_mov_b32_e32 v61, 0
	v_mov_b32_e32 v62, 0
	v_mov_b32_e32 v63, 0
	v_mov_b32_e32 v64, 0
	v_mov_b32_e32 v65, 0
	s_and_b32 s1, s53, 31
	v_readlane_b32 s8, v253, 28
	v_readlane_b32 s9, v253, 29
	s_lshl_b32 s1, s1, 19
	s_nop 0
	s_add_u32 s8, s8, s1
	s_addc_u32 s9, s9, 0
	s_lshr_b32 s1, s53, 5
	v_readlane_b32 s14, v254, 6
	v_readlane_b32 s15, v254, 7
	s_lshl_b32 s1, s1, 18
	s_lshl_b32 s57, s50, 16
	s_add_u32 s1, s1, s57
	s_add_u32 s14, s14, s1
	s_addc_u32 s15, s15, 0
	s_waitcnt lgkmcnt(0)
	s_barrier
	s_mov_b32 m0, s20
	s_nop 0
	global_load_lds_dwordx4 v66, s[8:9]
	s_add_u32 m0, s20, 0x400
	s_nop 0
	global_load_lds_dwordx4 v67, s[8:9]
	s_add_u32 m0, s20, 0x800
	s_nop 0
	global_load_lds_dwordx4 v68, s[8:9]
	s_add_u32 m0, s20, 0xc00
	s_nop 0
	global_load_lds_dwordx4 v69, s[8:9]
	s_mov_b32 m0, s54
	s_nop 0
	global_load_lds_dwordx4 v70, s[14:15]
	s_add_u32 m0, s54, 0x400
	s_nop 0
	global_load_lds_dwordx4 v71, s[14:15]
	s_add_u32 s8, s8, 0x80
	s_addc_u32 s9, s9, 0
	s_add_u32 s14, s14, 0x80
	s_addc_u32 s15, s15, 0
	s_mov_b32 m0, s21
	s_nop 0
	global_load_lds_dwordx4 v66, s[8:9]
	s_add_u32 m0, s21, 0x400
	s_nop 0
	global_load_lds_dwordx4 v67, s[8:9]
	s_add_u32 m0, s21, 0x800
	s_nop 0
	global_load_lds_dwordx4 v68, s[8:9]
	s_add_u32 m0, s21, 0xc00
	s_nop 0
	global_load_lds_dwordx4 v69, s[8:9]
	s_mov_b32 m0, s55
	s_nop 0
	global_load_lds_dwordx4 v70, s[14:15]
	s_add_u32 m0, s55, 0x400
	s_nop 0
	global_load_lds_dwordx4 v71, s[14:15]
	s_add_u32 s8, s8, 0x80
	s_addc_u32 s9, s9, 0
	s_add_u32 s14, s14, 0x80
	s_addc_u32 s15, s15, 0
	s_waitcnt vmcnt(6)
	s_barrier
	ds_read_b128 v[148:151], v72 offset:0
	ds_read_b128 v[152:155], v72 offset:2048
	ds_read_b128 v[156:159], v72 offset:4096
	ds_read_b128 v[160:163], v72 offset:6144
	ds_read_b128 v[164:167], v80 offset:0
	ds_read_b128 v[168:171], v80 offset:2048
	ds_read_b128 v[172:175], v80 offset:4096
	ds_read_b128 v[176:179], v80 offset:6144
	ds_read_b128 v[180:183], v75 offset:0
	ds_read_b128 v[184:187], v75 offset:2048
	ds_read_b128 v[188:191], v75 offset:4096
	ds_read_b128 v[192:195], v75 offset:6144
	ds_read_b128 v[228:231], v83 offset:0
	ds_read_b128 v[232:235], v83 offset:2048
	ds_read_b128 v[236:239], v83 offset:4096
	ds_read_b128 v[240:243], v83 offset:6144
	s_waitcnt lgkmcnt(8)
	v_mfma_f32_16x16x32_bf16 v[2:5], v[164:167], v[148:151], v[2:5]
	s_mov_b32 m0, s22
	v_mfma_f32_16x16x32_bf16 v[6:9], v[168:171], v[148:151], v[6:9]
	global_load_lds_dwordx4 v66, s[8:9]
	v_mfma_f32_16x16x32_bf16 v[10:13], v[172:175], v[148:151], v[10:13]
	s_add_u32 m0, s22, 0x400
	v_mfma_f32_16x16x32_bf16 v[14:17], v[176:179], v[148:151], v[14:17]
	global_load_lds_dwordx4 v67, s[8:9]
	v_mfma_f32_16x16x32_bf16 v[18:21], v[164:167], v[152:155], v[18:21]
	s_add_u32 m0, s22, 0x800
	v_mfma_f32_16x16x32_bf16 v[22:25], v[168:171], v[152:155], v[22:25]
	global_load_lds_dwordx4 v68, s[8:9]
	v_mfma_f32_16x16x32_bf16 v[26:29], v[172:175], v[152:155], v[26:29]
	s_add_u32 m0, s22, 0xc00
	v_mfma_f32_16x16x32_bf16 v[30:33], v[176:179], v[152:155], v[30:33]
	global_load_lds_dwordx4 v69, s[8:9]
	v_mfma_f32_16x16x32_bf16 v[34:37], v[164:167], v[156:159], v[34:37]
	s_mov_b32 m0, s56
	v_mfma_f32_16x16x32_bf16 v[38:41], v[168:171], v[156:159], v[38:41]
	global_load_lds_dwordx4 v70, s[14:15]
	v_mfma_f32_16x16x32_bf16 v[42:45], v[172:175], v[156:159], v[42:45]
	s_add_u32 m0, s56, 0x400
	v_mfma_f32_16x16x32_bf16 v[46:49], v[176:179], v[156:159], v[46:49]
	global_load_lds_dwordx4 v71, s[14:15]
	v_mfma_f32_16x16x32_bf16 v[50:53], v[164:167], v[160:163], v[50:53]
	v_mfma_f32_16x16x32_bf16 v[54:57], v[168:171], v[160:163], v[54:57]
	v_mfma_f32_16x16x32_bf16 v[58:61], v[172:175], v[160:163], v[58:61]
	v_mfma_f32_16x16x32_bf16 v[62:65], v[176:179], v[160:163], v[62:65]
	s_waitcnt lgkmcnt(0)
	v_mfma_f32_16x16x32_bf16 v[2:5], v[228:231], v[180:183], v[2:5]
	v_mfma_f32_16x16x32_bf16 v[6:9], v[232:235], v[180:183], v[6:9]
	v_mfma_f32_16x16x32_bf16 v[10:13], v[236:239], v[180:183], v[10:13]
	v_mfma_f32_16x16x32_bf16 v[14:17], v[240:243], v[180:183], v[14:17]
	v_mfma_f32_16x16x32_bf16 v[18:21], v[228:231], v[184:187], v[18:21]
	v_mfma_f32_16x16x32_bf16 v[22:25], v[232:235], v[184:187], v[22:25]
	v_mfma_f32_16x16x32_bf16 v[26:29], v[236:239], v[184:187], v[26:29]
	v_mfma_f32_16x16x32_bf16 v[30:33], v[240:243], v[184:187], v[30:33]
	v_mfma_f32_16x16x32_bf16 v[34:37], v[228:231], v[188:191], v[34:37]
	v_mfma_f32_16x16x32_bf16 v[38:41], v[232:235], v[188:191], v[38:41]
	v_mfma_f32_16x16x32_bf16 v[42:45], v[236:239], v[188:191], v[42:45]
	v_mfma_f32_16x16x32_bf16 v[46:49], v[240:243], v[188:191], v[46:49]
	v_mfma_f32_16x16x32_bf16 v[50:53], v[228:231], v[192:195], v[50:53]
	v_mfma_f32_16x16x32_bf16 v[54:57], v[232:235], v[192:195], v[54:57]
	v_mfma_f32_16x16x32_bf16 v[58:61], v[236:239], v[192:195], v[58:61]
	v_mfma_f32_16x16x32_bf16 v[62:65], v[240:243], v[192:195], v[62:65]
	s_add_u32 s8, s8, 0x80
	s_addc_u32 s9, s9, 0
	s_add_u32 s14, s14, 0x80
	s_addc_u32 s15, s15, 0
	s_waitcnt vmcnt(6)
	s_barrier
	ds_read_b128 v[148:151], v73 offset:0
	ds_read_b128 v[152:155], v73 offset:2048
	ds_read_b128 v[156:159], v73 offset:4096
	ds_read_b128 v[160:163], v73 offset:6144
	ds_read_b128 v[164:167], v81 offset:0
	ds_read_b128 v[168:171], v81 offset:2048
	ds_read_b128 v[172:175], v81 offset:4096
	ds_read_b128 v[176:179], v81 offset:6144
	ds_read_b128 v[180:183], v76 offset:0
	ds_read_b128 v[184:187], v76 offset:2048
	ds_read_b128 v[188:191], v76 offset:4096
	ds_read_b128 v[192:195], v76 offset:6144
	ds_read_b128 v[228:231], v84 offset:0
	ds_read_b128 v[232:235], v84 offset:2048
	ds_read_b128 v[236:239], v84 offset:4096
	ds_read_b128 v[240:243], v84 offset:6144
	s_waitcnt lgkmcnt(8)
	v_mfma_f32_16x16x32_bf16 v[2:5], v[164:167], v[148:151], v[2:5]
	s_mov_b32 m0, s20
	v_mfma_f32_16x16x32_bf16 v[6:9], v[168:171], v[148:151], v[6:9]
	global_load_lds_dwordx4 v66, s[8:9]
	v_mfma_f32_16x16x32_bf16 v[10:13], v[172:175], v[148:151], v[10:13]
	s_add_u32 m0, s20, 0x400
	v_mfma_f32_16x16x32_bf16 v[14:17], v[176:179], v[148:151], v[14:17]
	global_load_lds_dwordx4 v67, s[8:9]
	v_mfma_f32_16x16x32_bf16 v[18:21], v[164:167], v[152:155], v[18:21]
	s_add_u32 m0, s20, 0x800
	v_mfma_f32_16x16x32_bf16 v[22:25], v[168:171], v[152:155], v[22:25]
	global_load_lds_dwordx4 v68, s[8:9]
	v_mfma_f32_16x16x32_bf16 v[26:29], v[172:175], v[152:155], v[26:29]
	s_add_u32 m0, s20, 0xc00
	v_mfma_f32_16x16x32_bf16 v[30:33], v[176:179], v[152:155], v[30:33]
	global_load_lds_dwordx4 v69, s[8:9]
	v_mfma_f32_16x16x32_bf16 v[34:37], v[164:167], v[156:159], v[34:37]
	s_mov_b32 m0, s54
	v_mfma_f32_16x16x32_bf16 v[38:41], v[168:171], v[156:159], v[38:41]
	global_load_lds_dwordx4 v70, s[14:15]
	v_mfma_f32_16x16x32_bf16 v[42:45], v[172:175], v[156:159], v[42:45]
	s_add_u32 m0, s54, 0x400
	v_mfma_f32_16x16x32_bf16 v[46:49], v[176:179], v[156:159], v[46:49]
	global_load_lds_dwordx4 v71, s[14:15]
	v_mfma_f32_16x16x32_bf16 v[50:53], v[164:167], v[160:163], v[50:53]
	v_mfma_f32_16x16x32_bf16 v[54:57], v[168:171], v[160:163], v[54:57]
	v_mfma_f32_16x16x32_bf16 v[58:61], v[172:175], v[160:163], v[58:61]
	v_mfma_f32_16x16x32_bf16 v[62:65], v[176:179], v[160:163], v[62:65]
	s_waitcnt lgkmcnt(0)
	v_mfma_f32_16x16x32_bf16 v[2:5], v[228:231], v[180:183], v[2:5]
	v_mfma_f32_16x16x32_bf16 v[6:9], v[232:235], v[180:183], v[6:9]
	v_mfma_f32_16x16x32_bf16 v[10:13], v[236:239], v[180:183], v[10:13]
	v_mfma_f32_16x16x32_bf16 v[14:17], v[240:243], v[180:183], v[14:17]
	v_mfma_f32_16x16x32_bf16 v[18:21], v[228:231], v[184:187], v[18:21]
	v_mfma_f32_16x16x32_bf16 v[22:25], v[232:235], v[184:187], v[22:25]
	v_mfma_f32_16x16x32_bf16 v[26:29], v[236:239], v[184:187], v[26:29]
	v_mfma_f32_16x16x32_bf16 v[30:33], v[240:243], v[184:187], v[30:33]
	v_mfma_f32_16x16x32_bf16 v[34:37], v[228:231], v[188:191], v[34:37]
	v_mfma_f32_16x16x32_bf16 v[38:41], v[232:235], v[188:191], v[38:41]
	v_mfma_f32_16x16x32_bf16 v[42:45], v[236:239], v[188:191], v[42:45]
	v_mfma_f32_16x16x32_bf16 v[46:49], v[240:243], v[188:191], v[46:49]
	v_mfma_f32_16x16x32_bf16 v[50:53], v[228:231], v[192:195], v[50:53]
	v_mfma_f32_16x16x32_bf16 v[54:57], v[232:235], v[192:195], v[54:57]
	v_mfma_f32_16x16x32_bf16 v[58:61], v[236:239], v[192:195], v[58:61]
	v_mfma_f32_16x16x32_bf16 v[62:65], v[240:243], v[192:195], v[62:65]
	s_add_u32 s8, s8, 0x80
	s_addc_u32 s9, s9, 0
	s_add_u32 s14, s14, 0x80
	s_addc_u32 s15, s15, 0
	s_waitcnt vmcnt(6)
	s_barrier
	ds_read_b128 v[148:151], v74 offset:0
	ds_read_b128 v[152:155], v74 offset:2048
	ds_read_b128 v[156:159], v74 offset:4096
	ds_read_b128 v[160:163], v74 offset:6144
	ds_read_b128 v[164:167], v82 offset:0
	ds_read_b128 v[168:171], v82 offset:2048
	ds_read_b128 v[172:175], v82 offset:4096
	ds_read_b128 v[176:179], v82 offset:6144
	ds_read_b128 v[180:183], v77 offset:0
	ds_read_b128 v[184:187], v77 offset:2048
	ds_read_b128 v[188:191], v77 offset:4096
	ds_read_b128 v[192:195], v77 offset:6144
	ds_read_b128 v[228:231], v85 offset:0
	ds_read_b128 v[232:235], v85 offset:2048
	ds_read_b128 v[236:239], v85 offset:4096
	ds_read_b128 v[240:243], v85 offset:6144
	s_waitcnt lgkmcnt(8)
	v_mfma_f32_16x16x32_bf16 v[2:5], v[164:167], v[148:151], v[2:5]
	s_mov_b32 m0, s21
	v_mfma_f32_16x16x32_bf16 v[6:9], v[168:171], v[148:151], v[6:9]
	global_load_lds_dwordx4 v66, s[8:9]
	v_mfma_f32_16x16x32_bf16 v[10:13], v[172:175], v[148:151], v[10:13]
	s_add_u32 m0, s21, 0x400
	v_mfma_f32_16x16x32_bf16 v[14:17], v[176:179], v[148:151], v[14:17]
	global_load_lds_dwordx4 v67, s[8:9]
	v_mfma_f32_16x16x32_bf16 v[18:21], v[164:167], v[152:155], v[18:21]
	s_add_u32 m0, s21, 0x800
	v_mfma_f32_16x16x32_bf16 v[22:25], v[168:171], v[152:155], v[22:25]
	global_load_lds_dwordx4 v68, s[8:9]
	v_mfma_f32_16x16x32_bf16 v[26:29], v[172:175], v[152:155], v[26:29]
	s_add_u32 m0, s21, 0xc00
	v_mfma_f32_16x16x32_bf16 v[30:33], v[176:179], v[152:155], v[30:33]
	global_load_lds_dwordx4 v69, s[8:9]
	v_mfma_f32_16x16x32_bf16 v[34:37], v[164:167], v[156:159], v[34:37]
	s_mov_b32 m0, s55
	v_mfma_f32_16x16x32_bf16 v[38:41], v[168:171], v[156:159], v[38:41]
	global_load_lds_dwordx4 v70, s[14:15]
	v_mfma_f32_16x16x32_bf16 v[42:45], v[172:175], v[156:159], v[42:45]
	s_add_u32 m0, s55, 0x400
	v_mfma_f32_16x16x32_bf16 v[46:49], v[176:179], v[156:159], v[46:49]
	global_load_lds_dwordx4 v71, s[14:15]
	v_mfma_f32_16x16x32_bf16 v[50:53], v[164:167], v[160:163], v[50:53]
	v_mfma_f32_16x16x32_bf16 v[54:57], v[168:171], v[160:163], v[54:57]
	v_mfma_f32_16x16x32_bf16 v[58:61], v[172:175], v[160:163], v[58:61]
	v_mfma_f32_16x16x32_bf16 v[62:65], v[176:179], v[160:163], v[62:65]
	s_waitcnt lgkmcnt(0)
	v_mfma_f32_16x16x32_bf16 v[2:5], v[228:231], v[180:183], v[2:5]
	v_mfma_f32_16x16x32_bf16 v[6:9], v[232:235], v[180:183], v[6:9]
	v_mfma_f32_16x16x32_bf16 v[10:13], v[236:239], v[180:183], v[10:13]
	v_mfma_f32_16x16x32_bf16 v[14:17], v[240:243], v[180:183], v[14:17]
	v_mfma_f32_16x16x32_bf16 v[18:21], v[228:231], v[184:187], v[18:21]
	v_mfma_f32_16x16x32_bf16 v[22:25], v[232:235], v[184:187], v[22:25]
	v_mfma_f32_16x16x32_bf16 v[26:29], v[236:239], v[184:187], v[26:29]
	v_mfma_f32_16x16x32_bf16 v[30:33], v[240:243], v[184:187], v[30:33]
	v_mfma_f32_16x16x32_bf16 v[34:37], v[228:231], v[188:191], v[34:37]
	v_mfma_f32_16x16x32_bf16 v[38:41], v[232:235], v[188:191], v[38:41]
	v_mfma_f32_16x16x32_bf16 v[42:45], v[236:239], v[188:191], v[42:45]
	v_mfma_f32_16x16x32_bf16 v[46:49], v[240:243], v[188:191], v[46:49]
	v_mfma_f32_16x16x32_bf16 v[50:53], v[228:231], v[192:195], v[50:53]
	v_mfma_f32_16x16x32_bf16 v[54:57], v[232:235], v[192:195], v[54:57]
	v_mfma_f32_16x16x32_bf16 v[58:61], v[236:239], v[192:195], v[58:61]
	v_mfma_f32_16x16x32_bf16 v[62:65], v[240:243], v[192:195], v[62:65]
	s_add_u32 s8, s8, 0x80
	s_addc_u32 s9, s9, 0
	s_add_u32 s14, s14, 0x80
	s_addc_u32 s15, s15, 0
	s_waitcnt vmcnt(6)
	s_barrier
	ds_read_b128 v[148:151], v72 offset:0
	ds_read_b128 v[152:155], v72 offset:2048
	ds_read_b128 v[156:159], v72 offset:4096
	ds_read_b128 v[160:163], v72 offset:6144
	ds_read_b128 v[164:167], v80 offset:0
	ds_read_b128 v[168:171], v80 offset:2048
	ds_read_b128 v[172:175], v80 offset:4096
	ds_read_b128 v[176:179], v80 offset:6144
	ds_read_b128 v[180:183], v75 offset:0
	ds_read_b128 v[184:187], v75 offset:2048
	ds_read_b128 v[188:191], v75 offset:4096
	ds_read_b128 v[192:195], v75 offset:6144
	ds_read_b128 v[228:231], v83 offset:0
	ds_read_b128 v[232:235], v83 offset:2048
	ds_read_b128 v[236:239], v83 offset:4096
	ds_read_b128 v[240:243], v83 offset:6144
	s_waitcnt lgkmcnt(8)
	v_mfma_f32_16x16x32_bf16 v[2:5], v[164:167], v[148:151], v[2:5]
	s_mov_b32 m0, s22
	v_mfma_f32_16x16x32_bf16 v[6:9], v[168:171], v[148:151], v[6:9]
	global_load_lds_dwordx4 v66, s[8:9]
	v_mfma_f32_16x16x32_bf16 v[10:13], v[172:175], v[148:151], v[10:13]
	s_add_u32 m0, s22, 0x400
	v_mfma_f32_16x16x32_bf16 v[14:17], v[176:179], v[148:151], v[14:17]
	global_load_lds_dwordx4 v67, s[8:9]
	v_mfma_f32_16x16x32_bf16 v[18:21], v[164:167], v[152:155], v[18:21]
	s_add_u32 m0, s22, 0x800
	v_mfma_f32_16x16x32_bf16 v[22:25], v[168:171], v[152:155], v[22:25]
	global_load_lds_dwordx4 v68, s[8:9]
	v_mfma_f32_16x16x32_bf16 v[26:29], v[172:175], v[152:155], v[26:29]
	s_add_u32 m0, s22, 0xc00
	v_mfma_f32_16x16x32_bf16 v[30:33], v[176:179], v[152:155], v[30:33]
	global_load_lds_dwordx4 v69, s[8:9]
	v_mfma_f32_16x16x32_bf16 v[34:37], v[164:167], v[156:159], v[34:37]
	s_mov_b32 m0, s56
	v_mfma_f32_16x16x32_bf16 v[38:41], v[168:171], v[156:159], v[38:41]
	global_load_lds_dwordx4 v70, s[14:15]
	v_mfma_f32_16x16x32_bf16 v[42:45], v[172:175], v[156:159], v[42:45]
	s_add_u32 m0, s56, 0x400
	v_mfma_f32_16x16x32_bf16 v[46:49], v[176:179], v[156:159], v[46:49]
	global_load_lds_dwordx4 v71, s[14:15]
	v_mfma_f32_16x16x32_bf16 v[50:53], v[164:167], v[160:163], v[50:53]
	v_mfma_f32_16x16x32_bf16 v[54:57], v[168:171], v[160:163], v[54:57]
	v_mfma_f32_16x16x32_bf16 v[58:61], v[172:175], v[160:163], v[58:61]
	v_mfma_f32_16x16x32_bf16 v[62:65], v[176:179], v[160:163], v[62:65]
	s_waitcnt lgkmcnt(0)
	v_mfma_f32_16x16x32_bf16 v[2:5], v[228:231], v[180:183], v[2:5]
	v_mfma_f32_16x16x32_bf16 v[6:9], v[232:235], v[180:183], v[6:9]
	v_mfma_f32_16x16x32_bf16 v[10:13], v[236:239], v[180:183], v[10:13]
	v_mfma_f32_16x16x32_bf16 v[14:17], v[240:243], v[180:183], v[14:17]
	v_mfma_f32_16x16x32_bf16 v[18:21], v[228:231], v[184:187], v[18:21]
	v_mfma_f32_16x16x32_bf16 v[22:25], v[232:235], v[184:187], v[22:25]
	v_mfma_f32_16x16x32_bf16 v[26:29], v[236:239], v[184:187], v[26:29]
	v_mfma_f32_16x16x32_bf16 v[30:33], v[240:243], v[184:187], v[30:33]
	v_mfma_f32_16x16x32_bf16 v[34:37], v[228:231], v[188:191], v[34:37]
	v_mfma_f32_16x16x32_bf16 v[38:41], v[232:235], v[188:191], v[38:41]
	v_mfma_f32_16x16x32_bf16 v[42:45], v[236:239], v[188:191], v[42:45]
	v_mfma_f32_16x16x32_bf16 v[46:49], v[240:243], v[188:191], v[46:49]
	v_mfma_f32_16x16x32_bf16 v[50:53], v[228:231], v[192:195], v[50:53]
	v_mfma_f32_16x16x32_bf16 v[54:57], v[232:235], v[192:195], v[54:57]
	v_mfma_f32_16x16x32_bf16 v[58:61], v[236:239], v[192:195], v[58:61]
	v_mfma_f32_16x16x32_bf16 v[62:65], v[240:243], v[192:195], v[62:65]
	s_add_u32 s8, s8, 0x80
	s_addc_u32 s9, s9, 0
	s_add_u32 s14, s14, 0x80
	s_addc_u32 s15, s15, 0
	s_waitcnt vmcnt(6)
	s_barrier
	ds_read_b128 v[148:151], v73 offset:0
	ds_read_b128 v[152:155], v73 offset:2048
	ds_read_b128 v[156:159], v73 offset:4096
	ds_read_b128 v[160:163], v73 offset:6144
	ds_read_b128 v[164:167], v81 offset:0
	ds_read_b128 v[168:171], v81 offset:2048
	ds_read_b128 v[172:175], v81 offset:4096
	ds_read_b128 v[176:179], v81 offset:6144
	ds_read_b128 v[180:183], v76 offset:0
	ds_read_b128 v[184:187], v76 offset:2048
	ds_read_b128 v[188:191], v76 offset:4096
	ds_read_b128 v[192:195], v76 offset:6144
	ds_read_b128 v[228:231], v84 offset:0
	ds_read_b128 v[232:235], v84 offset:2048
	ds_read_b128 v[236:239], v84 offset:4096
	ds_read_b128 v[240:243], v84 offset:6144
	s_waitcnt lgkmcnt(8)
	v_mfma_f32_16x16x32_bf16 v[2:5], v[164:167], v[148:151], v[2:5]
	s_mov_b32 m0, s20
	v_mfma_f32_16x16x32_bf16 v[6:9], v[168:171], v[148:151], v[6:9]
	global_load_lds_dwordx4 v66, s[8:9]
	v_mfma_f32_16x16x32_bf16 v[10:13], v[172:175], v[148:151], v[10:13]
	s_add_u32 m0, s20, 0x400
	v_mfma_f32_16x16x32_bf16 v[14:17], v[176:179], v[148:151], v[14:17]
	global_load_lds_dwordx4 v67, s[8:9]
	v_mfma_f32_16x16x32_bf16 v[18:21], v[164:167], v[152:155], v[18:21]
	s_add_u32 m0, s20, 0x800
	v_mfma_f32_16x16x32_bf16 v[22:25], v[168:171], v[152:155], v[22:25]
	global_load_lds_dwordx4 v68, s[8:9]
	v_mfma_f32_16x16x32_bf16 v[26:29], v[172:175], v[152:155], v[26:29]
	s_add_u32 m0, s20, 0xc00
	v_mfma_f32_16x16x32_bf16 v[30:33], v[176:179], v[152:155], v[30:33]
	global_load_lds_dwordx4 v69, s[8:9]
	v_mfma_f32_16x16x32_bf16 v[34:37], v[164:167], v[156:159], v[34:37]
	s_mov_b32 m0, s54
	v_mfma_f32_16x16x32_bf16 v[38:41], v[168:171], v[156:159], v[38:41]
	global_load_lds_dwordx4 v70, s[14:15]
	v_mfma_f32_16x16x32_bf16 v[42:45], v[172:175], v[156:159], v[42:45]
	s_add_u32 m0, s54, 0x400
	v_mfma_f32_16x16x32_bf16 v[46:49], v[176:179], v[156:159], v[46:49]
	global_load_lds_dwordx4 v71, s[14:15]
	v_mfma_f32_16x16x32_bf16 v[50:53], v[164:167], v[160:163], v[50:53]
	v_mfma_f32_16x16x32_bf16 v[54:57], v[168:171], v[160:163], v[54:57]
	v_mfma_f32_16x16x32_bf16 v[58:61], v[172:175], v[160:163], v[58:61]
	v_mfma_f32_16x16x32_bf16 v[62:65], v[176:179], v[160:163], v[62:65]
	s_waitcnt lgkmcnt(0)
	v_mfma_f32_16x16x32_bf16 v[2:5], v[228:231], v[180:183], v[2:5]
	v_mfma_f32_16x16x32_bf16 v[6:9], v[232:235], v[180:183], v[6:9]
	v_mfma_f32_16x16x32_bf16 v[10:13], v[236:239], v[180:183], v[10:13]
	v_mfma_f32_16x16x32_bf16 v[14:17], v[240:243], v[180:183], v[14:17]
	v_mfma_f32_16x16x32_bf16 v[18:21], v[228:231], v[184:187], v[18:21]
	v_mfma_f32_16x16x32_bf16 v[22:25], v[232:235], v[184:187], v[22:25]
	v_mfma_f32_16x16x32_bf16 v[26:29], v[236:239], v[184:187], v[26:29]
	v_mfma_f32_16x16x32_bf16 v[30:33], v[240:243], v[184:187], v[30:33]
	v_mfma_f32_16x16x32_bf16 v[34:37], v[228:231], v[188:191], v[34:37]
	v_mfma_f32_16x16x32_bf16 v[38:41], v[232:235], v[188:191], v[38:41]
	v_mfma_f32_16x16x32_bf16 v[42:45], v[236:239], v[188:191], v[42:45]
	v_mfma_f32_16x16x32_bf16 v[46:49], v[240:243], v[188:191], v[46:49]
	v_mfma_f32_16x16x32_bf16 v[50:53], v[228:231], v[192:195], v[50:53]
	v_mfma_f32_16x16x32_bf16 v[54:57], v[232:235], v[192:195], v[54:57]
	v_mfma_f32_16x16x32_bf16 v[58:61], v[236:239], v[192:195], v[58:61]
	v_mfma_f32_16x16x32_bf16 v[62:65], v[240:243], v[192:195], v[62:65]
	s_add_u32 s8, s8, 0x80
	s_addc_u32 s9, s9, 0
	s_add_u32 s14, s14, 0x80
	s_addc_u32 s15, s15, 0
	s_waitcnt vmcnt(6)
	s_barrier
	ds_read_b128 v[148:151], v74 offset:0
	ds_read_b128 v[152:155], v74 offset:2048
	ds_read_b128 v[156:159], v74 offset:4096
	ds_read_b128 v[160:163], v74 offset:6144
	ds_read_b128 v[164:167], v82 offset:0
	ds_read_b128 v[168:171], v82 offset:2048
	ds_read_b128 v[172:175], v82 offset:4096
	ds_read_b128 v[176:179], v82 offset:6144
	ds_read_b128 v[180:183], v77 offset:0
	ds_read_b128 v[184:187], v77 offset:2048
	ds_read_b128 v[188:191], v77 offset:4096
	ds_read_b128 v[192:195], v77 offset:6144
	ds_read_b128 v[228:231], v85 offset:0
	ds_read_b128 v[232:235], v85 offset:2048
	ds_read_b128 v[236:239], v85 offset:4096
	ds_read_b128 v[240:243], v85 offset:6144
	s_waitcnt lgkmcnt(8)
	v_mfma_f32_16x16x32_bf16 v[2:5], v[164:167], v[148:151], v[2:5]
	s_mov_b32 m0, s21
	v_mfma_f32_16x16x32_bf16 v[6:9], v[168:171], v[148:151], v[6:9]
	global_load_lds_dwordx4 v66, s[8:9]
	v_mfma_f32_16x16x32_bf16 v[10:13], v[172:175], v[148:151], v[10:13]
	s_add_u32 m0, s21, 0x400
	v_mfma_f32_16x16x32_bf16 v[14:17], v[176:179], v[148:151], v[14:17]
	global_load_lds_dwordx4 v67, s[8:9]
	v_mfma_f32_16x16x32_bf16 v[18:21], v[164:167], v[152:155], v[18:21]
	s_add_u32 m0, s21, 0x800
	v_mfma_f32_16x16x32_bf16 v[22:25], v[168:171], v[152:155], v[22:25]
	global_load_lds_dwordx4 v68, s[8:9]
	v_mfma_f32_16x16x32_bf16 v[26:29], v[172:175], v[152:155], v[26:29]
	s_add_u32 m0, s21, 0xc00
	v_mfma_f32_16x16x32_bf16 v[30:33], v[176:179], v[152:155], v[30:33]
	global_load_lds_dwordx4 v69, s[8:9]
	v_mfma_f32_16x16x32_bf16 v[34:37], v[164:167], v[156:159], v[34:37]
	s_mov_b32 m0, s55
	v_mfma_f32_16x16x32_bf16 v[38:41], v[168:171], v[156:159], v[38:41]
	global_load_lds_dwordx4 v70, s[14:15]
	v_mfma_f32_16x16x32_bf16 v[42:45], v[172:175], v[156:159], v[42:45]
	s_add_u32 m0, s55, 0x400
	v_mfma_f32_16x16x32_bf16 v[46:49], v[176:179], v[156:159], v[46:49]
	global_load_lds_dwordx4 v71, s[14:15]
	v_mfma_f32_16x16x32_bf16 v[50:53], v[164:167], v[160:163], v[50:53]
	v_mfma_f32_16x16x32_bf16 v[54:57], v[168:171], v[160:163], v[54:57]
	v_mfma_f32_16x16x32_bf16 v[58:61], v[172:175], v[160:163], v[58:61]
	v_mfma_f32_16x16x32_bf16 v[62:65], v[176:179], v[160:163], v[62:65]
	s_waitcnt lgkmcnt(0)
	v_mfma_f32_16x16x32_bf16 v[2:5], v[228:231], v[180:183], v[2:5]
	v_mfma_f32_16x16x32_bf16 v[6:9], v[232:235], v[180:183], v[6:9]
	v_mfma_f32_16x16x32_bf16 v[10:13], v[236:239], v[180:183], v[10:13]
	v_mfma_f32_16x16x32_bf16 v[14:17], v[240:243], v[180:183], v[14:17]
	v_mfma_f32_16x16x32_bf16 v[18:21], v[228:231], v[184:187], v[18:21]
	v_mfma_f32_16x16x32_bf16 v[22:25], v[232:235], v[184:187], v[22:25]
	v_mfma_f32_16x16x32_bf16 v[26:29], v[236:239], v[184:187], v[26:29]
	v_mfma_f32_16x16x32_bf16 v[30:33], v[240:243], v[184:187], v[30:33]
	v_mfma_f32_16x16x32_bf16 v[34:37], v[228:231], v[188:191], v[34:37]
	v_mfma_f32_16x16x32_bf16 v[38:41], v[232:235], v[188:191], v[38:41]
	v_mfma_f32_16x16x32_bf16 v[42:45], v[236:239], v[188:191], v[42:45]
	v_mfma_f32_16x16x32_bf16 v[46:49], v[240:243], v[188:191], v[46:49]
	v_mfma_f32_16x16x32_bf16 v[50:53], v[228:231], v[192:195], v[50:53]
	v_mfma_f32_16x16x32_bf16 v[54:57], v[232:235], v[192:195], v[54:57]
	v_mfma_f32_16x16x32_bf16 v[58:61], v[236:239], v[192:195], v[58:61]
	v_mfma_f32_16x16x32_bf16 v[62:65], v[240:243], v[192:195], v[62:65]
	s_add_u32 s8, s8, 0x80
	s_addc_u32 s9, s9, 0
	s_add_u32 s14, s14, 0x80
	s_addc_u32 s15, s15, 0
	s_waitcnt vmcnt(6)
	s_barrier
	ds_read_b128 v[148:151], v72 offset:0
	ds_read_b128 v[152:155], v72 offset:2048
	ds_read_b128 v[156:159], v72 offset:4096
	ds_read_b128 v[160:163], v72 offset:6144
	ds_read_b128 v[164:167], v80 offset:0
	ds_read_b128 v[168:171], v80 offset:2048
	ds_read_b128 v[172:175], v80 offset:4096
	ds_read_b128 v[176:179], v80 offset:6144
	ds_read_b128 v[180:183], v75 offset:0
	ds_read_b128 v[184:187], v75 offset:2048
	ds_read_b128 v[188:191], v75 offset:4096
	ds_read_b128 v[192:195], v75 offset:6144
	ds_read_b128 v[228:231], v83 offset:0
	ds_read_b128 v[232:235], v83 offset:2048
	ds_read_b128 v[236:239], v83 offset:4096
	ds_read_b128 v[240:243], v83 offset:6144
	s_waitcnt lgkmcnt(8)
	v_mfma_f32_16x16x32_bf16 v[2:5], v[164:167], v[148:151], v[2:5]
	s_mov_b32 m0, s22
	v_mfma_f32_16x16x32_bf16 v[6:9], v[168:171], v[148:151], v[6:9]
	global_load_lds_dwordx4 v66, s[8:9]
	v_mfma_f32_16x16x32_bf16 v[10:13], v[172:175], v[148:151], v[10:13]
	s_add_u32 m0, s22, 0x400
	v_mfma_f32_16x16x32_bf16 v[14:17], v[176:179], v[148:151], v[14:17]
	global_load_lds_dwordx4 v67, s[8:9]
	v_mfma_f32_16x16x32_bf16 v[18:21], v[164:167], v[152:155], v[18:21]
	s_add_u32 m0, s22, 0x800
	v_mfma_f32_16x16x32_bf16 v[22:25], v[168:171], v[152:155], v[22:25]
	global_load_lds_dwordx4 v68, s[8:9]
	v_mfma_f32_16x16x32_bf16 v[26:29], v[172:175], v[152:155], v[26:29]
	s_add_u32 m0, s22, 0xc00
	v_mfma_f32_16x16x32_bf16 v[30:33], v[176:179], v[152:155], v[30:33]
	global_load_lds_dwordx4 v69, s[8:9]
	v_mfma_f32_16x16x32_bf16 v[34:37], v[164:167], v[156:159], v[34:37]
	s_mov_b32 m0, s56
	v_mfma_f32_16x16x32_bf16 v[38:41], v[168:171], v[156:159], v[38:41]
	global_load_lds_dwordx4 v70, s[14:15]
	v_mfma_f32_16x16x32_bf16 v[42:45], v[172:175], v[156:159], v[42:45]
	s_add_u32 m0, s56, 0x400
	v_mfma_f32_16x16x32_bf16 v[46:49], v[176:179], v[156:159], v[46:49]
	global_load_lds_dwordx4 v71, s[14:15]
	v_mfma_f32_16x16x32_bf16 v[50:53], v[164:167], v[160:163], v[50:53]
	v_mfma_f32_16x16x32_bf16 v[54:57], v[168:171], v[160:163], v[54:57]
	v_mfma_f32_16x16x32_bf16 v[58:61], v[172:175], v[160:163], v[58:61]
	v_mfma_f32_16x16x32_bf16 v[62:65], v[176:179], v[160:163], v[62:65]
	s_waitcnt lgkmcnt(0)
	v_mfma_f32_16x16x32_bf16 v[2:5], v[228:231], v[180:183], v[2:5]
	v_mfma_f32_16x16x32_bf16 v[6:9], v[232:235], v[180:183], v[6:9]
	v_mfma_f32_16x16x32_bf16 v[10:13], v[236:239], v[180:183], v[10:13]
	v_mfma_f32_16x16x32_bf16 v[14:17], v[240:243], v[180:183], v[14:17]
	v_mfma_f32_16x16x32_bf16 v[18:21], v[228:231], v[184:187], v[18:21]
	v_mfma_f32_16x16x32_bf16 v[22:25], v[232:235], v[184:187], v[22:25]
	v_mfma_f32_16x16x32_bf16 v[26:29], v[236:239], v[184:187], v[26:29]
	v_mfma_f32_16x16x32_bf16 v[30:33], v[240:243], v[184:187], v[30:33]
	v_mfma_f32_16x16x32_bf16 v[34:37], v[228:231], v[188:191], v[34:37]
	v_mfma_f32_16x16x32_bf16 v[38:41], v[232:235], v[188:191], v[38:41]
	v_mfma_f32_16x16x32_bf16 v[42:45], v[236:239], v[188:191], v[42:45]
	v_mfma_f32_16x16x32_bf16 v[46:49], v[240:243], v[188:191], v[46:49]
	v_mfma_f32_16x16x32_bf16 v[50:53], v[228:231], v[192:195], v[50:53]
	v_mfma_f32_16x16x32_bf16 v[54:57], v[232:235], v[192:195], v[54:57]
	v_mfma_f32_16x16x32_bf16 v[58:61], v[236:239], v[192:195], v[58:61]
	v_mfma_f32_16x16x32_bf16 v[62:65], v[240:243], v[192:195], v[62:65]
	s_add_u32 s8, s8, 0x80
	s_addc_u32 s9, s9, 0
	s_add_u32 s14, s14, 0x80
	s_addc_u32 s15, s15, 0
	s_waitcnt vmcnt(6)
	s_barrier
	ds_read_b128 v[148:151], v73 offset:0
	ds_read_b128 v[152:155], v73 offset:2048
	ds_read_b128 v[156:159], v73 offset:4096
	ds_read_b128 v[160:163], v73 offset:6144
	ds_read_b128 v[164:167], v81 offset:0
	ds_read_b128 v[168:171], v81 offset:2048
	ds_read_b128 v[172:175], v81 offset:4096
	ds_read_b128 v[176:179], v81 offset:6144
	ds_read_b128 v[180:183], v76 offset:0
	ds_read_b128 v[184:187], v76 offset:2048
	ds_read_b128 v[188:191], v76 offset:4096
	ds_read_b128 v[192:195], v76 offset:6144
	ds_read_b128 v[228:231], v84 offset:0
	ds_read_b128 v[232:235], v84 offset:2048
	ds_read_b128 v[236:239], v84 offset:4096
	ds_read_b128 v[240:243], v84 offset:6144
	s_waitcnt lgkmcnt(8)
	v_mfma_f32_16x16x32_bf16 v[2:5], v[164:167], v[148:151], v[2:5]
	s_mov_b32 m0, s20
	v_mfma_f32_16x16x32_bf16 v[6:9], v[168:171], v[148:151], v[6:9]
	global_load_lds_dwordx4 v66, s[8:9]
	v_mfma_f32_16x16x32_bf16 v[10:13], v[172:175], v[148:151], v[10:13]
	s_add_u32 m0, s20, 0x400
	v_mfma_f32_16x16x32_bf16 v[14:17], v[176:179], v[148:151], v[14:17]
	global_load_lds_dwordx4 v67, s[8:9]
	v_mfma_f32_16x16x32_bf16 v[18:21], v[164:167], v[152:155], v[18:21]
	s_add_u32 m0, s20, 0x800
	v_mfma_f32_16x16x32_bf16 v[22:25], v[168:171], v[152:155], v[22:25]
	global_load_lds_dwordx4 v68, s[8:9]
	v_mfma_f32_16x16x32_bf16 v[26:29], v[172:175], v[152:155], v[26:29]
	s_add_u32 m0, s20, 0xc00
	v_mfma_f32_16x16x32_bf16 v[30:33], v[176:179], v[152:155], v[30:33]
	global_load_lds_dwordx4 v69, s[8:9]
	v_mfma_f32_16x16x32_bf16 v[34:37], v[164:167], v[156:159], v[34:37]
	s_mov_b32 m0, s54
	v_mfma_f32_16x16x32_bf16 v[38:41], v[168:171], v[156:159], v[38:41]
	global_load_lds_dwordx4 v70, s[14:15]
	v_mfma_f32_16x16x32_bf16 v[42:45], v[172:175], v[156:159], v[42:45]
	s_add_u32 m0, s54, 0x400
	v_mfma_f32_16x16x32_bf16 v[46:49], v[176:179], v[156:159], v[46:49]
	global_load_lds_dwordx4 v71, s[14:15]
	v_mfma_f32_16x16x32_bf16 v[50:53], v[164:167], v[160:163], v[50:53]
	v_mfma_f32_16x16x32_bf16 v[54:57], v[168:171], v[160:163], v[54:57]
	v_mfma_f32_16x16x32_bf16 v[58:61], v[172:175], v[160:163], v[58:61]
	v_mfma_f32_16x16x32_bf16 v[62:65], v[176:179], v[160:163], v[62:65]
	s_waitcnt lgkmcnt(0)
	v_mfma_f32_16x16x32_bf16 v[2:5], v[228:231], v[180:183], v[2:5]
	v_mfma_f32_16x16x32_bf16 v[6:9], v[232:235], v[180:183], v[6:9]
	v_mfma_f32_16x16x32_bf16 v[10:13], v[236:239], v[180:183], v[10:13]
	v_mfma_f32_16x16x32_bf16 v[14:17], v[240:243], v[180:183], v[14:17]
	v_mfma_f32_16x16x32_bf16 v[18:21], v[228:231], v[184:187], v[18:21]
	v_mfma_f32_16x16x32_bf16 v[22:25], v[232:235], v[184:187], v[22:25]
	v_mfma_f32_16x16x32_bf16 v[26:29], v[236:239], v[184:187], v[26:29]
	v_mfma_f32_16x16x32_bf16 v[30:33], v[240:243], v[184:187], v[30:33]
	v_mfma_f32_16x16x32_bf16 v[34:37], v[228:231], v[188:191], v[34:37]
	v_mfma_f32_16x16x32_bf16 v[38:41], v[232:235], v[188:191], v[38:41]
	v_mfma_f32_16x16x32_bf16 v[42:45], v[236:239], v[188:191], v[42:45]
	v_mfma_f32_16x16x32_bf16 v[46:49], v[240:243], v[188:191], v[46:49]
	v_mfma_f32_16x16x32_bf16 v[50:53], v[228:231], v[192:195], v[50:53]
	v_mfma_f32_16x16x32_bf16 v[54:57], v[232:235], v[192:195], v[54:57]
	v_mfma_f32_16x16x32_bf16 v[58:61], v[236:239], v[192:195], v[58:61]
	v_mfma_f32_16x16x32_bf16 v[62:65], v[240:243], v[192:195], v[62:65]
	s_add_u32 s8, s8, 0x80
	s_addc_u32 s9, s9, 0
	s_add_u32 s14, s14, 0x80
	s_addc_u32 s15, s15, 0
	s_waitcnt vmcnt(6)
	s_barrier
	ds_read_b128 v[148:151], v74 offset:0
	ds_read_b128 v[152:155], v74 offset:2048
	ds_read_b128 v[156:159], v74 offset:4096
	ds_read_b128 v[160:163], v74 offset:6144
	ds_read_b128 v[164:167], v82 offset:0
	ds_read_b128 v[168:171], v82 offset:2048
	ds_read_b128 v[172:175], v82 offset:4096
	ds_read_b128 v[176:179], v82 offset:6144
	ds_read_b128 v[180:183], v77 offset:0
	ds_read_b128 v[184:187], v77 offset:2048
	ds_read_b128 v[188:191], v77 offset:4096
	ds_read_b128 v[192:195], v77 offset:6144
	ds_read_b128 v[228:231], v85 offset:0
	ds_read_b128 v[232:235], v85 offset:2048
	ds_read_b128 v[236:239], v85 offset:4096
	ds_read_b128 v[240:243], v85 offset:6144
	s_waitcnt lgkmcnt(8)
	v_mfma_f32_16x16x32_bf16 v[2:5], v[164:167], v[148:151], v[2:5]
	s_mov_b32 m0, s21
	v_mfma_f32_16x16x32_bf16 v[6:9], v[168:171], v[148:151], v[6:9]
	global_load_lds_dwordx4 v66, s[8:9]
	v_mfma_f32_16x16x32_bf16 v[10:13], v[172:175], v[148:151], v[10:13]
	s_add_u32 m0, s21, 0x400
	v_mfma_f32_16x16x32_bf16 v[14:17], v[176:179], v[148:151], v[14:17]
	global_load_lds_dwordx4 v67, s[8:9]
	v_mfma_f32_16x16x32_bf16 v[18:21], v[164:167], v[152:155], v[18:21]
	s_add_u32 m0, s21, 0x800
	v_mfma_f32_16x16x32_bf16 v[22:25], v[168:171], v[152:155], v[22:25]
	global_load_lds_dwordx4 v68, s[8:9]
	v_mfma_f32_16x16x32_bf16 v[26:29], v[172:175], v[152:155], v[26:29]
	s_add_u32 m0, s21, 0xc00
	v_mfma_f32_16x16x32_bf16 v[30:33], v[176:179], v[152:155], v[30:33]
	global_load_lds_dwordx4 v69, s[8:9]
	v_mfma_f32_16x16x32_bf16 v[34:37], v[164:167], v[156:159], v[34:37]
	s_mov_b32 m0, s55
	v_mfma_f32_16x16x32_bf16 v[38:41], v[168:171], v[156:159], v[38:41]
	global_load_lds_dwordx4 v70, s[14:15]
	v_mfma_f32_16x16x32_bf16 v[42:45], v[172:175], v[156:159], v[42:45]
	s_add_u32 m0, s55, 0x400
	v_mfma_f32_16x16x32_bf16 v[46:49], v[176:179], v[156:159], v[46:49]
	global_load_lds_dwordx4 v71, s[14:15]
	v_mfma_f32_16x16x32_bf16 v[50:53], v[164:167], v[160:163], v[50:53]
	v_mfma_f32_16x16x32_bf16 v[54:57], v[168:171], v[160:163], v[54:57]
	v_mfma_f32_16x16x32_bf16 v[58:61], v[172:175], v[160:163], v[58:61]
	v_mfma_f32_16x16x32_bf16 v[62:65], v[176:179], v[160:163], v[62:65]
	s_waitcnt lgkmcnt(0)
	v_mfma_f32_16x16x32_bf16 v[2:5], v[228:231], v[180:183], v[2:5]
	v_mfma_f32_16x16x32_bf16 v[6:9], v[232:235], v[180:183], v[6:9]
	v_mfma_f32_16x16x32_bf16 v[10:13], v[236:239], v[180:183], v[10:13]
	v_mfma_f32_16x16x32_bf16 v[14:17], v[240:243], v[180:183], v[14:17]
	v_mfma_f32_16x16x32_bf16 v[18:21], v[228:231], v[184:187], v[18:21]
	v_mfma_f32_16x16x32_bf16 v[22:25], v[232:235], v[184:187], v[22:25]
	v_mfma_f32_16x16x32_bf16 v[26:29], v[236:239], v[184:187], v[26:29]
	v_mfma_f32_16x16x32_bf16 v[30:33], v[240:243], v[184:187], v[30:33]
	v_mfma_f32_16x16x32_bf16 v[34:37], v[228:231], v[188:191], v[34:37]
	v_mfma_f32_16x16x32_bf16 v[38:41], v[232:235], v[188:191], v[38:41]
	v_mfma_f32_16x16x32_bf16 v[42:45], v[236:239], v[188:191], v[42:45]
	v_mfma_f32_16x16x32_bf16 v[46:49], v[240:243], v[188:191], v[46:49]
	v_mfma_f32_16x16x32_bf16 v[50:53], v[228:231], v[192:195], v[50:53]
	v_mfma_f32_16x16x32_bf16 v[54:57], v[232:235], v[192:195], v[54:57]
	v_mfma_f32_16x16x32_bf16 v[58:61], v[236:239], v[192:195], v[58:61]
	v_mfma_f32_16x16x32_bf16 v[62:65], v[240:243], v[192:195], v[62:65]
	s_add_u32 s8, s8, 0x80
	s_addc_u32 s9, s9, 0
	s_add_u32 s14, s14, 0x80
	s_addc_u32 s15, s15, 0
	s_waitcnt vmcnt(6)
	s_barrier
	ds_read_b128 v[148:151], v72 offset:0
	ds_read_b128 v[152:155], v72 offset:2048
	ds_read_b128 v[156:159], v72 offset:4096
	ds_read_b128 v[160:163], v72 offset:6144
	ds_read_b128 v[164:167], v80 offset:0
	ds_read_b128 v[168:171], v80 offset:2048
	ds_read_b128 v[172:175], v80 offset:4096
	ds_read_b128 v[176:179], v80 offset:6144
	ds_read_b128 v[180:183], v75 offset:0
	ds_read_b128 v[184:187], v75 offset:2048
	ds_read_b128 v[188:191], v75 offset:4096
	ds_read_b128 v[192:195], v75 offset:6144
	ds_read_b128 v[228:231], v83 offset:0
	ds_read_b128 v[232:235], v83 offset:2048
	ds_read_b128 v[236:239], v83 offset:4096
	ds_read_b128 v[240:243], v83 offset:6144
	s_waitcnt lgkmcnt(8)
	v_mfma_f32_16x16x32_bf16 v[2:5], v[164:167], v[148:151], v[2:5]
	s_mov_b32 m0, s22
	v_mfma_f32_16x16x32_bf16 v[6:9], v[168:171], v[148:151], v[6:9]
	global_load_lds_dwordx4 v66, s[8:9]
	v_mfma_f32_16x16x32_bf16 v[10:13], v[172:175], v[148:151], v[10:13]
	s_add_u32 m0, s22, 0x400
	v_mfma_f32_16x16x32_bf16 v[14:17], v[176:179], v[148:151], v[14:17]
	global_load_lds_dwordx4 v67, s[8:9]
	v_mfma_f32_16x16x32_bf16 v[18:21], v[164:167], v[152:155], v[18:21]
	s_add_u32 m0, s22, 0x800
	v_mfma_f32_16x16x32_bf16 v[22:25], v[168:171], v[152:155], v[22:25]
	global_load_lds_dwordx4 v68, s[8:9]
	v_mfma_f32_16x16x32_bf16 v[26:29], v[172:175], v[152:155], v[26:29]
	s_add_u32 m0, s22, 0xc00
	v_mfma_f32_16x16x32_bf16 v[30:33], v[176:179], v[152:155], v[30:33]
	global_load_lds_dwordx4 v69, s[8:9]
	v_mfma_f32_16x16x32_bf16 v[34:37], v[164:167], v[156:159], v[34:37]
	s_mov_b32 m0, s56
	v_mfma_f32_16x16x32_bf16 v[38:41], v[168:171], v[156:159], v[38:41]
	global_load_lds_dwordx4 v70, s[14:15]
	v_mfma_f32_16x16x32_bf16 v[42:45], v[172:175], v[156:159], v[42:45]
	s_add_u32 m0, s56, 0x400
	v_mfma_f32_16x16x32_bf16 v[46:49], v[176:179], v[156:159], v[46:49]
	global_load_lds_dwordx4 v71, s[14:15]
	v_mfma_f32_16x16x32_bf16 v[50:53], v[164:167], v[160:163], v[50:53]
	v_mfma_f32_16x16x32_bf16 v[54:57], v[168:171], v[160:163], v[54:57]
	v_mfma_f32_16x16x32_bf16 v[58:61], v[172:175], v[160:163], v[58:61]
	v_mfma_f32_16x16x32_bf16 v[62:65], v[176:179], v[160:163], v[62:65]
	s_waitcnt lgkmcnt(0)
	v_mfma_f32_16x16x32_bf16 v[2:5], v[228:231], v[180:183], v[2:5]
	v_mfma_f32_16x16x32_bf16 v[6:9], v[232:235], v[180:183], v[6:9]
	v_mfma_f32_16x16x32_bf16 v[10:13], v[236:239], v[180:183], v[10:13]
	v_mfma_f32_16x16x32_bf16 v[14:17], v[240:243], v[180:183], v[14:17]
	v_mfma_f32_16x16x32_bf16 v[18:21], v[228:231], v[184:187], v[18:21]
	v_mfma_f32_16x16x32_bf16 v[22:25], v[232:235], v[184:187], v[22:25]
	v_mfma_f32_16x16x32_bf16 v[26:29], v[236:239], v[184:187], v[26:29]
	v_mfma_f32_16x16x32_bf16 v[30:33], v[240:243], v[184:187], v[30:33]
	v_mfma_f32_16x16x32_bf16 v[34:37], v[228:231], v[188:191], v[34:37]
	v_mfma_f32_16x16x32_bf16 v[38:41], v[232:235], v[188:191], v[38:41]
	v_mfma_f32_16x16x32_bf16 v[42:45], v[236:239], v[188:191], v[42:45]
	v_mfma_f32_16x16x32_bf16 v[46:49], v[240:243], v[188:191], v[46:49]
	v_mfma_f32_16x16x32_bf16 v[50:53], v[228:231], v[192:195], v[50:53]
	v_mfma_f32_16x16x32_bf16 v[54:57], v[232:235], v[192:195], v[54:57]
	v_mfma_f32_16x16x32_bf16 v[58:61], v[236:239], v[192:195], v[58:61]
	v_mfma_f32_16x16x32_bf16 v[62:65], v[240:243], v[192:195], v[62:65]
	s_add_u32 s8, s8, 0x80
	s_addc_u32 s9, s9, 0
	s_add_u32 s14, s14, 0x80
	s_addc_u32 s15, s15, 0
	s_waitcnt vmcnt(6)
	s_barrier
	ds_read_b128 v[148:151], v73 offset:0
	ds_read_b128 v[152:155], v73 offset:2048
	ds_read_b128 v[156:159], v73 offset:4096
	ds_read_b128 v[160:163], v73 offset:6144
	ds_read_b128 v[164:167], v81 offset:0
	ds_read_b128 v[168:171], v81 offset:2048
	ds_read_b128 v[172:175], v81 offset:4096
	ds_read_b128 v[176:179], v81 offset:6144
	ds_read_b128 v[180:183], v76 offset:0
	ds_read_b128 v[184:187], v76 offset:2048
	ds_read_b128 v[188:191], v76 offset:4096
	ds_read_b128 v[192:195], v76 offset:6144
	ds_read_b128 v[228:231], v84 offset:0
	ds_read_b128 v[232:235], v84 offset:2048
	ds_read_b128 v[236:239], v84 offset:4096
	ds_read_b128 v[240:243], v84 offset:6144
	s_waitcnt lgkmcnt(8)
	v_mfma_f32_16x16x32_bf16 v[2:5], v[164:167], v[148:151], v[2:5]
	s_mov_b32 m0, s20
	v_mfma_f32_16x16x32_bf16 v[6:9], v[168:171], v[148:151], v[6:9]
	global_load_lds_dwordx4 v66, s[8:9]
	v_mfma_f32_16x16x32_bf16 v[10:13], v[172:175], v[148:151], v[10:13]
	s_add_u32 m0, s20, 0x400
	v_mfma_f32_16x16x32_bf16 v[14:17], v[176:179], v[148:151], v[14:17]
	global_load_lds_dwordx4 v67, s[8:9]
	v_mfma_f32_16x16x32_bf16 v[18:21], v[164:167], v[152:155], v[18:21]
	s_add_u32 m0, s20, 0x800
	v_mfma_f32_16x16x32_bf16 v[22:25], v[168:171], v[152:155], v[22:25]
	global_load_lds_dwordx4 v68, s[8:9]
	v_mfma_f32_16x16x32_bf16 v[26:29], v[172:175], v[152:155], v[26:29]
	s_add_u32 m0, s20, 0xc00
	v_mfma_f32_16x16x32_bf16 v[30:33], v[176:179], v[152:155], v[30:33]
	global_load_lds_dwordx4 v69, s[8:9]
	v_mfma_f32_16x16x32_bf16 v[34:37], v[164:167], v[156:159], v[34:37]
	s_mov_b32 m0, s54
	v_mfma_f32_16x16x32_bf16 v[38:41], v[168:171], v[156:159], v[38:41]
	global_load_lds_dwordx4 v70, s[14:15]
	v_mfma_f32_16x16x32_bf16 v[42:45], v[172:175], v[156:159], v[42:45]
	s_add_u32 m0, s54, 0x400
	v_mfma_f32_16x16x32_bf16 v[46:49], v[176:179], v[156:159], v[46:49]
	global_load_lds_dwordx4 v71, s[14:15]
	v_mfma_f32_16x16x32_bf16 v[50:53], v[164:167], v[160:163], v[50:53]
	v_mfma_f32_16x16x32_bf16 v[54:57], v[168:171], v[160:163], v[54:57]
	v_mfma_f32_16x16x32_bf16 v[58:61], v[172:175], v[160:163], v[58:61]
	v_mfma_f32_16x16x32_bf16 v[62:65], v[176:179], v[160:163], v[62:65]
	s_waitcnt lgkmcnt(0)
	v_mfma_f32_16x16x32_bf16 v[2:5], v[228:231], v[180:183], v[2:5]
	v_mfma_f32_16x16x32_bf16 v[6:9], v[232:235], v[180:183], v[6:9]
	v_mfma_f32_16x16x32_bf16 v[10:13], v[236:239], v[180:183], v[10:13]
	v_mfma_f32_16x16x32_bf16 v[14:17], v[240:243], v[180:183], v[14:17]
	v_mfma_f32_16x16x32_bf16 v[18:21], v[228:231], v[184:187], v[18:21]
	v_mfma_f32_16x16x32_bf16 v[22:25], v[232:235], v[184:187], v[22:25]
	v_mfma_f32_16x16x32_bf16 v[26:29], v[236:239], v[184:187], v[26:29]
	v_mfma_f32_16x16x32_bf16 v[30:33], v[240:243], v[184:187], v[30:33]
	v_mfma_f32_16x16x32_bf16 v[34:37], v[228:231], v[188:191], v[34:37]
	v_mfma_f32_16x16x32_bf16 v[38:41], v[232:235], v[188:191], v[38:41]
	v_mfma_f32_16x16x32_bf16 v[42:45], v[236:239], v[188:191], v[42:45]
	v_mfma_f32_16x16x32_bf16 v[46:49], v[240:243], v[188:191], v[46:49]
	v_mfma_f32_16x16x32_bf16 v[50:53], v[228:231], v[192:195], v[50:53]
	v_mfma_f32_16x16x32_bf16 v[54:57], v[232:235], v[192:195], v[54:57]
	v_mfma_f32_16x16x32_bf16 v[58:61], v[236:239], v[192:195], v[58:61]
	v_mfma_f32_16x16x32_bf16 v[62:65], v[240:243], v[192:195], v[62:65]
	s_add_u32 s8, s8, 0x80
	s_addc_u32 s9, s9, 0
	s_add_u32 s14, s14, 0x80
	s_addc_u32 s15, s15, 0
	s_waitcnt vmcnt(6)
	s_barrier
	ds_read_b128 v[148:151], v74 offset:0
	ds_read_b128 v[152:155], v74 offset:2048
	ds_read_b128 v[156:159], v74 offset:4096
	ds_read_b128 v[160:163], v74 offset:6144
	ds_read_b128 v[164:167], v82 offset:0
	ds_read_b128 v[168:171], v82 offset:2048
	ds_read_b128 v[172:175], v82 offset:4096
	ds_read_b128 v[176:179], v82 offset:6144
	ds_read_b128 v[180:183], v77 offset:0
	ds_read_b128 v[184:187], v77 offset:2048
	ds_read_b128 v[188:191], v77 offset:4096
	ds_read_b128 v[192:195], v77 offset:6144
	ds_read_b128 v[228:231], v85 offset:0
	ds_read_b128 v[232:235], v85 offset:2048
	ds_read_b128 v[236:239], v85 offset:4096
	ds_read_b128 v[240:243], v85 offset:6144
	s_waitcnt lgkmcnt(8)
	v_mfma_f32_16x16x32_bf16 v[2:5], v[164:167], v[148:151], v[2:5]
	s_mov_b32 m0, s21
	v_mfma_f32_16x16x32_bf16 v[6:9], v[168:171], v[148:151], v[6:9]
	global_load_lds_dwordx4 v66, s[8:9]
	v_mfma_f32_16x16x32_bf16 v[10:13], v[172:175], v[148:151], v[10:13]
	s_add_u32 m0, s21, 0x400
	v_mfma_f32_16x16x32_bf16 v[14:17], v[176:179], v[148:151], v[14:17]
	global_load_lds_dwordx4 v67, s[8:9]
	v_mfma_f32_16x16x32_bf16 v[18:21], v[164:167], v[152:155], v[18:21]
	s_add_u32 m0, s21, 0x800
	v_mfma_f32_16x16x32_bf16 v[22:25], v[168:171], v[152:155], v[22:25]
	global_load_lds_dwordx4 v68, s[8:9]
	v_mfma_f32_16x16x32_bf16 v[26:29], v[172:175], v[152:155], v[26:29]
	s_add_u32 m0, s21, 0xc00
	v_mfma_f32_16x16x32_bf16 v[30:33], v[176:179], v[152:155], v[30:33]
	global_load_lds_dwordx4 v69, s[8:9]
	v_mfma_f32_16x16x32_bf16 v[34:37], v[164:167], v[156:159], v[34:37]
	s_mov_b32 m0, s55
	v_mfma_f32_16x16x32_bf16 v[38:41], v[168:171], v[156:159], v[38:41]
	global_load_lds_dwordx4 v70, s[14:15]
	v_mfma_f32_16x16x32_bf16 v[42:45], v[172:175], v[156:159], v[42:45]
	s_add_u32 m0, s55, 0x400
	v_mfma_f32_16x16x32_bf16 v[46:49], v[176:179], v[156:159], v[46:49]
	global_load_lds_dwordx4 v71, s[14:15]
	v_mfma_f32_16x16x32_bf16 v[50:53], v[164:167], v[160:163], v[50:53]
	v_mfma_f32_16x16x32_bf16 v[54:57], v[168:171], v[160:163], v[54:57]
	v_mfma_f32_16x16x32_bf16 v[58:61], v[172:175], v[160:163], v[58:61]
	v_mfma_f32_16x16x32_bf16 v[62:65], v[176:179], v[160:163], v[62:65]
	s_waitcnt lgkmcnt(0)
	v_mfma_f32_16x16x32_bf16 v[2:5], v[228:231], v[180:183], v[2:5]
	v_mfma_f32_16x16x32_bf16 v[6:9], v[232:235], v[180:183], v[6:9]
	v_mfma_f32_16x16x32_bf16 v[10:13], v[236:239], v[180:183], v[10:13]
	v_mfma_f32_16x16x32_bf16 v[14:17], v[240:243], v[180:183], v[14:17]
	v_mfma_f32_16x16x32_bf16 v[18:21], v[228:231], v[184:187], v[18:21]
	v_mfma_f32_16x16x32_bf16 v[22:25], v[232:235], v[184:187], v[22:25]
	v_mfma_f32_16x16x32_bf16 v[26:29], v[236:239], v[184:187], v[26:29]
	v_mfma_f32_16x16x32_bf16 v[30:33], v[240:243], v[184:187], v[30:33]
	v_mfma_f32_16x16x32_bf16 v[34:37], v[228:231], v[188:191], v[34:37]
	v_mfma_f32_16x16x32_bf16 v[38:41], v[232:235], v[188:191], v[38:41]
	v_mfma_f32_16x16x32_bf16 v[42:45], v[236:239], v[188:191], v[42:45]
	v_mfma_f32_16x16x32_bf16 v[46:49], v[240:243], v[188:191], v[46:49]
	v_mfma_f32_16x16x32_bf16 v[50:53], v[228:231], v[192:195], v[50:53]
	v_mfma_f32_16x16x32_bf16 v[54:57], v[232:235], v[192:195], v[54:57]
	v_mfma_f32_16x16x32_bf16 v[58:61], v[236:239], v[192:195], v[58:61]
	v_mfma_f32_16x16x32_bf16 v[62:65], v[240:243], v[192:195], v[62:65]
	s_add_u32 s8, s8, 0x80
	s_addc_u32 s9, s9, 0
	s_add_u32 s14, s14, 0x80
	s_addc_u32 s15, s15, 0
	s_waitcnt vmcnt(6)
	s_barrier
	ds_read_b128 v[148:151], v72 offset:0
	ds_read_b128 v[152:155], v72 offset:2048
	ds_read_b128 v[156:159], v72 offset:4096
	ds_read_b128 v[160:163], v72 offset:6144
	ds_read_b128 v[164:167], v80 offset:0
	ds_read_b128 v[168:171], v80 offset:2048
	ds_read_b128 v[172:175], v80 offset:4096
	ds_read_b128 v[176:179], v80 offset:6144
	ds_read_b128 v[180:183], v75 offset:0
	ds_read_b128 v[184:187], v75 offset:2048
	ds_read_b128 v[188:191], v75 offset:4096
	ds_read_b128 v[192:195], v75 offset:6144
	ds_read_b128 v[228:231], v83 offset:0
	ds_read_b128 v[232:235], v83 offset:2048
	ds_read_b128 v[236:239], v83 offset:4096
	ds_read_b128 v[240:243], v83 offset:6144
	s_waitcnt lgkmcnt(8)
	v_mfma_f32_16x16x32_bf16 v[2:5], v[164:167], v[148:151], v[2:5]
	s_mov_b32 m0, s22
	v_mfma_f32_16x16x32_bf16 v[6:9], v[168:171], v[148:151], v[6:9]
	global_load_lds_dwordx4 v66, s[8:9]
	v_mfma_f32_16x16x32_bf16 v[10:13], v[172:175], v[148:151], v[10:13]
	s_add_u32 m0, s22, 0x400
	v_mfma_f32_16x16x32_bf16 v[14:17], v[176:179], v[148:151], v[14:17]
	global_load_lds_dwordx4 v67, s[8:9]
	v_mfma_f32_16x16x32_bf16 v[18:21], v[164:167], v[152:155], v[18:21]
	s_add_u32 m0, s22, 0x800
	v_mfma_f32_16x16x32_bf16 v[22:25], v[168:171], v[152:155], v[22:25]
	global_load_lds_dwordx4 v68, s[8:9]
	v_mfma_f32_16x16x32_bf16 v[26:29], v[172:175], v[152:155], v[26:29]
	s_add_u32 m0, s22, 0xc00
	v_mfma_f32_16x16x32_bf16 v[30:33], v[176:179], v[152:155], v[30:33]
	global_load_lds_dwordx4 v69, s[8:9]
	v_mfma_f32_16x16x32_bf16 v[34:37], v[164:167], v[156:159], v[34:37]
	s_mov_b32 m0, s56
	v_mfma_f32_16x16x32_bf16 v[38:41], v[168:171], v[156:159], v[38:41]
	global_load_lds_dwordx4 v70, s[14:15]
	v_mfma_f32_16x16x32_bf16 v[42:45], v[172:175], v[156:159], v[42:45]
	s_add_u32 m0, s56, 0x400
	v_mfma_f32_16x16x32_bf16 v[46:49], v[176:179], v[156:159], v[46:49]
	global_load_lds_dwordx4 v71, s[14:15]
	v_mfma_f32_16x16x32_bf16 v[50:53], v[164:167], v[160:163], v[50:53]
	v_mfma_f32_16x16x32_bf16 v[54:57], v[168:171], v[160:163], v[54:57]
	v_mfma_f32_16x16x32_bf16 v[58:61], v[172:175], v[160:163], v[58:61]
	v_mfma_f32_16x16x32_bf16 v[62:65], v[176:179], v[160:163], v[62:65]
	s_waitcnt lgkmcnt(0)
	v_mfma_f32_16x16x32_bf16 v[2:5], v[228:231], v[180:183], v[2:5]
	v_mfma_f32_16x16x32_bf16 v[6:9], v[232:235], v[180:183], v[6:9]
	v_mfma_f32_16x16x32_bf16 v[10:13], v[236:239], v[180:183], v[10:13]
	v_mfma_f32_16x16x32_bf16 v[14:17], v[240:243], v[180:183], v[14:17]
	v_mfma_f32_16x16x32_bf16 v[18:21], v[228:231], v[184:187], v[18:21]
	v_mfma_f32_16x16x32_bf16 v[22:25], v[232:235], v[184:187], v[22:25]
	v_mfma_f32_16x16x32_bf16 v[26:29], v[236:239], v[184:187], v[26:29]
	v_mfma_f32_16x16x32_bf16 v[30:33], v[240:243], v[184:187], v[30:33]
	v_mfma_f32_16x16x32_bf16 v[34:37], v[228:231], v[188:191], v[34:37]
	v_mfma_f32_16x16x32_bf16 v[38:41], v[232:235], v[188:191], v[38:41]
	v_mfma_f32_16x16x32_bf16 v[42:45], v[236:239], v[188:191], v[42:45]
	v_mfma_f32_16x16x32_bf16 v[46:49], v[240:243], v[188:191], v[46:49]
	v_mfma_f32_16x16x32_bf16 v[50:53], v[228:231], v[192:195], v[50:53]
	v_mfma_f32_16x16x32_bf16 v[54:57], v[232:235], v[192:195], v[54:57]
	v_mfma_f32_16x16x32_bf16 v[58:61], v[236:239], v[192:195], v[58:61]
	v_mfma_f32_16x16x32_bf16 v[62:65], v[240:243], v[192:195], v[62:65]
	s_add_u32 s8, s8, 0x80
	s_addc_u32 s9, s9, 0
	s_add_u32 s14, s14, 0x80
	s_addc_u32 s15, s15, 0
	s_waitcnt vmcnt(6)
	s_barrier
	ds_read_b128 v[148:151], v73 offset:0
	ds_read_b128 v[152:155], v73 offset:2048
	ds_read_b128 v[156:159], v73 offset:4096
	ds_read_b128 v[160:163], v73 offset:6144
	ds_read_b128 v[164:167], v81 offset:0
	ds_read_b128 v[168:171], v81 offset:2048
	ds_read_b128 v[172:175], v81 offset:4096
	ds_read_b128 v[176:179], v81 offset:6144
	ds_read_b128 v[180:183], v76 offset:0
	ds_read_b128 v[184:187], v76 offset:2048
	ds_read_b128 v[188:191], v76 offset:4096
	ds_read_b128 v[192:195], v76 offset:6144
	ds_read_b128 v[228:231], v84 offset:0
	ds_read_b128 v[232:235], v84 offset:2048
	ds_read_b128 v[236:239], v84 offset:4096
	ds_read_b128 v[240:243], v84 offset:6144
	s_waitcnt lgkmcnt(8)
	v_mfma_f32_16x16x32_bf16 v[2:5], v[164:167], v[148:151], v[2:5]
	s_mov_b32 m0, s20
	v_mfma_f32_16x16x32_bf16 v[6:9], v[168:171], v[148:151], v[6:9]
	global_load_lds_dwordx4 v66, s[8:9]
	v_mfma_f32_16x16x32_bf16 v[10:13], v[172:175], v[148:151], v[10:13]
	s_add_u32 m0, s20, 0x400
	v_mfma_f32_16x16x32_bf16 v[14:17], v[176:179], v[148:151], v[14:17]
	global_load_lds_dwordx4 v67, s[8:9]
	v_mfma_f32_16x16x32_bf16 v[18:21], v[164:167], v[152:155], v[18:21]
	s_add_u32 m0, s20, 0x800
	v_mfma_f32_16x16x32_bf16 v[22:25], v[168:171], v[152:155], v[22:25]
	global_load_lds_dwordx4 v68, s[8:9]
	v_mfma_f32_16x16x32_bf16 v[26:29], v[172:175], v[152:155], v[26:29]
	s_add_u32 m0, s20, 0xc00
	v_mfma_f32_16x16x32_bf16 v[30:33], v[176:179], v[152:155], v[30:33]
	global_load_lds_dwordx4 v69, s[8:9]
	v_mfma_f32_16x16x32_bf16 v[34:37], v[164:167], v[156:159], v[34:37]
	s_mov_b32 m0, s54
	v_mfma_f32_16x16x32_bf16 v[38:41], v[168:171], v[156:159], v[38:41]
	global_load_lds_dwordx4 v70, s[14:15]
	v_mfma_f32_16x16x32_bf16 v[42:45], v[172:175], v[156:159], v[42:45]
	s_add_u32 m0, s54, 0x400
	v_mfma_f32_16x16x32_bf16 v[46:49], v[176:179], v[156:159], v[46:49]
	global_load_lds_dwordx4 v71, s[14:15]
	v_mfma_f32_16x16x32_bf16 v[50:53], v[164:167], v[160:163], v[50:53]
	v_mfma_f32_16x16x32_bf16 v[54:57], v[168:171], v[160:163], v[54:57]
	v_mfma_f32_16x16x32_bf16 v[58:61], v[172:175], v[160:163], v[58:61]
	v_mfma_f32_16x16x32_bf16 v[62:65], v[176:179], v[160:163], v[62:65]
	s_waitcnt lgkmcnt(0)
	v_mfma_f32_16x16x32_bf16 v[2:5], v[228:231], v[180:183], v[2:5]
	v_mfma_f32_16x16x32_bf16 v[6:9], v[232:235], v[180:183], v[6:9]
	v_mfma_f32_16x16x32_bf16 v[10:13], v[236:239], v[180:183], v[10:13]
	v_mfma_f32_16x16x32_bf16 v[14:17], v[240:243], v[180:183], v[14:17]
	v_mfma_f32_16x16x32_bf16 v[18:21], v[228:231], v[184:187], v[18:21]
	v_mfma_f32_16x16x32_bf16 v[22:25], v[232:235], v[184:187], v[22:25]
	v_mfma_f32_16x16x32_bf16 v[26:29], v[236:239], v[184:187], v[26:29]
	v_mfma_f32_16x16x32_bf16 v[30:33], v[240:243], v[184:187], v[30:33]
	v_mfma_f32_16x16x32_bf16 v[34:37], v[228:231], v[188:191], v[34:37]
	v_mfma_f32_16x16x32_bf16 v[38:41], v[232:235], v[188:191], v[38:41]
	v_mfma_f32_16x16x32_bf16 v[42:45], v[236:239], v[188:191], v[42:45]
	v_mfma_f32_16x16x32_bf16 v[46:49], v[240:243], v[188:191], v[46:49]
	v_mfma_f32_16x16x32_bf16 v[50:53], v[228:231], v[192:195], v[50:53]
	v_mfma_f32_16x16x32_bf16 v[54:57], v[232:235], v[192:195], v[54:57]
	v_mfma_f32_16x16x32_bf16 v[58:61], v[236:239], v[192:195], v[58:61]
	v_mfma_f32_16x16x32_bf16 v[62:65], v[240:243], v[192:195], v[62:65]
	s_add_u32 s8, s8, 0x80
	s_addc_u32 s9, s9, 0
	s_add_u32 s14, s14, 0x80
	s_addc_u32 s15, s15, 0
	s_waitcnt vmcnt(6)
	s_barrier
	ds_read_b128 v[148:151], v74 offset:0
	ds_read_b128 v[152:155], v74 offset:2048
	ds_read_b128 v[156:159], v74 offset:4096
	ds_read_b128 v[160:163], v74 offset:6144
	ds_read_b128 v[164:167], v82 offset:0
	ds_read_b128 v[168:171], v82 offset:2048
	ds_read_b128 v[172:175], v82 offset:4096
	ds_read_b128 v[176:179], v82 offset:6144
	ds_read_b128 v[180:183], v77 offset:0
	ds_read_b128 v[184:187], v77 offset:2048
	ds_read_b128 v[188:191], v77 offset:4096
	ds_read_b128 v[192:195], v77 offset:6144
	ds_read_b128 v[228:231], v85 offset:0
	ds_read_b128 v[232:235], v85 offset:2048
	ds_read_b128 v[236:239], v85 offset:4096
	ds_read_b128 v[240:243], v85 offset:6144
	s_waitcnt lgkmcnt(8)
	v_mfma_f32_16x16x32_bf16 v[2:5], v[164:167], v[148:151], v[2:5]
	v_mfma_f32_16x16x32_bf16 v[6:9], v[168:171], v[148:151], v[6:9]
	v_mfma_f32_16x16x32_bf16 v[10:13], v[172:175], v[148:151], v[10:13]
	v_mfma_f32_16x16x32_bf16 v[14:17], v[176:179], v[148:151], v[14:17]
	v_mfma_f32_16x16x32_bf16 v[18:21], v[164:167], v[152:155], v[18:21]
	v_mfma_f32_16x16x32_bf16 v[22:25], v[168:171], v[152:155], v[22:25]
	v_mfma_f32_16x16x32_bf16 v[26:29], v[172:175], v[152:155], v[26:29]
	v_mfma_f32_16x16x32_bf16 v[30:33], v[176:179], v[152:155], v[30:33]
	v_mfma_f32_16x16x32_bf16 v[34:37], v[164:167], v[156:159], v[34:37]
	v_mfma_f32_16x16x32_bf16 v[38:41], v[168:171], v[156:159], v[38:41]
	v_mfma_f32_16x16x32_bf16 v[42:45], v[172:175], v[156:159], v[42:45]
	v_mfma_f32_16x16x32_bf16 v[46:49], v[176:179], v[156:159], v[46:49]
	v_mfma_f32_16x16x32_bf16 v[50:53], v[164:167], v[160:163], v[50:53]
	v_mfma_f32_16x16x32_bf16 v[54:57], v[168:171], v[160:163], v[54:57]
	v_mfma_f32_16x16x32_bf16 v[58:61], v[172:175], v[160:163], v[58:61]
	v_mfma_f32_16x16x32_bf16 v[62:65], v[176:179], v[160:163], v[62:65]
	s_waitcnt lgkmcnt(0)
	v_mfma_f32_16x16x32_bf16 v[2:5], v[228:231], v[180:183], v[2:5]
	v_mfma_f32_16x16x32_bf16 v[6:9], v[232:235], v[180:183], v[6:9]
	v_mfma_f32_16x16x32_bf16 v[10:13], v[236:239], v[180:183], v[10:13]
	v_mfma_f32_16x16x32_bf16 v[14:17], v[240:243], v[180:183], v[14:17]
	v_mfma_f32_16x16x32_bf16 v[18:21], v[228:231], v[184:187], v[18:21]
	v_mfma_f32_16x16x32_bf16 v[22:25], v[232:235], v[184:187], v[22:25]
	v_mfma_f32_16x16x32_bf16 v[26:29], v[236:239], v[184:187], v[26:29]
	v_mfma_f32_16x16x32_bf16 v[30:33], v[240:243], v[184:187], v[30:33]
	v_mfma_f32_16x16x32_bf16 v[34:37], v[228:231], v[188:191], v[34:37]
	v_mfma_f32_16x16x32_bf16 v[38:41], v[232:235], v[188:191], v[38:41]
	v_mfma_f32_16x16x32_bf16 v[42:45], v[236:239], v[188:191], v[42:45]
	v_mfma_f32_16x16x32_bf16 v[46:49], v[240:243], v[188:191], v[46:49]
	v_mfma_f32_16x16x32_bf16 v[50:53], v[228:231], v[192:195], v[50:53]
	v_mfma_f32_16x16x32_bf16 v[54:57], v[232:235], v[192:195], v[54:57]
	v_mfma_f32_16x16x32_bf16 v[58:61], v[236:239], v[192:195], v[58:61]
	v_mfma_f32_16x16x32_bf16 v[62:65], v[240:243], v[192:195], v[62:65]
	s_waitcnt vmcnt(0)
	s_barrier
	ds_read_b128 v[148:151], v72 offset:0
	ds_read_b128 v[152:155], v72 offset:2048
	ds_read_b128 v[156:159], v72 offset:4096
	ds_read_b128 v[160:163], v72 offset:6144
	ds_read_b128 v[164:167], v80 offset:0
	ds_read_b128 v[168:171], v80 offset:2048
	ds_read_b128 v[172:175], v80 offset:4096
	ds_read_b128 v[176:179], v80 offset:6144
	ds_read_b128 v[180:183], v75 offset:0
	ds_read_b128 v[184:187], v75 offset:2048
	ds_read_b128 v[188:191], v75 offset:4096
	ds_read_b128 v[192:195], v75 offset:6144
	ds_read_b128 v[228:231], v83 offset:0
	ds_read_b128 v[232:235], v83 offset:2048
	ds_read_b128 v[236:239], v83 offset:4096
	ds_read_b128 v[240:243], v83 offset:6144
	s_waitcnt lgkmcnt(8)
	v_mfma_f32_16x16x32_bf16 v[2:5], v[164:167], v[148:151], v[2:5]
	v_mfma_f32_16x16x32_bf16 v[6:9], v[168:171], v[148:151], v[6:9]
	v_mfma_f32_16x16x32_bf16 v[10:13], v[172:175], v[148:151], v[10:13]
	v_mfma_f32_16x16x32_bf16 v[14:17], v[176:179], v[148:151], v[14:17]
	v_mfma_f32_16x16x32_bf16 v[18:21], v[164:167], v[152:155], v[18:21]
	v_mfma_f32_16x16x32_bf16 v[22:25], v[168:171], v[152:155], v[22:25]
	v_mfma_f32_16x16x32_bf16 v[26:29], v[172:175], v[152:155], v[26:29]
	v_mfma_f32_16x16x32_bf16 v[30:33], v[176:179], v[152:155], v[30:33]
	v_mfma_f32_16x16x32_bf16 v[34:37], v[164:167], v[156:159], v[34:37]
	v_mfma_f32_16x16x32_bf16 v[38:41], v[168:171], v[156:159], v[38:41]
	v_mfma_f32_16x16x32_bf16 v[42:45], v[172:175], v[156:159], v[42:45]
	v_mfma_f32_16x16x32_bf16 v[46:49], v[176:179], v[156:159], v[46:49]
	v_mfma_f32_16x16x32_bf16 v[50:53], v[164:167], v[160:163], v[50:53]
	v_mfma_f32_16x16x32_bf16 v[54:57], v[168:171], v[160:163], v[54:57]
	v_mfma_f32_16x16x32_bf16 v[58:61], v[172:175], v[160:163], v[58:61]
	v_mfma_f32_16x16x32_bf16 v[62:65], v[176:179], v[160:163], v[62:65]
	s_waitcnt lgkmcnt(0)
	v_mfma_f32_16x16x32_bf16 v[2:5], v[228:231], v[180:183], v[2:5]
	v_mfma_f32_16x16x32_bf16 v[6:9], v[232:235], v[180:183], v[6:9]
	v_mfma_f32_16x16x32_bf16 v[10:13], v[236:239], v[180:183], v[10:13]
	v_mfma_f32_16x16x32_bf16 v[14:17], v[240:243], v[180:183], v[14:17]
	v_mfma_f32_16x16x32_bf16 v[18:21], v[228:231], v[184:187], v[18:21]
	v_mfma_f32_16x16x32_bf16 v[22:25], v[232:235], v[184:187], v[22:25]
	v_mfma_f32_16x16x32_bf16 v[26:29], v[236:239], v[184:187], v[26:29]
	v_mfma_f32_16x16x32_bf16 v[30:33], v[240:243], v[184:187], v[30:33]
	v_mfma_f32_16x16x32_bf16 v[34:37], v[228:231], v[188:191], v[34:37]
	v_mfma_f32_16x16x32_bf16 v[38:41], v[232:235], v[188:191], v[38:41]
	v_mfma_f32_16x16x32_bf16 v[42:45], v[236:239], v[188:191], v[42:45]
	v_mfma_f32_16x16x32_bf16 v[46:49], v[240:243], v[188:191], v[46:49]
	v_mfma_f32_16x16x32_bf16 v[50:53], v[228:231], v[192:195], v[50:53]
	v_mfma_f32_16x16x32_bf16 v[54:57], v[232:235], v[192:195], v[54:57]
	v_mfma_f32_16x16x32_bf16 v[58:61], v[236:239], v[192:195], v[58:61]
	v_mfma_f32_16x16x32_bf16 v[62:65], v[240:243], v[192:195], v[62:65]
	s_barrier
	v_mov_b32_e32 v86, 0x200f0
	ds_write_b64 v86, v[250:251]
	s_waitcnt lgkmcnt(0)
	s_nop 7
	s_nop 7
	s_and_b32 s14, s53, 31
	s_lshr_b32 s20, s53, 5
	s_sub_u32 s0, s14, 16
	s_lshr_b32 s0, s0, 2
	s_add_u32 s0, s0, 1
	s_cmp_lt_u32 s14, 16
	s_cselect_b32 s15, 0, s0
	ds_read_b128 v[74:77], v131
	s_add_u32 s0, s52, s15
	s_mul_i32 s0, s0, 0x3000
	s_add_u32 s0, s0, 0x2000
	s_add_u32 s22, s80, s0
	s_addc_u32 s23, s81, 0
	v_and_b32_e32 v66, 63, v0
	v_lshrrev_b32_e32 v67, 6, v0
	v_and_b32_e32 v68, 15, v66
	v_lshrrev_b32_e32 v69, 4, v66
	v_lshrrev_b32_e32 v70, 1, v67
	v_and_b32_e32 v71, 1, v67
	v_lshl_add_u32 v72, v70, 6, v68
	v_lshlrev_b32_e32 v73, 8, v71
	v_lshl_add_u32 v73, v69, 4, v73
	s_lshl_b32 s0, s20, 9
	v_add_u32_e32 v73, s0, v73
	s_waitcnt lgkmcnt(0)
	v_readfirstlane_b32 s8, v74
	v_readfirstlane_b32 s9, v75
	v_readfirstlane_b32 s54, v76
	v_readfirstlane_b32 s55, v77
	s_lshl_b32 s0, s14, 20
	s_cmp_eq_u32 s52, 0
	s_cbranch_scc1 .Ld_epi_l0
	s_mov_b32 s8, s16
	s_mov_b32 s9, s17
	s_branch .Ld_epi_xb

.Ld_epi_xb:
	s_add_u32 s8, s8, s0
	s_addc_u32 s9, s9, 0
	v_lshl_add_u32 v80, v72, 12, v73
	v_add_u32_e32 v81, 0x10000, v80
	v_add_u32_e32 v82, 0x20000, v80
	v_add_u32_e32 v83, 0x30000, v80
	global_load_dwordx4 v[236:239], v73, s[22:23] offset:0
	global_load_dwordx4 v[240:243], v73, s[22:23] offset:64
	global_load_dwordx4 v[244:247], v73, s[22:23] offset:128
	global_load_dwordx4 v[248:251], v73, s[22:23] offset:192
	global_load_dwordx4 v[148:151], v80, s[8:9] offset:0 nt
	global_load_dwordx4 v[152:155], v80, s[8:9] offset:64 nt
	global_load_dwordx4 v[156:159], v80, s[8:9] offset:128 nt
	global_load_dwordx4 v[160:163], v80, s[8:9] offset:192 nt
	global_load_dwordx4 v[164:167], v81, s[8:9] offset:0 nt
	global_load_dwordx4 v[168:171], v81, s[8:9] offset:64 nt
	global_load_dwordx4 v[172:175], v81, s[8:9] offset:128 nt
	global_load_dwordx4 v[176:179], v81, s[8:9] offset:192 nt
	global_load_dwordx4 v[180:183], v82, s[8:9] offset:0 nt
	global_load_dwordx4 v[184:187], v82, s[8:9] offset:64 nt
	global_load_dwordx4 v[188:191], v82, s[8:9] offset:128 nt
	global_load_dwordx4 v[192:195], v82, s[8:9] offset:192 nt
	global_load_dwordx4 v[196:199], v83, s[8:9] offset:0 nt
	global_load_dwordx4 v[200:203], v83, s[8:9] offset:64 nt
	global_load_dwordx4 v[228:231], v83, s[8:9] offset:128 nt
	global_load_dwordx4 v[232:235], v83, s[8:9] offset:192 nt
	v_lshlrev_b32_e32 v84, 5, v72
	v_lshl_add_u32 v84, v71, 4, v84
	v_lshl_add_u32 v84, v69, 2, v84
	v_add_u32_e32 v84, 0xf0, v84
	s_waitcnt vmcnt(12)
	v_pk_fma_f32 v[2:3], v[2:3], v[236:237], v[148:149]
	v_pk_fma_f32 v[4:5], v[4:5], v[238:239], v[150:151]
	v_pk_fma_f32 v[6:7], v[6:7], v[240:241], v[152:153]
	v_pk_fma_f32 v[8:9], v[8:9], v[242:243], v[154:155]
	v_pk_fma_f32 v[10:11], v[10:11], v[244:245], v[156:157]
	v_pk_fma_f32 v[12:13], v[12:13], v[246:247], v[158:159]
	v_pk_fma_f32 v[14:15], v[14:15], v[248:249], v[160:161]
	v_pk_fma_f32 v[16:17], v[16:17], v[250:251], v[162:163]
	v_pk_mul_f32 v[86:87], v[2:3], v[2:3]
	v_pk_mul_f32 v[88:89], v[4:5], v[4:5]
	v_pk_fma_f32 v[86:87], v[6:7], v[6:7], v[86:87]
	v_pk_fma_f32 v[88:89], v[8:9], v[8:9], v[88:89]
	v_pk_fma_f32 v[86:87], v[10:11], v[10:11], v[86:87]
	v_pk_fma_f32 v[88:89], v[12:13], v[12:13], v[88:89]
	v_pk_fma_f32 v[86:87], v[14:15], v[14:15], v[86:87]
	v_pk_fma_f32 v[88:89], v[16:17], v[16:17], v[88:89]
	s_nop 0
	v_pk_add_f32 v[86:87], v[86:87], v[88:89]
	s_nop 0
	v_add_f32_e32 v86, v86, v87
	ds_write_b32 v84, v86
	s_waitcnt vmcnt(8)
	v_pk_fma_f32 v[18:19], v[18:19], v[236:237], v[164:165]
	v_pk_fma_f32 v[20:21], v[20:21], v[238:239], v[166:167]
	v_pk_fma_f32 v[22:23], v[22:23], v[240:241], v[168:169]
	v_pk_fma_f32 v[24:25], v[24:25], v[242:243], v[170:171]
	v_pk_fma_f32 v[26:27], v[26:27], v[244:245], v[172:173]
	v_pk_fma_f32 v[28:29], v[28:29], v[246:247], v[174:175]
	v_pk_fma_f32 v[30:31], v[30:31], v[248:249], v[176:177]
	v_pk_fma_f32 v[32:33], v[32:33], v[250:251], v[178:179]
	v_pk_mul_f32 v[86:87], v[18:19], v[18:19]
	v_pk_mul_f32 v[88:89], v[20:21], v[20:21]
	v_pk_fma_f32 v[86:87], v[22:23], v[22:23], v[86:87]
	v_pk_fma_f32 v[88:89], v[24:25], v[24:25], v[88:89]
	v_pk_fma_f32 v[86:87], v[26:27], v[26:27], v[86:87]
	v_pk_fma_f32 v[88:89], v[28:29], v[28:29], v[88:89]
	v_pk_fma_f32 v[86:87], v[30:31], v[30:31], v[86:87]
	v_pk_fma_f32 v[88:89], v[32:33], v[32:33], v[88:89]
	s_nop 0
	v_pk_add_f32 v[86:87], v[86:87], v[88:89]
	s_nop 0
	v_add_f32_e32 v86, v86, v87
	ds_write_b32 v84, v86 offset:512
	s_waitcnt vmcnt(4)
	v_pk_fma_f32 v[34:35], v[34:35], v[236:237], v[180:181]
	v_pk_fma_f32 v[36:37], v[36:37], v[238:239], v[182:183]
	v_pk_fma_f32 v[38:39], v[38:39], v[240:241], v[184:185]
	v_pk_fma_f32 v[40:41], v[40:41], v[242:243], v[186:187]
	v_pk_fma_f32 v[42:43], v[42:43], v[244:245], v[188:189]
	v_pk_fma_f32 v[44:45], v[44:45], v[246:247], v[190:191]
	v_pk_fma_f32 v[46:47], v[46:47], v[248:249], v[192:193]
	v_pk_fma_f32 v[48:49], v[48:49], v[250:251], v[194:195]
	v_pk_mul_f32 v[86:87], v[34:35], v[34:35]
	v_pk_mul_f32 v[88:89], v[36:37], v[36:37]
	v_pk_fma_f32 v[86:87], v[38:39], v[38:39], v[86:87]
	v_pk_fma_f32 v[88:89], v[40:41], v[40:41], v[88:89]
	v_pk_fma_f32 v[86:87], v[42:43], v[42:43], v[86:87]
	v_pk_fma_f32 v[88:89], v[44:45], v[44:45], v[88:89]
	v_pk_fma_f32 v[86:87], v[46:47], v[46:47], v[86:87]
	v_pk_fma_f32 v[88:89], v[48:49], v[48:49], v[88:89]
	s_nop 0
	v_pk_add_f32 v[86:87], v[86:87], v[88:89]
	s_nop 0
	v_add_f32_e32 v86, v86, v87
	ds_write_b32 v84, v86 offset:1024
	s_waitcnt vmcnt(0)
	v_pk_fma_f32 v[50:51], v[50:51], v[236:237], v[196:197]
	v_pk_fma_f32 v[52:53], v[52:53], v[238:239], v[198:199]
	v_pk_fma_f32 v[54:55], v[54:55], v[240:241], v[200:201]
	v_pk_fma_f32 v[56:57], v[56:57], v[242:243], v[202:203]
	v_pk_fma_f32 v[58:59], v[58:59], v[244:245], v[228:229]
	v_pk_fma_f32 v[60:61], v[60:61], v[246:247], v[230:231]
	v_pk_fma_f32 v[62:63], v[62:63], v[248:249], v[232:233]
	v_pk_fma_f32 v[64:65], v[64:65], v[250:251], v[234:235]
	v_pk_mul_f32 v[86:87], v[50:51], v[50:51]
	v_pk_mul_f32 v[88:89], v[52:53], v[52:53]
	v_pk_fma_f32 v[86:87], v[54:55], v[54:55], v[86:87]
	v_pk_fma_f32 v[88:89], v[56:57], v[56:57], v[88:89]
	v_pk_fma_f32 v[86:87], v[58:59], v[58:59], v[86:87]
	v_pk_fma_f32 v[88:89], v[60:61], v[60:61], v[88:89]
	v_pk_fma_f32 v[86:87], v[62:63], v[62:63], v[86:87]
	v_pk_fma_f32 v[88:89], v[64:65], v[64:65], v[88:89]
	s_nop 0
	v_pk_add_f32 v[86:87], v[86:87], v[88:89]
	s_nop 0
	v_add_f32_e32 v86, v86, v87
	ds_write_b32 v84, v86 offset:1536
	s_waitcnt lgkmcnt(0)
	s_barrier
	s_add_u32 s0, s50, s14
	s_lshl_b32 s1, s0, 13
	s_add_u32 s56, s73, s1
	s_addc_u32 s57, s78, 0
	s_lshl_b32 s1, s0, 8
	s_add_u32 s58, s64, s1
	s_addc_u32 s59, s72, 0
	v_cmp_gt_u32_e32 vcc, 0x100, v0
	s_and_saveexec_b64 s[54:55], vcc
	s_cbranch_execz .Ld_epi_x1
	v_lshlrev_b32_e32 v85, 5, v0
	v_add_u32_e32 v86, 0xf0, v85
	ds_read_b128 v[88:91], v86
	ds_read_b128 v[92:95], v86 offset:16
	s_lshl_b32 s1, s20, 2
	v_add_u32_e32 v87, s1, v85
	s_waitcnt lgkmcnt(0)
	v_add_f32_e32 v88, v88, v89
	v_add_f32_e32 v90, v90, v91
	v_add_f32_e32 v92, v92, v93
	v_add_f32_e32 v94, v94, v95
	v_add_f32_e32 v88, v88, v90
	v_add_f32_e32 v92, v92, v94
	v_add_f32_e32 v88, v88, v92
	global_store_dword v87, v88, s[56:57] sc1

.Ld_epi_g1:
	s_waitcnt lgkmcnt(0)
	v_readfirstlane_b32 s8, v74
	v_readfirstlane_b32 s9, v75
	s_nop 3
	s_add_u32 s8, s8, s0
	s_addc_u32 s9, s9, 0
	s_lshl_b32 s0, s14, 20
	s_add_u32 s54, s16, s0
	s_addc_u32 s55, s17, 0
	s_nop 1
	global_load_dwordx4 v[148:151], v73, s[8:9] offset:0
	global_load_dwordx4 v[152:155], v73, s[8:9] offset:64
	global_load_dwordx4 v[156:159], v73, s[8:9] offset:128
	global_load_dwordx4 v[160:163], v73, s[8:9] offset:192
	s_cmp_eq_u32 s52, 0
	s_cbranch_scc0 .Ld_epi_last
	s_add_u32 s0, s15, 5
	s_mul_i32 s0, s0, 0x3000
	s_add_u32 s22, s80, s0
	s_addc_u32 s23, s81, 0
	s_add_u32 s56, s22, 0x1000
	s_addc_u32 s57, s23, 0
	global_load_dwordx4 v[164:167], v73, s[22:23] offset:0
	global_load_dwordx4 v[168:171], v73, s[22:23] offset:64
	global_load_dwordx4 v[172:175], v73, s[22:23] offset:128
	global_load_dwordx4 v[176:179], v73, s[22:23] offset:192
	global_load_dwordx4 v[180:183], v73, s[56:57] offset:0
	global_load_dwordx4 v[184:187], v73, s[56:57] offset:64
	global_load_dwordx4 v[188:191], v73, s[56:57] offset:128
	global_load_dwordx4 v[192:195], v73, s[56:57] offset:192
	s_lshl_b32 s0, s14, 19
	s_add_u32 s58, s26, s0
	s_addc_u32 s59, s27, 0
	v_lshlrev_b32_e32 v84, 11, v72
	v_lshrrev_b32_e32 v85, 1, v73
	v_add_u32_e32 v84, v84, v85
	global_store_dwordx4 v80, v[2:5], s[54:55] offset:0
	global_store_dwordx4 v80, v[6:9], s[54:55] offset:64
	global_store_dwordx4 v80, v[10:13], s[54:55] offset:128
	global_store_dwordx4 v80, v[14:17], s[54:55] offset:192
	global_store_dwordx4 v81, v[18:21], s[54:55] offset:0
	global_store_dwordx4 v81, v[22:25], s[54:55] offset:64
	global_store_dwordx4 v81, v[26:29], s[54:55] offset:128
	global_store_dwordx4 v81, v[30:33], s[54:55] offset:192
	global_store_dwordx4 v82, v[34:37], s[54:55] offset:0
	global_store_dwordx4 v82, v[38:41], s[54:55] offset:64
	global_store_dwordx4 v82, v[42:45], s[54:55] offset:128
	global_store_dwordx4 v82, v[46:49], s[54:55] offset:192
	global_store_dwordx4 v83, v[50:53], s[54:55] offset:0
	global_store_dwordx4 v83, v[54:57], s[54:55] offset:64
	global_store_dwordx4 v83, v[58:61], s[54:55] offset:128
	global_store_dwordx4 v83, v[62:65], s[54:55] offset:192
	s_waitcnt vmcnt(16)
	v_pk_add_f32 v[180:181], v[180:181], 1.0 op_sel_hi:[1,0]
	v_pk_add_f32 v[182:183], v[182:183], 1.0 op_sel_hi:[1,0]
	v_pk_add_f32 v[184:185], v[184:185], 1.0 op_sel_hi:[1,0]
	v_pk_add_f32 v[186:187], v[186:187], 1.0 op_sel_hi:[1,0]
	v_pk_add_f32 v[188:189], v[188:189], 1.0 op_sel_hi:[1,0]
	v_pk_add_f32 v[190:191], v[190:191], 1.0 op_sel_hi:[1,0]
	v_pk_add_f32 v[192:193], v[192:193], 1.0 op_sel_hi:[1,0]
	v_pk_add_f32 v[194:195], v[194:195], 1.0 op_sel_hi:[1,0]
	v_pk_mul_f32 v[148:149], v[148:149], v[180:181]
	v_pk_mul_f32 v[150:151], v[150:151], v[182:183]
	v_pk_mul_f32 v[152:153], v[152:153], v[184:185]
	v_pk_mul_f32 v[154:155], v[154:155], v[186:187]
	v_pk_mul_f32 v[156:157], v[156:157], v[188:189]
	v_pk_mul_f32 v[158:159], v[158:159], v[190:191]
	v_pk_mul_f32 v[160:161], v[160:161], v[192:193]
	v_pk_mul_f32 v[162:163], v[162:163], v[194:195]
	v_pk_mul_f32 v[2:3], v[2:3], v[108:109] op_sel_hi:[1,0]
	v_pk_mul_f32 v[4:5], v[4:5], v[108:109] op_sel_hi:[1,0]
	v_pk_fma_f32 v[2:3], v[2:3], v[148:149], v[164:165]
	v_pk_fma_f32 v[4:5], v[4:5], v[150:151], v[166:167]
	v_cvt_pk_bf16_f32 v2, v2, v3
	v_cvt_pk_bf16_f32 v3, v4, v5
	global_store_dwordx2 v84, v[2:3], s[58:59] offset:0
	v_pk_mul_f32 v[6:7], v[6:7], v[108:109] op_sel_hi:[1,0]
	v_pk_mul_f32 v[8:9], v[8:9], v[108:109] op_sel_hi:[1,0]
	v_pk_fma_f32 v[6:7], v[6:7], v[152:153], v[168:169]
	v_pk_fma_f32 v[8:9], v[8:9], v[154:155], v[170:171]
	v_cvt_pk_bf16_f32 v6, v6, v7
	v_cvt_pk_bf16_f32 v7, v8, v9
	global_store_dwordx2 v84, v[6:7], s[58:59] offset:32
	v_pk_mul_f32 v[10:11], v[10:11], v[108:109] op_sel_hi:[1,0]
	v_pk_mul_f32 v[12:13], v[12:13], v[108:109] op_sel_hi:[1,0]
	v_pk_fma_f32 v[10:11], v[10:11], v[156:157], v[172:173]
	v_pk_fma_f32 v[12:13], v[12:13], v[158:159], v[174:175]
	v_cvt_pk_bf16_f32 v10, v10, v11
	v_cvt_pk_bf16_f32 v11, v12, v13
	global_store_dwordx2 v84, v[10:11], s[58:59] offset:64
	v_pk_mul_f32 v[14:15], v[14:15], v[108:109] op_sel_hi:[1,0]
	v_pk_mul_f32 v[16:17], v[16:17], v[108:109] op_sel_hi:[1,0]
	v_pk_fma_f32 v[14:15], v[14:15], v[160:161], v[176:177]
	v_pk_fma_f32 v[16:17], v[16:17], v[162:163], v[178:179]
	v_cvt_pk_bf16_f32 v14, v14, v15
	v_cvt_pk_bf16_f32 v15, v16, v17
	global_store_dwordx2 v84, v[14:15], s[58:59] offset:96
	v_add_u32_e32 v84, 0x8000, v84
	v_pk_mul_f32 v[18:19], v[18:19], v[110:111] op_sel_hi:[1,0]
	v_pk_mul_f32 v[20:21], v[20:21], v[110:111] op_sel_hi:[1,0]
	v_pk_fma_f32 v[18:19], v[18:19], v[148:149], v[164:165]
	v_pk_fma_f32 v[20:21], v[20:21], v[150:151], v[166:167]
	v_cvt_pk_bf16_f32 v18, v18, v19
	v_cvt_pk_bf16_f32 v19, v20, v21
	global_store_dwordx2 v84, v[18:19], s[58:59] offset:0
	v_pk_mul_f32 v[22:23], v[22:23], v[110:111] op_sel_hi:[1,0]
	v_pk_mul_f32 v[24:25], v[24:25], v[110:111] op_sel_hi:[1,0]
	v_pk_fma_f32 v[22:23], v[22:23], v[152:153], v[168:169]
	v_pk_fma_f32 v[24:25], v[24:25], v[154:155], v[170:171]
	v_cvt_pk_bf16_f32 v22, v22, v23
	v_cvt_pk_bf16_f32 v23, v24, v25
	global_store_dwordx2 v84, v[22:23], s[58:59] offset:32
	v_pk_mul_f32 v[26:27], v[26:27], v[110:111] op_sel_hi:[1,0]
	v_pk_mul_f32 v[28:29], v[28:29], v[110:111] op_sel_hi:[1,0]
	v_pk_fma_f32 v[26:27], v[26:27], v[156:157], v[172:173]
	v_pk_fma_f32 v[28:29], v[28:29], v[158:159], v[174:175]
	v_cvt_pk_bf16_f32 v26, v26, v27
	v_cvt_pk_bf16_f32 v27, v28, v29
	global_store_dwordx2 v84, v[26:27], s[58:59] offset:64
	v_pk_mul_f32 v[30:31], v[30:31], v[110:111] op_sel_hi:[1,0]
	v_pk_mul_f32 v[32:33], v[32:33], v[110:111] op_sel_hi:[1,0]
	v_pk_fma_f32 v[30:31], v[30:31], v[160:161], v[176:177]
	v_pk_fma_f32 v[32:33], v[32:33], v[162:163], v[178:179]
	v_cvt_pk_bf16_f32 v30, v30, v31
	v_cvt_pk_bf16_f32 v31, v32, v33
	global_store_dwordx2 v84, v[30:31], s[58:59] offset:96
	v_add_u32_e32 v84, 0x8000, v84
	v_pk_mul_f32 v[34:35], v[34:35], v[112:113] op_sel_hi:[1,0]
	v_pk_mul_f32 v[36:37], v[36:37], v[112:113] op_sel_hi:[1,0]
	v_pk_fma_f32 v[34:35], v[34:35], v[148:149], v[164:165]
	v_pk_fma_f32 v[36:37], v[36:37], v[150:151], v[166:167]
	v_cvt_pk_bf16_f32 v34, v34, v35
	v_cvt_pk_bf16_f32 v35, v36, v37
	global_store_dwordx2 v84, v[34:35], s[58:59] offset:0
	v_pk_mul_f32 v[38:39], v[38:39], v[112:113] op_sel_hi:[1,0]
	v_pk_mul_f32 v[40:41], v[40:41], v[112:113] op_sel_hi:[1,0]
	v_pk_fma_f32 v[38:39], v[38:39], v[152:153], v[168:169]
	v_pk_fma_f32 v[40:41], v[40:41], v[154:155], v[170:171]
	v_cvt_pk_bf16_f32 v38, v38, v39
	v_cvt_pk_bf16_f32 v39, v40, v41
	global_store_dwordx2 v84, v[38:39], s[58:59] offset:32
	v_pk_mul_f32 v[42:43], v[42:43], v[112:113] op_sel_hi:[1,0]
	v_pk_mul_f32 v[44:45], v[44:45], v[112:113] op_sel_hi:[1,0]
	v_pk_fma_f32 v[42:43], v[42:43], v[156:157], v[172:173]
	v_pk_fma_f32 v[44:45], v[44:45], v[158:159], v[174:175]
	v_cvt_pk_bf16_f32 v42, v42, v43
	v_cvt_pk_bf16_f32 v43, v44, v45
	global_store_dwordx2 v84, v[42:43], s[58:59] offset:64
	v_pk_mul_f32 v[46:47], v[46:47], v[112:113] op_sel_hi:[1,0]
	v_pk_mul_f32 v[48:49], v[48:49], v[112:113] op_sel_hi:[1,0]
	v_pk_fma_f32 v[46:47], v[46:47], v[160:161], v[176:177]
	v_pk_fma_f32 v[48:49], v[48:49], v[162:163], v[178:179]
	v_cvt_pk_bf16_f32 v46, v46, v47
	v_cvt_pk_bf16_f32 v47, v48, v49
	global_store_dwordx2 v84, v[46:47], s[58:59] offset:96
	v_add_u32_e32 v84, 0x8000, v84
	v_pk_mul_f32 v[50:51], v[50:51], v[114:115] op_sel_hi:[1,0]
	v_pk_mul_f32 v[52:53], v[52:53], v[114:115] op_sel_hi:[1,0]
	v_pk_fma_f32 v[50:51], v[50:51], v[148:149], v[164:165]
	v_pk_fma_f32 v[52:53], v[52:53], v[150:151], v[166:167]
	v_cvt_pk_bf16_f32 v50, v50, v51
	v_cvt_pk_bf16_f32 v51, v52, v53
	global_store_dwordx2 v84, v[50:51], s[58:59] offset:0
	v_pk_mul_f32 v[54:55], v[54:55], v[114:115] op_sel_hi:[1,0]
	v_pk_mul_f32 v[56:57], v[56:57], v[114:115] op_sel_hi:[1,0]
	v_pk_fma_f32 v[54:55], v[54:55], v[152:153], v[168:169]
	v_pk_fma_f32 v[56:57], v[56:57], v[154:155], v[170:171]
	v_cvt_pk_bf16_f32 v54, v54, v55
	v_cvt_pk_bf16_f32 v55, v56, v57
	global_store_dwordx2 v84, v[54:55], s[58:59] offset:32
	v_pk_mul_f32 v[58:59], v[58:59], v[114:115] op_sel_hi:[1,0]
	v_pk_mul_f32 v[60:61], v[60:61], v[114:115] op_sel_hi:[1,0]
	v_pk_fma_f32 v[58:59], v[58:59], v[156:157], v[172:173]
	v_pk_fma_f32 v[60:61], v[60:61], v[158:159], v[174:175]
	v_cvt_pk_bf16_f32 v58, v58, v59
	v_cvt_pk_bf16_f32 v59, v60, v61
	global_store_dwordx2 v84, v[58:59], s[58:59] offset:64
	v_pk_mul_f32 v[62:63], v[62:63], v[114:115] op_sel_hi:[1,0]
	v_pk_mul_f32 v[64:65], v[64:65], v[114:115] op_sel_hi:[1,0]
	v_pk_fma_f32 v[62:63], v[62:63], v[160:161], v[176:177]
	v_pk_fma_f32 v[64:65], v[64:65], v[162:163], v[178:179]
	v_cvt_pk_bf16_f32 v62, v62, v63
	v_cvt_pk_bf16_f32 v63, v64, v65
	global_store_dwordx2 v84, v[62:63], s[58:59] offset:96
	s_branch .LBB0_893
.Ld_epi_last:
	s_waitcnt vmcnt(0)
	v_pk_mul_f32 v[2:3], v[2:3], v[108:109] op_sel_hi:[1,0]
	v_pk_mul_f32 v[4:5], v[4:5], v[108:109] op_sel_hi:[1,0]
	v_pk_mul_f32 v[2:3], v[2:3], v[148:149]
	v_pk_mul_f32 v[4:5], v[4:5], v[150:151]
	global_store_dwordx4 v80, v[2:5], s[54:55] offset:0
	v_pk_mul_f32 v[6:7], v[6:7], v[108:109] op_sel_hi:[1,0]
	v_pk_mul_f32 v[8:9], v[8:9], v[108:109] op_sel_hi:[1,0]
	v_pk_mul_f32 v[6:7], v[6:7], v[152:153]
	v_pk_mul_f32 v[8:9], v[8:9], v[154:155]
	global_store_dwordx4 v80, v[6:9], s[54:55] offset:64
	v_pk_mul_f32 v[10:11], v[10:11], v[108:109] op_sel_hi:[1,0]
	v_pk_mul_f32 v[12:13], v[12:13], v[108:109] op_sel_hi:[1,0]
	v_pk_mul_f32 v[10:11], v[10:11], v[156:157]
	v_pk_mul_f32 v[12:13], v[12:13], v[158:159]
	global_store_dwordx4 v80, v[10:13], s[54:55] offset:128
	v_pk_mul_f32 v[14:15], v[14:15], v[108:109] op_sel_hi:[1,0]
	v_pk_mul_f32 v[16:17], v[16:17], v[108:109] op_sel_hi:[1,0]
	v_pk_mul_f32 v[14:15], v[14:15], v[160:161]
	v_pk_mul_f32 v[16:17], v[16:17], v[162:163]
	global_store_dwordx4 v80, v[14:17], s[54:55] offset:192
	v_pk_mul_f32 v[18:19], v[18:19], v[110:111] op_sel_hi:[1,0]
	v_pk_mul_f32 v[20:21], v[20:21], v[110:111] op_sel_hi:[1,0]
	v_pk_mul_f32 v[18:19], v[18:19], v[148:149]
	v_pk_mul_f32 v[20:21], v[20:21], v[150:151]
	global_store_dwordx4 v81, v[18:21], s[54:55] offset:0
	v_pk_mul_f32 v[22:23], v[22:23], v[110:111] op_sel_hi:[1,0]
	v_pk_mul_f32 v[24:25], v[24:25], v[110:111] op_sel_hi:[1,0]
	v_pk_mul_f32 v[22:23], v[22:23], v[152:153]
	v_pk_mul_f32 v[24:25], v[24:25], v[154:155]
	global_store_dwordx4 v81, v[22:25], s[54:55] offset:64
	v_pk_mul_f32 v[26:27], v[26:27], v[110:111] op_sel_hi:[1,0]
	v_pk_mul_f32 v[28:29], v[28:29], v[110:111] op_sel_hi:[1,0]
	v_pk_mul_f32 v[26:27], v[26:27], v[156:157]
	v_pk_mul_f32 v[28:29], v[28:29], v[158:159]
	global_store_dwordx4 v81, v[26:29], s[54:55] offset:128
	v_pk_mul_f32 v[30:31], v[30:31], v[110:111] op_sel_hi:[1,0]
	v_pk_mul_f32 v[32:33], v[32:33], v[110:111] op_sel_hi:[1,0]
	v_pk_mul_f32 v[30:31], v[30:31], v[160:161]
	v_pk_mul_f32 v[32:33], v[32:33], v[162:163]
	global_store_dwordx4 v81, v[30:33], s[54:55] offset:192
	v_pk_mul_f32 v[34:35], v[34:35], v[112:113] op_sel_hi:[1,0]
	v_pk_mul_f32 v[36:37], v[36:37], v[112:113] op_sel_hi:[1,0]
	v_pk_mul_f32 v[34:35], v[34:35], v[148:149]
	v_pk_mul_f32 v[36:37], v[36:37], v[150:151]
	global_store_dwordx4 v82, v[34:37], s[54:55] offset:0
	v_pk_mul_f32 v[38:39], v[38:39], v[112:113] op_sel_hi:[1,0]
	v_pk_mul_f32 v[40:41], v[40:41], v[112:113] op_sel_hi:[1,0]
	v_pk_mul_f32 v[38:39], v[38:39], v[152:153]
	v_pk_mul_f32 v[40:41], v[40:41], v[154:155]
	global_store_dwordx4 v82, v[38:41], s[54:55] offset:64
	v_pk_mul_f32 v[42:43], v[42:43], v[112:113] op_sel_hi:[1,0]
	v_pk_mul_f32 v[44:45], v[44:45], v[112:113] op_sel_hi:[1,0]
	v_pk_mul_f32 v[42:43], v[42:43], v[156:157]
	v_pk_mul_f32 v[44:45], v[44:45], v[158:159]
	global_store_dwordx4 v82, v[42:45], s[54:55] offset:128
	v_pk_mul_f32 v[46:47], v[46:47], v[112:113] op_sel_hi:[1,0]
	v_pk_mul_f32 v[48:49], v[48:49], v[112:113] op_sel_hi:[1,0]
	v_pk_mul_f32 v[46:47], v[46:47], v[160:161]
	v_pk_mul_f32 v[48:49], v[48:49], v[162:163]
	global_store_dwordx4 v82, v[46:49], s[54:55] offset:192
	v_pk_mul_f32 v[50:51], v[50:51], v[114:115] op_sel_hi:[1,0]
	v_pk_mul_f32 v[52:53], v[52:53], v[114:115] op_sel_hi:[1,0]
	v_pk_mul_f32 v[50:51], v[50:51], v[148:149]
	v_pk_mul_f32 v[52:53], v[52:53], v[150:151]
	global_store_dwordx4 v83, v[50:53], s[54:55] offset:0
	v_pk_mul_f32 v[54:55], v[54:55], v[114:115] op_sel_hi:[1,0]
	v_pk_mul_f32 v[56:57], v[56:57], v[114:115] op_sel_hi:[1,0]
	v_pk_mul_f32 v[54:55], v[54:55], v[152:153]
	v_pk_mul_f32 v[56:57], v[56:57], v[154:155]
	global_store_dwordx4 v83, v[54:57], s[54:55] offset:64
	v_pk_mul_f32 v[58:59], v[58:59], v[114:115] op_sel_hi:[1,0]
	v_pk_mul_f32 v[60:61], v[60:61], v[114:115] op_sel_hi:[1,0]
	v_pk_mul_f32 v[58:59], v[58:59], v[156:157]
	v_pk_mul_f32 v[60:61], v[60:61], v[158:159]
	global_store_dwordx4 v83, v[58:61], s[54:55] offset:128
	v_pk_mul_f32 v[62:63], v[62:63], v[114:115] op_sel_hi:[1,0]
	v_pk_mul_f32 v[64:65], v[64:65], v[114:115] op_sel_hi:[1,0]
	v_pk_mul_f32 v[62:63], v[62:63], v[160:161]
	v_pk_mul_f32 v[64:65], v[64:65], v[162:163]
	global_store_dwordx4 v83, v[62:65], s[54:55] offset:192
	s_branch .LBB0_893

	.amdhsa_kernel _Z14fwd_megakernel6Params
		.amdhsa_group_segment_fixed_size 16640
		.amdhsa_private_segment_fixed_size 0
		.amdhsa_kernarg_size 496
		.amdhsa_user_sgpr_count 2
		.amdhsa_user_sgpr_dispatch_ptr 0
		.amdhsa_user_sgpr_queue_ptr 0
		.amdhsa_user_sgpr_kernarg_segment_ptr 1
		.amdhsa_user_sgpr_dispatch_id 0
		.amdhsa_user_sgpr_kernarg_preload_length 0
		.amdhsa_user_sgpr_kernarg_preload_offset 0
		.amdhsa_user_sgpr_private_segment_size 0
		.amdhsa_uses_dynamic_stack 0
		.amdhsa_enable_private_segment 0
		.amdhsa_system_sgpr_workgroup_id_x 1
		.amdhsa_system_sgpr_workgroup_id_y 0
		.amdhsa_system_sgpr_workgroup_id_z 0
		.amdhsa_system_sgpr_workgroup_info 0
		.amdhsa_system_vgpr_workitem_id 0
		.amdhsa_next_free_vgpr 256
		.amdhsa_next_free_sgpr 98
		.amdhsa_accum_offset 256
		.amdhsa_reserve_vcc 1
		.amdhsa_float_round_mode_32 0
		.amdhsa_float_round_mode_16_64 0
		.amdhsa_float_denorm_mode_32 3
		.amdhsa_float_denorm_mode_16_64 3
		.amdhsa_dx10_clamp 1
		.amdhsa_ieee_mode 1
		.amdhsa_fp16_overflow 0
		.amdhsa_tg_split 0
		.amdhsa_exception_fp_ieee_invalid_op 0
		.amdhsa_exception_fp_denorm_src 0
		.amdhsa_exception_fp_ieee_div_zero 0
		.amdhsa_exception_fp_ieee_overflow 0
		.amdhsa_exception_fp_ieee_underflow 0
		.amdhsa_exception_fp_ieee_inexact 0
		.amdhsa_exception_int_div_zero 0
	.end_amdhsa_kernel

amdhsa.kernels:
  - .agpr_count:     0
    .args:
      - .offset:         0
        .size:           240
        .value_kind:     by_value
      - .offset:         240
        .size:           4
        .value_kind:     hidden_block_count_x
      - .offset:         244
        .size:           4
        .value_kind:     hidden_block_count_y
      - .offset:         248
        .size:           4
        .value_kind:     hidden_block_count_z
      - .offset:         252
        .size:           2
        .value_kind:     hidden_group_size_x
      - .offset:         254
        .size:           2
        .value_kind:     hidden_group_size_y
      - .offset:         256
        .size:           2
        .value_kind:     hidden_group_size_z
      - .offset:         258
        .size:           2
        .value_kind:     hidden_remainder_x
      - .offset:         260
        .size:           2
        .value_kind:     hidden_remainder_y
      - .offset:         262
        .size:           2
        .value_kind:     hidden_remainder_z
      - .offset:         280
        .size:           8
        .value_kind:     hidden_global_offset_x
      - .offset:         288
        .size:           8
        .value_kind:     hidden_global_offset_y
      - .offset:         296
        .size:           8
        .value_kind:     hidden_global_offset_z
      - .offset:         304
        .size:           2
        .value_kind:     hidden_grid_dims
      - .offset:         360
        .size:           4
        .value_kind:     hidden_dynamic_lds_size
    .group_segment_fixed_size: 16640
    .kernarg_segment_align: 8
    .kernarg_segment_size: 496
    .language:       OpenCL C
    .language_version:
      - 2
      - 0
    .max_flat_workgroup_size: 512
    .name:           _Z14fwd_megakernel6Params
    .private_segment_fixed_size: 0
    .sgpr_count:     104
    .sgpr_spill_count: 130
    .symbol:         _Z14fwd_megakernel6Params.kd
    .uniform_work_group_size: 1
    .uses_dynamic_stack: false
    .vgpr_count:     256
    .vgpr_spill_count: 0
    .wavefront_size: 64
